# v1 + all 9 GEMM K-loops: first K-tile peeled with srcC=0 MFMAs, 128 accumulator-zeroing v_mov per tile removed, loop entered at midpoint
# speedup vs baseline: 1.0129x; 1.0129x over previous
; #define PG8_STAGE(bufoff, gbase, voff) do { _Pragma("unroll") for (int _i = 0; _i < 2; ++_i) \
;         __builtin_amdgcn_global_load_lds((const unsigned*)((const char*)(gbase) + (voff)[_i]), (PG8_LAS unsigned*)(lds + (bufoff) + ldsw + _i * 8192), 16, 0, PG8_LOAD_AUX); } while (0)
; #define PG8_LDA(dst, b, h) do { _Pragma("unroll") for (int m = 0; m < 4; ++m) _Pragma("unroll") for (int k = 0; k < 2; ++k) dst[m][k] = *(const PG8_LAS bf16x8*)(lds + PG8_SA(b, h) + aoff + m * 2048 + k * 1024); } while (0)
; #define PG8_LDB(dst, b, h) do { _Pragma("unroll") for (int n = 0; n < 2; ++n) _Pragma("unroll") for (int k = 0; k < 2; ++k) dst[n][k] = *(const PG8_LAS bf16x8*)(lds + PG8_SB(b, h) + boff + n * 2048 + k * 1024); } while (0)
; #define PG8_MMA(ai, bj, At, Bt) do { __builtin_amdgcn_s_setprio(1); _Pragma("unroll") for (int m = 0; m < 4; ++m) _Pragma("unroll") for (int n = 0; n < 2; ++n) _Pragma("unroll") for (int k = 0; k < 2; ++k) \
;         acc[ai][bj][m][n] = __builtin_amdgcn_mfma_f32_16x16x32_bf16(Bt[n][k], At[m][k], acc[ai][bj][m][n], 0, 0, 0); __builtin_amdgcn_s_setprio(0); } while (0)
; #define PG8_WAIT_V(n) asm volatile("s_waitcnt vmcnt(" #n ")" ::: "memory")
; #define PG8_WAIT_L(n) asm volatile("s_waitcnt lgkmcnt(" #n ")" ::: "memory")
; #define PG8_BAR __builtin_amdgcn_s_barrier()
; #define PG8_SCHED __builtin_amdgcn_sched_barrier(0)
; template <class Epi, class Sched, bool ALIGN_EPI = false, bool SP2 = false>
; __device__ __forceinline__ void gemm_phase(PG8_LAS unsigned char* lds, const Gemm g, const Sched& S, const Epi& E) {
;     ...
;             const bool last = (t == nt - 2);
;             const char* a1 = cA + (size_t)(t + 1) * kstep;
;             const char* a2 = last ? nA : cA + (size_t)(t + 2) * kstep; const char* b2 = last ? nB : cB + (size_t)(t + 2) * kstep;
;             const char* a3 = a2 + kstep; const char* b3 = b2 + kstep;
;             if (last && has_next) S.a_ready(nxt);
;             if constexpr (SP2) {
;             PG8_LDB(B0, 0, 0); PG8_LDB(B1, 0, 1); PG8_SCHED; PG8_LDA(At, 0, 0); PG8_STAGE(PG8_SA(1, 1), a1 + hstepA, voffA);
;             PG8_WAIT_V(8); PG8_WAIT_L(0); PG8_BAR; PG8_MMA(0, 0, At, B0); PG8_MMA(0, 1, At, B1); PG8_BAR; PG8_SCHED;
.LBB0_214:
	s_ashr_i32 s17, s16, 31
	s_lshl_b64 s[18:19], s[16:17], 19
	v_readlane_b32 s24, v239, 47
	v_readlane_b32 s25, v239, 48
	s_add_u32 s18, s24, s18
	s_addc_u32 s19, s25, s19
	s_and_b64 s[24:25], s[4:5], exec
	s_cselect_b32 s17, s19, s21
	s_cselect_b32 s24, s18, s20
	s_ashr_i32 s15, s14, 31
	s_lshl_b64 s[26:27], s[14:15], 19
	s_add_u32 s40, s64, s26
	s_addc_u32 s41, s65, s27
	s_and_b64 s[26:27], s[4:5], exec
	s_cselect_b32 s15, s41, s23
	s_cselect_b32 s25, s40, s22
	s_add_u32 s20, s20, 0x40080
	s_addc_u32 s21, s21, 0
	s_add_u32 s26, s22, 0x100
	s_addc_u32 s27, s23, 0
	s_mov_b32 s28, -2
	ds_read_b128 v[162:165], v158
	ds_read_b128 v[166:169], v158 offset:1024
	ds_read_b128 v[170:173], v158 offset:2048
	ds_read_b128 v[174:177], v158 offset:3072
	ds_read_b128 v[178:181], v159
	ds_read_b128 v[182:185], v159 offset:1024
	ds_read_b128 v[186:189], v159 offset:2048
	ds_read_b128 v[190:193], v159 offset:3072
	s_add_u32 s22, s20, 0xfffc0080
	s_addc_u32 s23, s21, -1
	s_cmp_eq_u32 s28, 12
	s_cselect_b32 s35, s17, s23
	s_cselect_b32 s34, s24, s22
	s_cselect_b32 s23, s15, s27
	s_cselect_b32 s22, s25, s26
	v_lshl_add_u64 v[226:227], s[20:21], 0, v[138:139]
	s_add_i32 m0, s42, 0xc000
	ds_read_b128 v[194:197], v160
	ds_read_b128 v[198:201], v160 offset:1024
	ds_read_b128 v[202:205], v160 offset:2048
	ds_read_b128 v[206:209], v160 offset:3072
	ds_read_b128 v[210:213], v160 offset:4096
	ds_read_b128 v[214:217], v160 offset:5120
	ds_read_b128 v[218:221], v160 offset:6144
	ds_read_b128 v[222:225], v160 offset:7168
	global_load_lds_dwordx4 v[226:227], off
	v_lshl_add_u64 v[226:227], s[20:21], 0, v[140:141]
	s_add_i32 m0, s42, 0xe000
	s_nop 0
	global_load_lds_dwordx4 v[226:227], off
	s_waitcnt vmcnt(8)
	s_waitcnt lgkmcnt(0)
	s_barrier
	s_setprio 1
	s_waitcnt lgkmcnt(0)
	v_mfma_f32_16x16x32_bf16 v[124:127], v[162:165], v[194:197], 0
	v_mfma_f32_16x16x32_bf16 v[120:123], v[170:173], v[194:197], 0
	v_mfma_f32_16x16x32_bf16 v[108:111], v[162:165], v[202:205], 0
	v_mfma_f32_16x16x32_bf16 v[104:107], v[170:173], v[202:205], 0
	v_mfma_f32_16x16x32_bf16 v[92:95], v[162:165], v[210:213], 0
	v_mfma_f32_16x16x32_bf16 v[88:91], v[170:173], v[210:213], 0
	v_mfma_f32_16x16x32_bf16 v[76:79], v[162:165], v[218:221], 0
	v_mfma_f32_16x16x32_bf16 v[72:75], v[170:173], v[218:221], 0
	v_mfma_f32_16x16x32_bf16 v[124:127], v[166:169], v[198:201], v[124:127]
	v_mfma_f32_16x16x32_bf16 v[120:123], v[174:177], v[198:201], v[120:123]
	v_mfma_f32_16x16x32_bf16 v[108:111], v[166:169], v[206:209], v[108:111]
	v_mfma_f32_16x16x32_bf16 v[104:107], v[174:177], v[206:209], v[104:107]
	v_mfma_f32_16x16x32_bf16 v[92:95], v[166:169], v[214:217], v[92:95]
	v_mfma_f32_16x16x32_bf16 v[88:91], v[174:177], v[214:217], v[88:91]
	v_mfma_f32_16x16x32_bf16 v[76:79], v[166:169], v[222:225], v[76:79]
	v_mfma_f32_16x16x32_bf16 v[72:75], v[174:177], v[222:225], v[72:75]
	s_setprio 0
	s_setprio 1
	v_mfma_f32_16x16x32_bf16 v[116:119], v[178:181], v[194:197], 0
	v_mfma_f32_16x16x32_bf16 v[112:115], v[186:189], v[194:197], 0
	v_mfma_f32_16x16x32_bf16 v[100:103], v[178:181], v[202:205], 0
	v_mfma_f32_16x16x32_bf16 v[96:99], v[186:189], v[202:205], 0
	v_mfma_f32_16x16x32_bf16 v[84:87], v[178:181], v[210:213], 0
	v_mfma_f32_16x16x32_bf16 v[80:83], v[186:189], v[210:213], 0
	v_mfma_f32_16x16x32_bf16 v[68:71], v[178:181], v[218:221], 0
	v_mfma_f32_16x16x32_bf16 v[64:67], v[186:189], v[218:221], 0
	v_mfma_f32_16x16x32_bf16 v[116:119], v[182:185], v[198:201], v[116:119]
	v_mfma_f32_16x16x32_bf16 v[112:115], v[190:193], v[198:201], v[112:115]
	v_mfma_f32_16x16x32_bf16 v[100:103], v[182:185], v[206:209], v[100:103]
	v_mfma_f32_16x16x32_bf16 v[96:99], v[190:193], v[206:209], v[96:99]
	v_mfma_f32_16x16x32_bf16 v[84:87], v[182:185], v[214:217], v[84:87]
	v_mfma_f32_16x16x32_bf16 v[80:83], v[190:193], v[214:217], v[80:83]
	v_mfma_f32_16x16x32_bf16 v[68:71], v[182:185], v[222:225], v[68:71]
	v_mfma_f32_16x16x32_bf16 v[64:67], v[190:193], v[222:225], v[64:67]
	s_setprio 0
	s_barrier
; #define PG8_STAGE(bufoff, gbase, voff) do { _Pragma("unroll") for (int _i = 0; _i < 2; ++_i) \
;         __builtin_amdgcn_global_load_lds((const unsigned*)((const char*)(gbase) + (voff)[_i]), (PG8_LAS unsigned*)(lds + (bufoff) + ldsw + _i * 8192), 16, 0, PG8_LOAD_AUX); } while (0)
; #define PG8_LDA(dst, b, h) do { _Pragma("unroll") for (int m = 0; m < 4; ++m) _Pragma("unroll") for (int k = 0; k < 2; ++k) dst[m][k] = *(const PG8_LAS bf16x8*)(lds + PG8_SA(b, h) + aoff + m * 2048 + k * 1024); } while (0)
; #define PG8_MMA(ai, bj, At, Bt) do { __builtin_amdgcn_s_setprio(1); _Pragma("unroll") for (int m = 0; m < 4; ++m) _Pragma("unroll") for (int n = 0; n < 2; ++n) _Pragma("unroll") for (int k = 0; k < 2; ++k) \
;         acc[ai][bj][m][n] = __builtin_amdgcn_mfma_f32_16x16x32_bf16(Bt[n][k], At[m][k], acc[ai][bj][m][n], 0, 0, 0); __builtin_amdgcn_s_setprio(0); } while (0)
; #define PG8_WAIT_V(n) asm volatile("s_waitcnt vmcnt(" #n ")" ::: "memory")
; #define PG8_WAIT_L(n) asm volatile("s_waitcnt lgkmcnt(" #n ")" ::: "memory")
; #define PG8_BAR __builtin_amdgcn_s_barrier()
; #define PG8_SCHED __builtin_amdgcn_sched_barrier(0)
; template <class Epi, class Sched, bool ALIGN_EPI = false, bool SP2 = false>
; __device__ __forceinline__ void gemm_phase(PG8_LAS unsigned char* lds, const Gemm g, const Sched& S, const Epi& E) {
;     ...
;             PG8_LDA(At, 0, 1); PG8_STAGE(PG8_SB(0, 0), b2, voffB); PG8_STAGE(PG8_SB(0, 1), b2 + hstepB, voffB); PG8_STAGE(PG8_SA(0, 0), a2, voffA);
;             PG8_WAIT_V(8); PG8_WAIT_L(0); PG8_BAR; PG8_MMA(1, 0, At, B0); PG8_MMA(1, 1, At, B1); PG8_BAR; PG8_SCHED;
	s_add_i32 s29, s51, s33
	v_lshl_add_u64 v[226:227], s[22:23], 0, v[130:131]
	s_mov_b32 m0, s29
	ds_read_b128 v[194:197], v160 offset:16384
	ds_read_b128 v[198:201], v160 offset:17408
	ds_read_b128 v[202:205], v160 offset:18432
	ds_read_b128 v[206:209], v160 offset:19456
	ds_read_b128 v[210:213], v160 offset:20480
	ds_read_b128 v[214:217], v160 offset:21504
	ds_read_b128 v[218:221], v160 offset:22528
	ds_read_b128 v[222:225], v160 offset:23552
	global_load_lds_dwordx4 v[226:227], off
	s_add_i32 m0, s29, 0x2000
	s_add_u32 s30, s22, 0x10000
	v_lshl_add_u64 v[228:229], s[22:23], 0, v[134:135]
	s_addc_u32 s31, s23, 0
	s_add_i32 s29, s52, s33
	global_load_lds_dwordx4 v[228:229], off
	v_lshl_add_u64 v[230:231], s[30:31], 0, v[130:131]
	s_mov_b32 m0, s29
	v_lshl_add_u64 v[232:233], s[34:35], 0, v[132:133]
	global_load_lds_dwordx4 v[230:231], off
	v_lshl_add_u64 v[230:231], s[30:31], 0, v[134:135]
	s_add_i32 m0, s29, 0x2000
	s_nop 0
	global_load_lds_dwordx4 v[230:231], off
	v_lshl_add_u64 v[230:231], s[34:35], 0, v[128:129]
	s_mov_b32 m0, s42
	s_nop 0
	global_load_lds_dwordx4 v[230:231], off
	s_mov_b32 m0, s43
	s_nop 0
	global_load_lds_dwordx4 v[232:233], off
	s_waitcnt vmcnt(8)
	s_waitcnt lgkmcnt(0)
	s_barrier
	s_setprio 1
	s_waitcnt lgkmcnt(0)
	v_mfma_f32_16x16x32_bf16 v[60:63], v[162:165], v[194:197], 0
	v_mfma_f32_16x16x32_bf16 v[56:59], v[170:173], v[194:197], 0
	v_mfma_f32_16x16x32_bf16 v[44:47], v[162:165], v[202:205], 0
	v_mfma_f32_16x16x32_bf16 v[40:43], v[170:173], v[202:205], 0
	v_mfma_f32_16x16x32_bf16 v[28:31], v[162:165], v[210:213], 0
	v_mfma_f32_16x16x32_bf16 v[24:27], v[170:173], v[210:213], 0
	v_mfma_f32_16x16x32_bf16 v[12:15], v[162:165], v[218:221], 0
	v_mfma_f32_16x16x32_bf16 v[8:11], v[170:173], v[218:221], 0
	v_mfma_f32_16x16x32_bf16 v[60:63], v[166:169], v[198:201], v[60:63]
	v_mfma_f32_16x16x32_bf16 v[56:59], v[174:177], v[198:201], v[56:59]
	v_mfma_f32_16x16x32_bf16 v[44:47], v[166:169], v[206:209], v[44:47]
	v_mfma_f32_16x16x32_bf16 v[40:43], v[174:177], v[206:209], v[40:43]
	v_mfma_f32_16x16x32_bf16 v[28:31], v[166:169], v[214:217], v[28:31]
	v_mfma_f32_16x16x32_bf16 v[24:27], v[174:177], v[214:217], v[24:27]
	v_mfma_f32_16x16x32_bf16 v[12:15], v[166:169], v[222:225], v[12:15]
	v_mfma_f32_16x16x32_bf16 v[8:11], v[174:177], v[222:225], v[8:11]
	s_setprio 0
	s_setprio 1
	v_mfma_f32_16x16x32_bf16 v[52:55], v[178:181], v[194:197], 0
	v_mfma_f32_16x16x32_bf16 v[48:51], v[186:189], v[194:197], 0
	v_mfma_f32_16x16x32_bf16 v[36:39], v[178:181], v[202:205], 0
	v_mfma_f32_16x16x32_bf16 v[32:35], v[186:189], v[202:205], 0
	v_mfma_f32_16x16x32_bf16 v[20:23], v[178:181], v[210:213], 0
	v_mfma_f32_16x16x32_bf16 v[16:19], v[186:189], v[210:213], 0
	v_mfma_f32_16x16x32_bf16 v[4:7], v[178:181], v[218:221], 0
	v_mfma_f32_16x16x32_bf16 v[0:3], v[186:189], v[218:221], 0
	v_mfma_f32_16x16x32_bf16 v[52:55], v[182:185], v[198:201], v[52:55]
	v_mfma_f32_16x16x32_bf16 v[48:51], v[190:193], v[198:201], v[48:51]
	v_mfma_f32_16x16x32_bf16 v[36:39], v[182:185], v[206:209], v[36:39]
	v_mfma_f32_16x16x32_bf16 v[32:35], v[190:193], v[206:209], v[32:35]
	v_mfma_f32_16x16x32_bf16 v[20:23], v[182:185], v[214:217], v[20:23]
	v_mfma_f32_16x16x32_bf16 v[16:19], v[190:193], v[214:217], v[16:19]
	v_mfma_f32_16x16x32_bf16 v[4:7], v[182:185], v[222:225], v[4:7]
	v_mfma_f32_16x16x32_bf16 v[0:3], v[190:193], v[222:225], v[0:3]
	s_setprio 0
	s_barrier
	s_branch .Lkmid_P1

; #define PG8_STAGE(bufoff, gbase, voff) do { _Pragma("unroll") for (int _i = 0; _i < 2; ++_i) \
;         __builtin_amdgcn_global_load_lds((const unsigned*)((const char*)(gbase) + (voff)[_i]), (PG8_LAS unsigned*)(lds + (bufoff) + ldsw + _i * 8192), 16, 0, PG8_LOAD_AUX); } while (0)
; #define PG8_LDA(dst, b, h) do { _Pragma("unroll") for (int m = 0; m < 4; ++m) _Pragma("unroll") for (int k = 0; k < 2; ++k) dst[m][k] = *(const PG8_LAS bf16x8*)(lds + PG8_SA(b, h) + aoff + m * 2048 + k * 1024); } while (0)
; #define PG8_LDB(dst, b, h) do { _Pragma("unroll") for (int n = 0; n < 2; ++n) _Pragma("unroll") for (int k = 0; k < 2; ++k) dst[n][k] = *(const PG8_LAS bf16x8*)(lds + PG8_SB(b, h) + boff + n * 2048 + k * 1024); } while (0)
; #define PG8_MMA(ai, bj, At, Bt) do { __builtin_amdgcn_s_setprio(1); _Pragma("unroll") for (int m = 0; m < 4; ++m) _Pragma("unroll") for (int n = 0; n < 2; ++n) _Pragma("unroll") for (int k = 0; k < 2; ++k) \
;         acc[ai][bj][m][n] = __builtin_amdgcn_mfma_f32_16x16x32_bf16(Bt[n][k], At[m][k], acc[ai][bj][m][n], 0, 0, 0); __builtin_amdgcn_s_setprio(0); } while (0)
; #define PG8_WAIT_V(n) asm volatile("s_waitcnt vmcnt(" #n ")" ::: "memory")
; #define PG8_WAIT_L(n) asm volatile("s_waitcnt lgkmcnt(" #n ")" ::: "memory")
; #define PG8_BAR __builtin_amdgcn_s_barrier()
; #define PG8_SCHED __builtin_amdgcn_sched_barrier(0)
; template <class Epi, class Sched, bool ALIGN_EPI = false, bool SP2 = false>
; __device__ __forceinline__ void gemm_phase(PG8_LAS unsigned char* lds, const Gemm g, const Sched& S, const Epi& E) {
;     ...
;             PG8_LDB(B0, 1, 0); PG8_LDB(B1, 1, 1); PG8_SCHED; PG8_LDA(At, 1, 0); PG8_STAGE(PG8_SA(0, 1), a2 + hstepA, voffA);
;             PG8_WAIT_V(8); PG8_WAIT_L(0); PG8_BAR; PG8_MMA(0, 0, At, B0); PG8_MMA(0, 1, At, B1); PG8_BAR; PG8_SCHED;
.Lkmid_P1:
	s_add_i32 s29, 0, 0x18000
	v_add_u32_e32 v161, s29, v146
	s_add_i32 s38, 0, 0x1c000
	ds_read_b128 v[162:165], v161
	ds_read_b128 v[166:169], v161 offset:1024
	ds_read_b128 v[170:173], v161 offset:2048
	ds_read_b128 v[174:177], v161 offset:3072
	v_add_u32_e32 v161, s38, v146
	ds_read_b128 v[178:181], v161
	ds_read_b128 v[182:185], v161 offset:1024
	ds_read_b128 v[186:189], v161 offset:2048
	ds_read_b128 v[190:193], v161 offset:3072
	s_add_u32 s30, s34, 0x40000
	s_addc_u32 s31, s35, 0
	s_mov_b32 m0, s44
	v_lshl_add_u64 v[234:235], s[30:31], 0, v[128:129]
	ds_read_b128 v[194:197], v160 offset:32768
	ds_read_b128 v[198:201], v160 offset:33792
	ds_read_b128 v[202:205], v160 offset:34816
	ds_read_b128 v[206:209], v160 offset:35840
	ds_read_b128 v[210:213], v160 offset:36864
	ds_read_b128 v[214:217], v160 offset:37888
	ds_read_b128 v[218:221], v160 offset:38912
	ds_read_b128 v[222:225], v160 offset:39936
	global_load_lds_dwordx4 v[234:235], off
	v_lshl_add_u64 v[234:235], s[30:31], 0, v[132:133]
	s_mov_b32 m0, s45
	s_nop 0
	global_load_lds_dwordx4 v[234:235], off
	s_waitcnt vmcnt(8)
	s_waitcnt lgkmcnt(0)
	s_barrier
	s_setprio 1
	s_waitcnt lgkmcnt(0)
	v_mfma_f32_16x16x32_bf16 v[124:127], v[162:165], v[194:197], v[124:127]
	v_mfma_f32_16x16x32_bf16 v[120:123], v[170:173], v[194:197], v[120:123]
	v_mfma_f32_16x16x32_bf16 v[108:111], v[162:165], v[202:205], v[108:111]
	v_mfma_f32_16x16x32_bf16 v[104:107], v[170:173], v[202:205], v[104:107]
	v_mfma_f32_16x16x32_bf16 v[92:95], v[162:165], v[210:213], v[92:95]
	v_mfma_f32_16x16x32_bf16 v[88:91], v[170:173], v[210:213], v[88:91]
	v_mfma_f32_16x16x32_bf16 v[76:79], v[162:165], v[218:221], v[76:79]
	v_mfma_f32_16x16x32_bf16 v[72:75], v[170:173], v[218:221], v[72:75]
	v_mfma_f32_16x16x32_bf16 v[124:127], v[166:169], v[198:201], v[124:127]
	v_mfma_f32_16x16x32_bf16 v[120:123], v[174:177], v[198:201], v[120:123]
	v_mfma_f32_16x16x32_bf16 v[108:111], v[166:169], v[206:209], v[108:111]
	v_mfma_f32_16x16x32_bf16 v[104:107], v[174:177], v[206:209], v[104:107]
	v_mfma_f32_16x16x32_bf16 v[92:95], v[166:169], v[214:217], v[92:95]
	v_mfma_f32_16x16x32_bf16 v[88:91], v[174:177], v[214:217], v[88:91]
	v_mfma_f32_16x16x32_bf16 v[76:79], v[166:169], v[222:225], v[76:79]
	v_mfma_f32_16x16x32_bf16 v[72:75], v[174:177], v[222:225], v[72:75]
	s_setprio 0
	s_setprio 1
	v_mfma_f32_16x16x32_bf16 v[116:119], v[178:181], v[194:197], v[116:119]
	v_mfma_f32_16x16x32_bf16 v[112:115], v[186:189], v[194:197], v[112:115]
	v_mfma_f32_16x16x32_bf16 v[100:103], v[178:181], v[202:205], v[100:103]
	v_mfma_f32_16x16x32_bf16 v[96:99], v[186:189], v[202:205], v[96:99]
	v_mfma_f32_16x16x32_bf16 v[84:87], v[178:181], v[210:213], v[84:87]
	v_mfma_f32_16x16x32_bf16 v[80:83], v[186:189], v[210:213], v[80:83]
	v_mfma_f32_16x16x32_bf16 v[68:71], v[178:181], v[218:221], v[68:71]
	v_mfma_f32_16x16x32_bf16 v[64:67], v[186:189], v[218:221], v[64:67]
	v_mfma_f32_16x16x32_bf16 v[116:119], v[182:185], v[198:201], v[116:119]
	v_mfma_f32_16x16x32_bf16 v[112:115], v[190:193], v[198:201], v[112:115]
	v_mfma_f32_16x16x32_bf16 v[100:103], v[182:185], v[206:209], v[100:103]
	v_mfma_f32_16x16x32_bf16 v[96:99], v[190:193], v[206:209], v[96:99]
	v_mfma_f32_16x16x32_bf16 v[84:87], v[182:185], v[214:217], v[84:87]
	v_mfma_f32_16x16x32_bf16 v[80:83], v[190:193], v[214:217], v[80:83]
	v_mfma_f32_16x16x32_bf16 v[68:71], v[182:185], v[222:225], v[68:71]
	v_mfma_f32_16x16x32_bf16 v[64:67], v[190:193], v[222:225], v[64:67]
	s_setprio 0
	s_barrier
; #define PG8_STAGE(bufoff, gbase, voff) do { _Pragma("unroll") for (int _i = 0; _i < 2; ++_i) \
;         __builtin_amdgcn_global_load_lds((const unsigned*)((const char*)(gbase) + (voff)[_i]), (PG8_LAS unsigned*)(lds + (bufoff) + ldsw + _i * 8192), 16, 0, PG8_LOAD_AUX); } while (0)
; #define PG8_LDA(dst, b, h) do { _Pragma("unroll") for (int m = 0; m < 4; ++m) _Pragma("unroll") for (int k = 0; k < 2; ++k) dst[m][k] = *(const PG8_LAS bf16x8*)(lds + PG8_SA(b, h) + aoff + m * 2048 + k * 1024); } while (0)
; #define PG8_MMA(ai, bj, At, Bt) do { __builtin_amdgcn_s_setprio(1); _Pragma("unroll") for (int m = 0; m < 4; ++m) _Pragma("unroll") for (int n = 0; n < 2; ++n) _Pragma("unroll") for (int k = 0; k < 2; ++k) \
;         acc[ai][bj][m][n] = __builtin_amdgcn_mfma_f32_16x16x32_bf16(Bt[n][k], At[m][k], acc[ai][bj][m][n], 0, 0, 0); __builtin_amdgcn_s_setprio(0); } while (0)
; #define PG8_WAIT_V(n) asm volatile("s_waitcnt vmcnt(" #n ")" ::: "memory")
; #define PG8_WAIT_L(n) asm volatile("s_waitcnt lgkmcnt(" #n ")" ::: "memory")
; #define PG8_BAR __builtin_amdgcn_s_barrier()
; #define PG8_SCHED __builtin_amdgcn_sched_barrier(0)
; template <class Epi, class Sched, bool ALIGN_EPI = false, bool SP2 = false>
; __device__ __forceinline__ void gemm_phase(PG8_LAS unsigned char* lds, const Gemm g, const Sched& S, const Epi& E) {
;     ...
;             PG8_LDA(At, 1, 1); PG8_STAGE(PG8_SB(1, 0), b3, voffB); PG8_STAGE(PG8_SB(1, 1), b3 + hstepB, voffB); PG8_STAGE(PG8_SA(1, 0), a3, voffA);
;             PG8_WAIT_V(8); PG8_WAIT_L(0); PG8_BAR; PG8_MMA(1, 0, At, B0); PG8_MMA(1, 1, At, B1); PG8_BAR; PG8_SCHED;
;     ...
;         }
;         if constexpr (ALIGN_EPI) { if (wr == 0) PG8_BAR; }
	s_add_i32 s29, s29, s33
	v_lshl_add_u64 v[226:227], v[226:227], 0, s[10:11]
	s_mov_b32 m0, s29
	ds_read_b128 v[194:197], v160 offset:49152
	ds_read_b128 v[198:201], v160 offset:50176
	ds_read_b128 v[202:205], v160 offset:51200
	ds_read_b128 v[206:209], v160 offset:52224
	ds_read_b128 v[210:213], v160 offset:53248
	ds_read_b128 v[214:217], v160 offset:54272
	ds_read_b128 v[218:221], v160 offset:55296
	ds_read_b128 v[222:225], v160 offset:56320
	global_load_lds_dwordx4 v[226:227], off
	s_add_i32 m0, s29, 0x2000
	s_add_u32 s22, s22, 0x10080
	v_lshl_add_u64 v[226:227], v[228:229], 0, s[10:11]
	s_addc_u32 s23, s23, 0
	s_add_i32 s29, s38, s33
	global_load_lds_dwordx4 v[226:227], off
	v_lshl_add_u64 v[226:227], s[22:23], 0, v[130:131]
	s_mov_b32 m0, s29
	s_nop 0
	global_load_lds_dwordx4 v[226:227], off
	v_lshl_add_u64 v[226:227], s[22:23], 0, v[134:135]
	s_add_i32 m0, s29, 0x2000
	s_nop 0
	global_load_lds_dwordx4 v[226:227], off
	v_lshl_add_u64 v[226:227], v[230:231], 0, s[10:11]
	s_mov_b32 m0, s48
	s_nop 0
	global_load_lds_dwordx4 v[226:227], off
	v_lshl_add_u64 v[226:227], v[232:233], 0, s[10:11]
	s_mov_b32 m0, s49
	s_nop 0
	global_load_lds_dwordx4 v[226:227], off
	s_waitcnt vmcnt(8)
	s_waitcnt lgkmcnt(0)
	s_barrier
	s_setprio 1
	s_waitcnt lgkmcnt(0)
	v_mfma_f32_16x16x32_bf16 v[60:63], v[162:165], v[194:197], v[60:63]
	v_mfma_f32_16x16x32_bf16 v[56:59], v[170:173], v[194:197], v[56:59]
	v_mfma_f32_16x16x32_bf16 v[44:47], v[162:165], v[202:205], v[44:47]
	v_mfma_f32_16x16x32_bf16 v[40:43], v[170:173], v[202:205], v[40:43]
	v_mfma_f32_16x16x32_bf16 v[28:31], v[162:165], v[210:213], v[28:31]
	v_mfma_f32_16x16x32_bf16 v[24:27], v[170:173], v[210:213], v[24:27]
	v_mfma_f32_16x16x32_bf16 v[12:15], v[162:165], v[218:221], v[12:15]
	v_mfma_f32_16x16x32_bf16 v[8:11], v[170:173], v[218:221], v[8:11]
	v_mfma_f32_16x16x32_bf16 v[60:63], v[166:169], v[198:201], v[60:63]
	v_mfma_f32_16x16x32_bf16 v[56:59], v[174:177], v[198:201], v[56:59]
	v_mfma_f32_16x16x32_bf16 v[44:47], v[166:169], v[206:209], v[44:47]
	v_mfma_f32_16x16x32_bf16 v[40:43], v[174:177], v[206:209], v[40:43]
	v_mfma_f32_16x16x32_bf16 v[28:31], v[166:169], v[214:217], v[28:31]
	v_mfma_f32_16x16x32_bf16 v[24:27], v[174:177], v[214:217], v[24:27]
	v_mfma_f32_16x16x32_bf16 v[12:15], v[166:169], v[222:225], v[12:15]
	v_mfma_f32_16x16x32_bf16 v[8:11], v[174:177], v[222:225], v[8:11]
	s_setprio 0
	s_setprio 1
	v_mfma_f32_16x16x32_bf16 v[52:55], v[178:181], v[194:197], v[52:55]
	v_mfma_f32_16x16x32_bf16 v[48:51], v[186:189], v[194:197], v[48:51]
	v_mfma_f32_16x16x32_bf16 v[36:39], v[178:181], v[202:205], v[36:39]
	v_mfma_f32_16x16x32_bf16 v[32:35], v[186:189], v[202:205], v[32:35]
	v_mfma_f32_16x16x32_bf16 v[20:23], v[178:181], v[210:213], v[20:23]
	v_mfma_f32_16x16x32_bf16 v[16:19], v[186:189], v[210:213], v[16:19]
	v_mfma_f32_16x16x32_bf16 v[4:7], v[178:181], v[218:221], v[4:7]
	v_mfma_f32_16x16x32_bf16 v[0:3], v[186:189], v[218:221], v[0:3]
	v_mfma_f32_16x16x32_bf16 v[52:55], v[182:185], v[198:201], v[52:55]
	v_mfma_f32_16x16x32_bf16 v[48:51], v[190:193], v[198:201], v[48:51]
	v_mfma_f32_16x16x32_bf16 v[36:39], v[182:185], v[206:209], v[36:39]
	v_mfma_f32_16x16x32_bf16 v[32:35], v[190:193], v[206:209], v[32:35]
	v_mfma_f32_16x16x32_bf16 v[20:23], v[182:185], v[214:217], v[20:23]
	v_mfma_f32_16x16x32_bf16 v[16:19], v[190:193], v[214:217], v[16:19]
	v_mfma_f32_16x16x32_bf16 v[4:7], v[182:185], v[222:225], v[4:7]
	v_mfma_f32_16x16x32_bf16 v[0:3], v[190:193], v[222:225], v[0:3]
	s_setprio 0
	s_barrier
	s_add_i32 s28, s28, 2
	s_add_u32 s20, s20, 0x100
	s_addc_u32 s21, s21, 0
	s_add_u32 s26, s26, 0x100
	s_addc_u32 s27, s27, 0
	s_cmp_gt_u32 s28, 13
	s_cbranch_scc0 .LBB0_215
	s_and_b64 vcc, exec, s[12:13]
	s_cbranch_vccz .LBB0_218
	s_barrier

; #define PG8_STAGE(bufoff, gbase, voff) do { _Pragma("unroll") for (int _i = 0; _i < 2; ++_i) \
;         __builtin_amdgcn_global_load_lds((const unsigned*)((const char*)(gbase) + (voff)[_i]), (PG8_LAS unsigned*)(lds + (bufoff) + ldsw + _i * 8192), 16, 0, PG8_LOAD_AUX); } while (0)
; #define PG8_LDA(dst, b, h) do { _Pragma("unroll") for (int m = 0; m < 4; ++m) _Pragma("unroll") for (int k = 0; k < 2; ++k) dst[m][k] = *(const PG8_LAS bf16x8*)(lds + PG8_SA(b, h) + aoff + m * 2048 + k * 1024); } while (0)
; #define PG8_LDB(dst, b, h) do { _Pragma("unroll") for (int n = 0; n < 2; ++n) _Pragma("unroll") for (int k = 0; k < 2; ++k) dst[n][k] = *(const PG8_LAS bf16x8*)(lds + PG8_SB(b, h) + boff + n * 2048 + k * 1024); } while (0)
; #define PG8_MMA(ai, bj, At, Bt) do { __builtin_amdgcn_s_setprio(1); _Pragma("unroll") for (int m = 0; m < 4; ++m) _Pragma("unroll") for (int n = 0; n < 2; ++n) _Pragma("unroll") for (int k = 0; k < 2; ++k) \
;         acc[ai][bj][m][n] = __builtin_amdgcn_mfma_f32_16x16x32_bf16(Bt[n][k], At[m][k], acc[ai][bj][m][n], 0, 0, 0); __builtin_amdgcn_s_setprio(0); } while (0)
; #define PG8_WAIT_V(n) asm volatile("s_waitcnt vmcnt(" #n ")" ::: "memory")
; #define PG8_WAIT_L(n) asm volatile("s_waitcnt lgkmcnt(" #n ")" ::: "memory")
; #define PG8_BAR __builtin_amdgcn_s_barrier()
; #define PG8_SCHED __builtin_amdgcn_sched_barrier(0)
; template <class Epi, class Sched, bool ALIGN_EPI = false, bool SP2 = false>
; __device__ __forceinline__ void gemm_phase(PG8_LAS unsigned char* lds, const Gemm g, const Sched& S, const Epi& E) {
;     ...
;             const bool last = (t == nt - 2);
;             const char* a1 = cA + (size_t)(t + 1) * kstep;
;             const char* a2 = last ? nA : cA + (size_t)(t + 2) * kstep; const char* b2 = last ? nB : cB + (size_t)(t + 2) * kstep;
;             const char* a3 = a2 + kstep; const char* b3 = b2 + kstep;
;             if (last && has_next) S.a_ready(nxt);
;             if constexpr (SP2) {
;             PG8_LDB(B0, 0, 0); PG8_LDB(B1, 0, 1); PG8_SCHED; PG8_LDA(At, 0, 0); PG8_STAGE(PG8_SA(1, 1), a1 + hstepA, voffA);
;             PG8_WAIT_V(8); PG8_WAIT_L(0); PG8_BAR; PG8_MMA(0, 0, At, B0); PG8_MMA(0, 1, At, B1); PG8_BAR; PG8_SCHED;
.LBB0_368:
	s_ashr_i32 s17, s16, 31
	s_lshl_b64 s[18:19], s[16:17], 19
	s_add_u32 s18, s33, s18
	s_addc_u32 s19, s36, s19
	s_and_b64 s[24:25], s[4:5], exec
	s_cselect_b32 s17, s19, s21
	s_cselect_b32 s24, s18, s20
	s_ashr_i32 s15, s14, 31
	s_lshl_b64 s[26:27], s[14:15], 19
	s_add_u32 s40, s64, s26
	s_addc_u32 s41, s65, s27
	s_and_b64 s[26:27], s[4:5], exec
	s_cselect_b32 s15, s41, s23
	s_cselect_b32 s25, s40, s22
	s_add_u32 s20, s20, 0x40080
	s_addc_u32 s21, s21, 0
	s_add_u32 s26, s22, 0x100
	s_addc_u32 s27, s23, 0
	s_mov_b32 s28, -2
	ds_read_b128 v[162:165], v159
	ds_read_b128 v[166:169], v159 offset:1024
	ds_read_b128 v[170:173], v159 offset:2048
	ds_read_b128 v[174:177], v159 offset:3072
	ds_read_b128 v[178:181], v160
	ds_read_b128 v[182:185], v160 offset:1024
	ds_read_b128 v[186:189], v160 offset:2048
	ds_read_b128 v[190:193], v160 offset:3072
	s_add_u32 s22, s20, 0xfffc0080
	s_addc_u32 s23, s21, -1
	s_cmp_eq_u32 s28, 12
	s_cselect_b32 s35, s17, s23
	s_cselect_b32 s34, s24, s22
	s_cselect_b32 s23, s15, s27
	s_cselect_b32 s22, s25, s26
	v_lshl_add_u64 v[226:227], s[20:21], 0, v[138:139]
	s_add_i32 m0, s44, 0xc000
	ds_read_b128 v[194:197], v161
	ds_read_b128 v[198:201], v161 offset:1024
	ds_read_b128 v[202:205], v161 offset:2048
	ds_read_b128 v[206:209], v161 offset:3072
	ds_read_b128 v[210:213], v161 offset:4096
	ds_read_b128 v[214:217], v161 offset:5120
	ds_read_b128 v[218:221], v161 offset:6144
	ds_read_b128 v[222:225], v161 offset:7168
	global_load_lds_dwordx4 v[226:227], off
	v_lshl_add_u64 v[226:227], s[20:21], 0, v[140:141]
	s_add_i32 m0, s44, 0xe000
	s_nop 0
	global_load_lds_dwordx4 v[226:227], off
	s_waitcnt vmcnt(8)
	s_waitcnt lgkmcnt(0)
	s_barrier
	s_setprio 1
	s_waitcnt lgkmcnt(0)
	v_mfma_f32_16x16x32_bf16 v[124:127], v[162:165], v[194:197], 0
	v_mfma_f32_16x16x32_bf16 v[120:123], v[170:173], v[194:197], 0
	v_mfma_f32_16x16x32_bf16 v[108:111], v[162:165], v[202:205], 0
	v_mfma_f32_16x16x32_bf16 v[104:107], v[170:173], v[202:205], 0
	v_mfma_f32_16x16x32_bf16 v[92:95], v[162:165], v[210:213], 0
	v_mfma_f32_16x16x32_bf16 v[88:91], v[170:173], v[210:213], 0
	v_mfma_f32_16x16x32_bf16 v[76:79], v[162:165], v[218:221], 0
	v_mfma_f32_16x16x32_bf16 v[72:75], v[170:173], v[218:221], 0
	v_mfma_f32_16x16x32_bf16 v[124:127], v[166:169], v[198:201], v[124:127]
	v_mfma_f32_16x16x32_bf16 v[120:123], v[174:177], v[198:201], v[120:123]
	v_mfma_f32_16x16x32_bf16 v[108:111], v[166:169], v[206:209], v[108:111]
	v_mfma_f32_16x16x32_bf16 v[104:107], v[174:177], v[206:209], v[104:107]
	v_mfma_f32_16x16x32_bf16 v[92:95], v[166:169], v[214:217], v[92:95]
	v_mfma_f32_16x16x32_bf16 v[88:91], v[174:177], v[214:217], v[88:91]
	v_mfma_f32_16x16x32_bf16 v[76:79], v[166:169], v[222:225], v[76:79]
	v_mfma_f32_16x16x32_bf16 v[72:75], v[174:177], v[222:225], v[72:75]
	s_setprio 0
	s_setprio 1
	v_mfma_f32_16x16x32_bf16 v[116:119], v[178:181], v[194:197], 0
	v_mfma_f32_16x16x32_bf16 v[112:115], v[186:189], v[194:197], 0
	v_mfma_f32_16x16x32_bf16 v[100:103], v[178:181], v[202:205], 0
	v_mfma_f32_16x16x32_bf16 v[96:99], v[186:189], v[202:205], 0
	v_mfma_f32_16x16x32_bf16 v[84:87], v[178:181], v[210:213], 0
	v_mfma_f32_16x16x32_bf16 v[80:83], v[186:189], v[210:213], 0
	v_mfma_f32_16x16x32_bf16 v[68:71], v[178:181], v[218:221], 0
	v_mfma_f32_16x16x32_bf16 v[64:67], v[186:189], v[218:221], 0
	v_mfma_f32_16x16x32_bf16 v[116:119], v[182:185], v[198:201], v[116:119]
	v_mfma_f32_16x16x32_bf16 v[112:115], v[190:193], v[198:201], v[112:115]
	v_mfma_f32_16x16x32_bf16 v[100:103], v[182:185], v[206:209], v[100:103]
	v_mfma_f32_16x16x32_bf16 v[96:99], v[190:193], v[206:209], v[96:99]
	v_mfma_f32_16x16x32_bf16 v[84:87], v[182:185], v[214:217], v[84:87]
	v_mfma_f32_16x16x32_bf16 v[80:83], v[190:193], v[214:217], v[80:83]
	v_mfma_f32_16x16x32_bf16 v[68:71], v[182:185], v[222:225], v[68:71]
	v_mfma_f32_16x16x32_bf16 v[64:67], v[190:193], v[222:225], v[64:67]
	s_setprio 0
	s_barrier
; #define PG8_STAGE(bufoff, gbase, voff) do { _Pragma("unroll") for (int _i = 0; _i < 2; ++_i) \
;         __builtin_amdgcn_global_load_lds((const unsigned*)((const char*)(gbase) + (voff)[_i]), (PG8_LAS unsigned*)(lds + (bufoff) + ldsw + _i * 8192), 16, 0, PG8_LOAD_AUX); } while (0)
; #define PG8_LDA(dst, b, h) do { _Pragma("unroll") for (int m = 0; m < 4; ++m) _Pragma("unroll") for (int k = 0; k < 2; ++k) dst[m][k] = *(const PG8_LAS bf16x8*)(lds + PG8_SA(b, h) + aoff + m * 2048 + k * 1024); } while (0)
; #define PG8_MMA(ai, bj, At, Bt) do { __builtin_amdgcn_s_setprio(1); _Pragma("unroll") for (int m = 0; m < 4; ++m) _Pragma("unroll") for (int n = 0; n < 2; ++n) _Pragma("unroll") for (int k = 0; k < 2; ++k) \
;         acc[ai][bj][m][n] = __builtin_amdgcn_mfma_f32_16x16x32_bf16(Bt[n][k], At[m][k], acc[ai][bj][m][n], 0, 0, 0); __builtin_amdgcn_s_setprio(0); } while (0)
; #define PG8_WAIT_V(n) asm volatile("s_waitcnt vmcnt(" #n ")" ::: "memory")
; #define PG8_WAIT_L(n) asm volatile("s_waitcnt lgkmcnt(" #n ")" ::: "memory")
; #define PG8_BAR __builtin_amdgcn_s_barrier()
; #define PG8_SCHED __builtin_amdgcn_sched_barrier(0)
; template <class Epi, class Sched, bool ALIGN_EPI = false, bool SP2 = false>
; __device__ __forceinline__ void gemm_phase(PG8_LAS unsigned char* lds, const Gemm g, const Sched& S, const Epi& E) {
;     ...
;             PG8_LDA(At, 0, 1); PG8_STAGE(PG8_SB(0, 0), b2, voffB); PG8_STAGE(PG8_SB(0, 1), b2 + hstepB, voffB); PG8_STAGE(PG8_SA(0, 0), a2, voffA);
;             PG8_WAIT_V(8); PG8_WAIT_L(0); PG8_BAR; PG8_MMA(1, 0, At, B0); PG8_MMA(1, 1, At, B1); PG8_BAR; PG8_SCHED;
	s_add_i32 s29, s53, s37
	v_lshl_add_u64 v[226:227], s[22:23], 0, v[132:133]
	s_mov_b32 m0, s29
	ds_read_b128 v[194:197], v161 offset:16384
	ds_read_b128 v[198:201], v161 offset:17408
	ds_read_b128 v[202:205], v161 offset:18432
	ds_read_b128 v[206:209], v161 offset:19456
	ds_read_b128 v[210:213], v161 offset:20480
	ds_read_b128 v[214:217], v161 offset:21504
	ds_read_b128 v[218:221], v161 offset:22528
	ds_read_b128 v[222:225], v161 offset:23552
	global_load_lds_dwordx4 v[226:227], off
	s_add_i32 m0, s29, 0x2000
	s_add_u32 s30, s22, 0x10000
	v_lshl_add_u64 v[228:229], s[22:23], 0, v[128:129]
	s_addc_u32 s31, s23, 0
	s_add_i32 s29, s54, s37
	global_load_lds_dwordx4 v[228:229], off
	v_lshl_add_u64 v[230:231], s[30:31], 0, v[132:133]
	s_mov_b32 m0, s29
	v_lshl_add_u64 v[232:233], s[34:35], 0, v[130:131]
	global_load_lds_dwordx4 v[230:231], off
	v_lshl_add_u64 v[230:231], s[30:31], 0, v[128:129]
	s_add_i32 m0, s29, 0x2000
	s_nop 0
	global_load_lds_dwordx4 v[230:231], off
	v_lshl_add_u64 v[230:231], s[34:35], 0, v[134:135]
	s_mov_b32 m0, s44
	s_nop 0
	global_load_lds_dwordx4 v[230:231], off
	s_mov_b32 m0, s45
	s_nop 0
	global_load_lds_dwordx4 v[232:233], off
	s_waitcnt vmcnt(8)
	s_waitcnt lgkmcnt(0)
	s_barrier
	s_setprio 1
	s_waitcnt lgkmcnt(0)
	v_mfma_f32_16x16x32_bf16 v[60:63], v[162:165], v[194:197], 0
	v_mfma_f32_16x16x32_bf16 v[56:59], v[170:173], v[194:197], 0
	v_mfma_f32_16x16x32_bf16 v[44:47], v[162:165], v[202:205], 0
	v_mfma_f32_16x16x32_bf16 v[40:43], v[170:173], v[202:205], 0
	v_mfma_f32_16x16x32_bf16 v[28:31], v[162:165], v[210:213], 0
	v_mfma_f32_16x16x32_bf16 v[24:27], v[170:173], v[210:213], 0
	v_mfma_f32_16x16x32_bf16 v[12:15], v[162:165], v[218:221], 0
	v_mfma_f32_16x16x32_bf16 v[8:11], v[170:173], v[218:221], 0
	v_mfma_f32_16x16x32_bf16 v[60:63], v[166:169], v[198:201], v[60:63]
	v_mfma_f32_16x16x32_bf16 v[56:59], v[174:177], v[198:201], v[56:59]
	v_mfma_f32_16x16x32_bf16 v[44:47], v[166:169], v[206:209], v[44:47]
	v_mfma_f32_16x16x32_bf16 v[40:43], v[174:177], v[206:209], v[40:43]
	v_mfma_f32_16x16x32_bf16 v[28:31], v[166:169], v[214:217], v[28:31]
	v_mfma_f32_16x16x32_bf16 v[24:27], v[174:177], v[214:217], v[24:27]
	v_mfma_f32_16x16x32_bf16 v[12:15], v[166:169], v[222:225], v[12:15]
	v_mfma_f32_16x16x32_bf16 v[8:11], v[174:177], v[222:225], v[8:11]
	s_setprio 0
	s_setprio 1
	v_mfma_f32_16x16x32_bf16 v[52:55], v[178:181], v[194:197], 0
	v_mfma_f32_16x16x32_bf16 v[48:51], v[186:189], v[194:197], 0
	v_mfma_f32_16x16x32_bf16 v[36:39], v[178:181], v[202:205], 0
	v_mfma_f32_16x16x32_bf16 v[32:35], v[186:189], v[202:205], 0
	v_mfma_f32_16x16x32_bf16 v[20:23], v[178:181], v[210:213], 0
	v_mfma_f32_16x16x32_bf16 v[16:19], v[186:189], v[210:213], 0
	v_mfma_f32_16x16x32_bf16 v[4:7], v[178:181], v[218:221], 0
	v_mfma_f32_16x16x32_bf16 v[0:3], v[186:189], v[218:221], 0
	v_mfma_f32_16x16x32_bf16 v[52:55], v[182:185], v[198:201], v[52:55]
	v_mfma_f32_16x16x32_bf16 v[48:51], v[190:193], v[198:201], v[48:51]
	v_mfma_f32_16x16x32_bf16 v[36:39], v[182:185], v[206:209], v[36:39]
	v_mfma_f32_16x16x32_bf16 v[32:35], v[190:193], v[206:209], v[32:35]
	v_mfma_f32_16x16x32_bf16 v[20:23], v[182:185], v[214:217], v[20:23]
	v_mfma_f32_16x16x32_bf16 v[16:19], v[190:193], v[214:217], v[16:19]
	v_mfma_f32_16x16x32_bf16 v[4:7], v[182:185], v[222:225], v[4:7]
	v_mfma_f32_16x16x32_bf16 v[0:3], v[190:193], v[222:225], v[0:3]
	s_setprio 0
	s_barrier
	s_branch .Lkmid_P3

; #define PG8_STAGE(bufoff, gbase, voff) do { _Pragma("unroll") for (int _i = 0; _i < 2; ++_i) \
;         __builtin_amdgcn_global_load_lds((const unsigned*)((const char*)(gbase) + (voff)[_i]), (PG8_LAS unsigned*)(lds + (bufoff) + ldsw + _i * 8192), 16, 0, PG8_LOAD_AUX); } while (0)
; #define PG8_LDA(dst, b, h) do { _Pragma("unroll") for (int m = 0; m < 4; ++m) _Pragma("unroll") for (int k = 0; k < 2; ++k) dst[m][k] = *(const PG8_LAS bf16x8*)(lds + PG8_SA(b, h) + aoff + m * 2048 + k * 1024); } while (0)
; #define PG8_LDB(dst, b, h) do { _Pragma("unroll") for (int n = 0; n < 2; ++n) _Pragma("unroll") for (int k = 0; k < 2; ++k) dst[n][k] = *(const PG8_LAS bf16x8*)(lds + PG8_SB(b, h) + boff + n * 2048 + k * 1024); } while (0)
; #define PG8_MMA(ai, bj, At, Bt) do { __builtin_amdgcn_s_setprio(1); _Pragma("unroll") for (int m = 0; m < 4; ++m) _Pragma("unroll") for (int n = 0; n < 2; ++n) _Pragma("unroll") for (int k = 0; k < 2; ++k) \
;         acc[ai][bj][m][n] = __builtin_amdgcn_mfma_f32_16x16x32_bf16(Bt[n][k], At[m][k], acc[ai][bj][m][n], 0, 0, 0); __builtin_amdgcn_s_setprio(0); } while (0)
; #define PG8_WAIT_V(n) asm volatile("s_waitcnt vmcnt(" #n ")" ::: "memory")
; #define PG8_WAIT_L(n) asm volatile("s_waitcnt lgkmcnt(" #n ")" ::: "memory")
; #define PG8_BAR __builtin_amdgcn_s_barrier()
; #define PG8_SCHED __builtin_amdgcn_sched_barrier(0)
; template <class Epi, class Sched, bool ALIGN_EPI = false, bool SP2 = false>
; __device__ __forceinline__ void gemm_phase(PG8_LAS unsigned char* lds, const Gemm g, const Sched& S, const Epi& E) {
;     ...
;             PG8_LDB(B0, 1, 0); PG8_LDB(B1, 1, 1); PG8_SCHED; PG8_LDA(At, 1, 0); PG8_STAGE(PG8_SA(0, 1), a2 + hstepA, voffA);
;             PG8_WAIT_V(8); PG8_WAIT_L(0); PG8_BAR; PG8_MMA(0, 0, At, B0); PG8_MMA(0, 1, At, B1); PG8_BAR; PG8_SCHED;
.Lkmid_P3:
	s_add_i32 s29, 0, 0x18000
	s_add_i32 s38, 0, 0x1c000
	v_add_u32_e32 v174, s29, v146
	v_add_u32_e32 v190, s38, v146
	ds_read_b128 v[162:165], v174
	ds_read_b128 v[166:169], v174 offset:1024
	ds_read_b128 v[170:173], v174 offset:2048
	ds_read_b128 v[174:177], v174 offset:3072
	ds_read_b128 v[178:181], v190
	ds_read_b128 v[182:185], v190 offset:1024
	ds_read_b128 v[186:189], v190 offset:2048
	ds_read_b128 v[190:193], v190 offset:3072
	s_add_u32 s30, s34, 0x40000
	s_addc_u32 s31, s35, 0
	s_mov_b32 m0, s46
	v_lshl_add_u64 v[234:235], s[30:31], 0, v[134:135]
	ds_read_b128 v[194:197], v161 offset:32768
	ds_read_b128 v[198:201], v161 offset:33792
	ds_read_b128 v[202:205], v161 offset:34816
	ds_read_b128 v[206:209], v161 offset:35840
	ds_read_b128 v[210:213], v161 offset:36864
	ds_read_b128 v[214:217], v161 offset:37888
	ds_read_b128 v[218:221], v161 offset:38912
	ds_read_b128 v[222:225], v161 offset:39936
	global_load_lds_dwordx4 v[234:235], off
	v_lshl_add_u64 v[234:235], s[30:31], 0, v[130:131]
	s_mov_b32 m0, s47
	s_nop 0
	global_load_lds_dwordx4 v[234:235], off
	s_waitcnt vmcnt(8)
	s_waitcnt lgkmcnt(0)
	s_barrier
	s_setprio 1
	s_waitcnt lgkmcnt(0)
	v_mfma_f32_16x16x32_bf16 v[124:127], v[162:165], v[194:197], v[124:127]
	v_mfma_f32_16x16x32_bf16 v[120:123], v[170:173], v[194:197], v[120:123]
	v_mfma_f32_16x16x32_bf16 v[108:111], v[162:165], v[202:205], v[108:111]
	v_mfma_f32_16x16x32_bf16 v[104:107], v[170:173], v[202:205], v[104:107]
	v_mfma_f32_16x16x32_bf16 v[92:95], v[162:165], v[210:213], v[92:95]
	v_mfma_f32_16x16x32_bf16 v[88:91], v[170:173], v[210:213], v[88:91]
	v_mfma_f32_16x16x32_bf16 v[76:79], v[162:165], v[218:221], v[76:79]
	v_mfma_f32_16x16x32_bf16 v[72:75], v[170:173], v[218:221], v[72:75]
	v_mfma_f32_16x16x32_bf16 v[124:127], v[166:169], v[198:201], v[124:127]
	v_mfma_f32_16x16x32_bf16 v[120:123], v[174:177], v[198:201], v[120:123]
	v_mfma_f32_16x16x32_bf16 v[108:111], v[166:169], v[206:209], v[108:111]
	v_mfma_f32_16x16x32_bf16 v[104:107], v[174:177], v[206:209], v[104:107]
	v_mfma_f32_16x16x32_bf16 v[92:95], v[166:169], v[214:217], v[92:95]
	v_mfma_f32_16x16x32_bf16 v[88:91], v[174:177], v[214:217], v[88:91]
	v_mfma_f32_16x16x32_bf16 v[76:79], v[166:169], v[222:225], v[76:79]
	v_mfma_f32_16x16x32_bf16 v[72:75], v[174:177], v[222:225], v[72:75]
	s_setprio 0
	s_setprio 1
	v_mfma_f32_16x16x32_bf16 v[116:119], v[178:181], v[194:197], v[116:119]
	v_mfma_f32_16x16x32_bf16 v[112:115], v[186:189], v[194:197], v[112:115]
	v_mfma_f32_16x16x32_bf16 v[100:103], v[178:181], v[202:205], v[100:103]
	v_mfma_f32_16x16x32_bf16 v[96:99], v[186:189], v[202:205], v[96:99]
	v_mfma_f32_16x16x32_bf16 v[84:87], v[178:181], v[210:213], v[84:87]
	v_mfma_f32_16x16x32_bf16 v[80:83], v[186:189], v[210:213], v[80:83]
	v_mfma_f32_16x16x32_bf16 v[68:71], v[178:181], v[218:221], v[68:71]
	v_mfma_f32_16x16x32_bf16 v[64:67], v[186:189], v[218:221], v[64:67]
	v_mfma_f32_16x16x32_bf16 v[116:119], v[182:185], v[198:201], v[116:119]
	v_mfma_f32_16x16x32_bf16 v[112:115], v[190:193], v[198:201], v[112:115]
	v_mfma_f32_16x16x32_bf16 v[100:103], v[182:185], v[206:209], v[100:103]
	v_mfma_f32_16x16x32_bf16 v[96:99], v[190:193], v[206:209], v[96:99]
	v_mfma_f32_16x16x32_bf16 v[84:87], v[182:185], v[214:217], v[84:87]
	v_mfma_f32_16x16x32_bf16 v[80:83], v[190:193], v[214:217], v[80:83]
	v_mfma_f32_16x16x32_bf16 v[68:71], v[182:185], v[222:225], v[68:71]
	v_mfma_f32_16x16x32_bf16 v[64:67], v[190:193], v[222:225], v[64:67]
	s_setprio 0
	s_barrier
; #define PG8_STAGE(bufoff, gbase, voff) do { _Pragma("unroll") for (int _i = 0; _i < 2; ++_i) \
;         __builtin_amdgcn_global_load_lds((const unsigned*)((const char*)(gbase) + (voff)[_i]), (PG8_LAS unsigned*)(lds + (bufoff) + ldsw + _i * 8192), 16, 0, PG8_LOAD_AUX); } while (0)
; #define PG8_LDA(dst, b, h) do { _Pragma("unroll") for (int m = 0; m < 4; ++m) _Pragma("unroll") for (int k = 0; k < 2; ++k) dst[m][k] = *(const PG8_LAS bf16x8*)(lds + PG8_SA(b, h) + aoff + m * 2048 + k * 1024); } while (0)
; #define PG8_MMA(ai, bj, At, Bt) do { __builtin_amdgcn_s_setprio(1); _Pragma("unroll") for (int m = 0; m < 4; ++m) _Pragma("unroll") for (int n = 0; n < 2; ++n) _Pragma("unroll") for (int k = 0; k < 2; ++k) \
;         acc[ai][bj][m][n] = __builtin_amdgcn_mfma_f32_16x16x32_bf16(Bt[n][k], At[m][k], acc[ai][bj][m][n], 0, 0, 0); __builtin_amdgcn_s_setprio(0); } while (0)
; #define PG8_WAIT_V(n) asm volatile("s_waitcnt vmcnt(" #n ")" ::: "memory")
; #define PG8_WAIT_L(n) asm volatile("s_waitcnt lgkmcnt(" #n ")" ::: "memory")
; #define PG8_BAR __builtin_amdgcn_s_barrier()
; #define PG8_SCHED __builtin_amdgcn_sched_barrier(0)
; template <class Epi, class Sched, bool ALIGN_EPI = false, bool SP2 = false>
; __device__ __forceinline__ void gemm_phase(PG8_LAS unsigned char* lds, const Gemm g, const Sched& S, const Epi& E) {
;     ...
;             PG8_LDA(At, 1, 1); PG8_STAGE(PG8_SB(1, 0), b3, voffB); PG8_STAGE(PG8_SB(1, 1), b3 + hstepB, voffB); PG8_STAGE(PG8_SA(1, 0), a3, voffA);
;             PG8_WAIT_V(8); PG8_WAIT_L(0); PG8_BAR; PG8_MMA(1, 0, At, B0); PG8_MMA(1, 1, At, B1); PG8_BAR; PG8_SCHED;
;     ...
;         }
;         if constexpr (ALIGN_EPI) { if (wr == 0) PG8_BAR; }
	s_add_i32 s29, s29, s37
	v_lshl_add_u64 v[226:227], v[226:227], 0, s[10:11]
	s_mov_b32 m0, s29
	ds_read_b128 v[194:197], v161 offset:49152
	ds_read_b128 v[198:201], v161 offset:50176
	ds_read_b128 v[202:205], v161 offset:51200
	ds_read_b128 v[206:209], v161 offset:52224
	ds_read_b128 v[210:213], v161 offset:53248
	ds_read_b128 v[214:217], v161 offset:54272
	ds_read_b128 v[218:221], v161 offset:55296
	ds_read_b128 v[222:225], v161 offset:56320
	global_load_lds_dwordx4 v[226:227], off
	s_add_i32 m0, s29, 0x2000
	s_add_u32 s22, s22, 0x10080
	v_lshl_add_u64 v[226:227], v[228:229], 0, s[10:11]
	s_addc_u32 s23, s23, 0
	s_add_i32 s29, s38, s37
	global_load_lds_dwordx4 v[226:227], off
	v_lshl_add_u64 v[226:227], s[22:23], 0, v[132:133]
	s_mov_b32 m0, s29
	s_nop 0
	global_load_lds_dwordx4 v[226:227], off
	v_lshl_add_u64 v[226:227], s[22:23], 0, v[128:129]
	s_add_i32 m0, s29, 0x2000
	s_nop 0
	global_load_lds_dwordx4 v[226:227], off
	v_lshl_add_u64 v[226:227], v[230:231], 0, s[10:11]
	s_mov_b32 m0, s49
	s_nop 0
	global_load_lds_dwordx4 v[226:227], off
	v_lshl_add_u64 v[226:227], v[232:233], 0, s[10:11]
	s_mov_b32 m0, s50
	s_nop 0
	global_load_lds_dwordx4 v[226:227], off
	s_waitcnt vmcnt(8)
	s_waitcnt lgkmcnt(0)
	s_barrier
	s_setprio 1
	s_waitcnt lgkmcnt(0)
	v_mfma_f32_16x16x32_bf16 v[60:63], v[162:165], v[194:197], v[60:63]
	v_mfma_f32_16x16x32_bf16 v[56:59], v[170:173], v[194:197], v[56:59]
	v_mfma_f32_16x16x32_bf16 v[44:47], v[162:165], v[202:205], v[44:47]
	v_mfma_f32_16x16x32_bf16 v[40:43], v[170:173], v[202:205], v[40:43]
	v_mfma_f32_16x16x32_bf16 v[28:31], v[162:165], v[210:213], v[28:31]
	v_mfma_f32_16x16x32_bf16 v[24:27], v[170:173], v[210:213], v[24:27]
	v_mfma_f32_16x16x32_bf16 v[12:15], v[162:165], v[218:221], v[12:15]
	v_mfma_f32_16x16x32_bf16 v[8:11], v[170:173], v[218:221], v[8:11]
	v_mfma_f32_16x16x32_bf16 v[60:63], v[166:169], v[198:201], v[60:63]
	v_mfma_f32_16x16x32_bf16 v[56:59], v[174:177], v[198:201], v[56:59]
	v_mfma_f32_16x16x32_bf16 v[44:47], v[166:169], v[206:209], v[44:47]
	v_mfma_f32_16x16x32_bf16 v[40:43], v[174:177], v[206:209], v[40:43]
	v_mfma_f32_16x16x32_bf16 v[28:31], v[166:169], v[214:217], v[28:31]
	v_mfma_f32_16x16x32_bf16 v[24:27], v[174:177], v[214:217], v[24:27]
	v_mfma_f32_16x16x32_bf16 v[12:15], v[166:169], v[222:225], v[12:15]
	v_mfma_f32_16x16x32_bf16 v[8:11], v[174:177], v[222:225], v[8:11]
	s_setprio 0
	s_setprio 1
	v_mfma_f32_16x16x32_bf16 v[52:55], v[178:181], v[194:197], v[52:55]
	v_mfma_f32_16x16x32_bf16 v[48:51], v[186:189], v[194:197], v[48:51]
	v_mfma_f32_16x16x32_bf16 v[36:39], v[178:181], v[202:205], v[36:39]
	v_mfma_f32_16x16x32_bf16 v[32:35], v[186:189], v[202:205], v[32:35]
	v_mfma_f32_16x16x32_bf16 v[20:23], v[178:181], v[210:213], v[20:23]
	v_mfma_f32_16x16x32_bf16 v[16:19], v[186:189], v[210:213], v[16:19]
	v_mfma_f32_16x16x32_bf16 v[4:7], v[178:181], v[218:221], v[4:7]
	v_mfma_f32_16x16x32_bf16 v[0:3], v[186:189], v[218:221], v[0:3]
	v_mfma_f32_16x16x32_bf16 v[52:55], v[182:185], v[198:201], v[52:55]
	v_mfma_f32_16x16x32_bf16 v[48:51], v[190:193], v[198:201], v[48:51]
	v_mfma_f32_16x16x32_bf16 v[36:39], v[182:185], v[206:209], v[36:39]
	v_mfma_f32_16x16x32_bf16 v[32:35], v[190:193], v[206:209], v[32:35]
	v_mfma_f32_16x16x32_bf16 v[20:23], v[182:185], v[214:217], v[20:23]
	v_mfma_f32_16x16x32_bf16 v[16:19], v[190:193], v[214:217], v[16:19]
	v_mfma_f32_16x16x32_bf16 v[4:7], v[182:185], v[222:225], v[4:7]
	v_mfma_f32_16x16x32_bf16 v[0:3], v[190:193], v[222:225], v[0:3]
	s_setprio 0
	s_barrier
	s_add_i32 s28, s28, 2
	s_add_u32 s20, s20, 0x100
	s_addc_u32 s21, s21, 0
	s_add_u32 s26, s26, 0x100
	s_addc_u32 s27, s27, 0
	s_cmp_gt_u32 s28, 13
	s_cbranch_scc0 .LBB0_369
	s_and_b64 vcc, exec, s[12:13]
	s_cbranch_vccz .LBB0_372
	s_barrier

; #define PG8_STAGE(bufoff, gbase, voff) do { _Pragma("unroll") for (int _i = 0; _i < 2; ++_i) \
;         __builtin_amdgcn_global_load_lds((const unsigned*)((const char*)(gbase) + (voff)[_i]), (PG8_LAS unsigned*)(lds + (bufoff) + ldsw + _i * 8192), 16, 0, PG8_LOAD_AUX); } while (0)
; #define PG8_LDA(dst, b, h) do { _Pragma("unroll") for (int m = 0; m < 4; ++m) _Pragma("unroll") for (int k = 0; k < 2; ++k) dst[m][k] = *(const PG8_LAS bf16x8*)(lds + PG8_SA(b, h) + aoff + m * 2048 + k * 1024); } while (0)
; #define PG8_LDB(dst, b, h) do { _Pragma("unroll") for (int n = 0; n < 2; ++n) _Pragma("unroll") for (int k = 0; k < 2; ++k) dst[n][k] = *(const PG8_LAS bf16x8*)(lds + PG8_SB(b, h) + boff + n * 2048 + k * 1024); } while (0)
; #define PG8_MMA(ai, bj, At, Bt) do { __builtin_amdgcn_s_setprio(1); _Pragma("unroll") for (int m = 0; m < 4; ++m) _Pragma("unroll") for (int n = 0; n < 2; ++n) _Pragma("unroll") for (int k = 0; k < 2; ++k) \
;         acc[ai][bj][m][n] = __builtin_amdgcn_mfma_f32_16x16x32_bf16(Bt[n][k], At[m][k], acc[ai][bj][m][n], 0, 0, 0); __builtin_amdgcn_s_setprio(0); } while (0)
; #define PG8_WAIT_V(n) asm volatile("s_waitcnt vmcnt(" #n ")" ::: "memory")
; #define PG8_WAIT_L(n) asm volatile("s_waitcnt lgkmcnt(" #n ")" ::: "memory")
; #define PG8_BAR __builtin_amdgcn_s_barrier()
; #define PG8_SCHED __builtin_amdgcn_sched_barrier(0)
; template <class Epi, class Sched, bool ALIGN_EPI = false, bool SP2 = false>
; __device__ __forceinline__ void gemm_phase(PG8_LAS unsigned char* lds, const Gemm g, const Sched& S, const Epi& E) {
;     ...
;             const bool last = (t == nt - 2);
;             const char* a1 = cA + (size_t)(t + 1) * kstep;
;             const char* a2 = last ? nA : cA + (size_t)(t + 2) * kstep; const char* b2 = last ? nB : cB + (size_t)(t + 2) * kstep;
;             const char* a3 = a2 + kstep; const char* b3 = b2 + kstep;
;             if (last && has_next) S.a_ready(nxt);
;             if constexpr (SP2) {
;             PG8_LDB(B0, 0, 0); PG8_LDB(B1, 0, 1); PG8_SCHED; PG8_LDA(At, 0, 0); PG8_STAGE(PG8_SA(1, 1), a1 + hstepA, voffA);
;             PG8_WAIT_V(8); PG8_WAIT_L(0); PG8_BAR; PG8_MMA(0, 0, At, B0); PG8_MMA(0, 1, At, B1); PG8_BAR; PG8_SCHED;
.LBB0_584:
	s_ashr_i32 s41, s40, 31
	s_lshl_b64 s[22:23], s[40:41], 19
	v_readlane_b32 s24, v239, 47
	v_readlane_b32 s25, v239, 48
	s_add_u32 s42, s24, s22
	s_addc_u32 s43, s25, s23
	s_and_b64 s[22:23], s[6:7], exec
	s_cselect_b32 s24, s43, s1
	s_cselect_b32 s25, s42, s0
	s_ashr_i32 s19, s18, 31
	s_lshl_b64 s[22:23], s[18:19], 19
	v_readlane_b32 s26, v239, 34
	v_readlane_b32 s27, v239, 35
	s_add_u32 s46, s26, s22
	s_addc_u32 s47, s27, s23
	s_and_b64 s[22:23], s[6:7], exec
	s_cselect_b32 s19, s47, s21
	s_cselect_b32 s26, s46, s20
	s_add_u32 s0, s0, 0x40080
	s_addc_u32 s1, s1, 0
	s_add_u32 s27, s20, 0x100
	s_addc_u32 s28, s21, 0
	s_mov_b32 s29, -2
	s_waitcnt lgkmcnt(0)
	ds_read_b128 v[146:149], v157
	ds_read_b128 v[162:165], v157 offset:1024
	ds_read_b128 v[166:169], v157 offset:2048
	ds_read_b128 v[170:173], v157 offset:3072
	ds_read_b128 v[174:177], v158
	ds_read_b128 v[178:181], v158 offset:1024
	ds_read_b128 v[182:185], v158 offset:2048
	ds_read_b128 v[186:189], v158 offset:3072
	s_add_u32 s20, s0, 0xfffc0080
	s_addc_u32 s21, s1, -1
	s_cmp_eq_u32 s29, 12
	s_cselect_b32 s23, s24, s21
	s_cselect_b32 s22, s25, s20
	s_cselect_b32 s21, s19, s28
	s_cselect_b32 s20, s26, s27
	v_lshl_add_u64 v[222:223], s[0:1], 0, v[138:139]
	s_add_i32 m0, s35, 0xc000
	ds_read_b128 v[190:193], v159
	ds_read_b128 v[194:197], v159 offset:1024
	ds_read_b128 v[198:201], v159 offset:2048
	ds_read_b128 v[202:205], v159 offset:3072
	ds_read_b128 v[206:209], v159 offset:4096
	ds_read_b128 v[210:213], v159 offset:5120
	ds_read_b128 v[214:217], v159 offset:6144
	ds_read_b128 v[218:221], v159 offset:7168
	global_load_lds_dwordx4 v[222:223], off
	v_lshl_add_u64 v[222:223], s[0:1], 0, v[140:141]
	s_add_i32 m0, s35, 0xe000
	s_nop 0
	global_load_lds_dwordx4 v[222:223], off
	s_waitcnt vmcnt(8)
	s_waitcnt lgkmcnt(0)
	s_barrier
	s_setprio 1
	s_waitcnt lgkmcnt(0)
	v_mfma_f32_16x16x32_bf16 v[124:127], v[146:149], v[190:193], 0
	v_mfma_f32_16x16x32_bf16 v[120:123], v[166:169], v[190:193], 0
	v_mfma_f32_16x16x32_bf16 v[108:111], v[146:149], v[198:201], 0
	v_mfma_f32_16x16x32_bf16 v[104:107], v[166:169], v[198:201], 0
	v_mfma_f32_16x16x32_bf16 v[92:95], v[146:149], v[206:209], 0
	v_mfma_f32_16x16x32_bf16 v[88:91], v[166:169], v[206:209], 0
	v_mfma_f32_16x16x32_bf16 v[76:79], v[146:149], v[214:217], 0
	v_mfma_f32_16x16x32_bf16 v[72:75], v[166:169], v[214:217], 0
	v_mfma_f32_16x16x32_bf16 v[124:127], v[162:165], v[194:197], v[124:127]
	v_mfma_f32_16x16x32_bf16 v[120:123], v[170:173], v[194:197], v[120:123]
	v_mfma_f32_16x16x32_bf16 v[108:111], v[162:165], v[202:205], v[108:111]
	v_mfma_f32_16x16x32_bf16 v[104:107], v[170:173], v[202:205], v[104:107]
	v_mfma_f32_16x16x32_bf16 v[92:95], v[162:165], v[210:213], v[92:95]
	v_mfma_f32_16x16x32_bf16 v[88:91], v[170:173], v[210:213], v[88:91]
	v_mfma_f32_16x16x32_bf16 v[76:79], v[162:165], v[218:221], v[76:79]
	v_mfma_f32_16x16x32_bf16 v[72:75], v[170:173], v[218:221], v[72:75]
	s_setprio 0
	s_setprio 1
	v_mfma_f32_16x16x32_bf16 v[116:119], v[174:177], v[190:193], 0
	v_mfma_f32_16x16x32_bf16 v[112:115], v[182:185], v[190:193], 0
	v_mfma_f32_16x16x32_bf16 v[100:103], v[174:177], v[198:201], 0
	v_mfma_f32_16x16x32_bf16 v[96:99], v[182:185], v[198:201], 0
	v_mfma_f32_16x16x32_bf16 v[84:87], v[174:177], v[206:209], 0
	v_mfma_f32_16x16x32_bf16 v[80:83], v[182:185], v[206:209], 0
	v_mfma_f32_16x16x32_bf16 v[68:71], v[174:177], v[214:217], 0
	v_mfma_f32_16x16x32_bf16 v[64:67], v[182:185], v[214:217], 0
	v_mfma_f32_16x16x32_bf16 v[116:119], v[178:181], v[194:197], v[116:119]
	v_mfma_f32_16x16x32_bf16 v[112:115], v[186:189], v[194:197], v[112:115]
	v_mfma_f32_16x16x32_bf16 v[100:103], v[178:181], v[202:205], v[100:103]
	v_mfma_f32_16x16x32_bf16 v[96:99], v[186:189], v[202:205], v[96:99]
	v_mfma_f32_16x16x32_bf16 v[84:87], v[178:181], v[210:213], v[84:87]
	v_mfma_f32_16x16x32_bf16 v[80:83], v[186:189], v[210:213], v[80:83]
	v_mfma_f32_16x16x32_bf16 v[68:71], v[178:181], v[218:221], v[68:71]
	v_mfma_f32_16x16x32_bf16 v[64:67], v[186:189], v[218:221], v[64:67]
	s_setprio 0
	s_barrier
; #define PG8_STAGE(bufoff, gbase, voff) do { _Pragma("unroll") for (int _i = 0; _i < 2; ++_i) \
;         __builtin_amdgcn_global_load_lds((const unsigned*)((const char*)(gbase) + (voff)[_i]), (PG8_LAS unsigned*)(lds + (bufoff) + ldsw + _i * 8192), 16, 0, PG8_LOAD_AUX); } while (0)
; #define PG8_LDA(dst, b, h) do { _Pragma("unroll") for (int m = 0; m < 4; ++m) _Pragma("unroll") for (int k = 0; k < 2; ++k) dst[m][k] = *(const PG8_LAS bf16x8*)(lds + PG8_SA(b, h) + aoff + m * 2048 + k * 1024); } while (0)
; #define PG8_MMA(ai, bj, At, Bt) do { __builtin_amdgcn_s_setprio(1); _Pragma("unroll") for (int m = 0; m < 4; ++m) _Pragma("unroll") for (int n = 0; n < 2; ++n) _Pragma("unroll") for (int k = 0; k < 2; ++k) \
;         acc[ai][bj][m][n] = __builtin_amdgcn_mfma_f32_16x16x32_bf16(Bt[n][k], At[m][k], acc[ai][bj][m][n], 0, 0, 0); __builtin_amdgcn_s_setprio(0); } while (0)
; #define PG8_WAIT_V(n) asm volatile("s_waitcnt vmcnt(" #n ")" ::: "memory")
; #define PG8_WAIT_L(n) asm volatile("s_waitcnt lgkmcnt(" #n ")" ::: "memory")
; #define PG8_BAR __builtin_amdgcn_s_barrier()
; #define PG8_SCHED __builtin_amdgcn_sched_barrier(0)
; template <class Epi, class Sched, bool ALIGN_EPI = false, bool SP2 = false>
; __device__ __forceinline__ void gemm_phase(PG8_LAS unsigned char* lds, const Gemm g, const Sched& S, const Epi& E) {
;     ...
;             PG8_LDA(At, 0, 1); PG8_STAGE(PG8_SB(0, 0), b2, voffB); PG8_STAGE(PG8_SB(0, 1), b2 + hstepB, voffB); PG8_STAGE(PG8_SA(0, 0), a2, voffA);
;             PG8_WAIT_V(8); PG8_WAIT_L(0); PG8_BAR; PG8_MMA(1, 0, At, B0); PG8_MMA(1, 1, At, B1); PG8_BAR; PG8_SCHED;
	s_add_i32 s30, s60, s34
	v_lshl_add_u64 v[222:223], s[20:21], 0, v[130:131]
	s_mov_b32 m0, s30
	ds_read_b128 v[190:193], v159 offset:16384
	ds_read_b128 v[194:197], v159 offset:17408
	ds_read_b128 v[198:201], v159 offset:18432
	ds_read_b128 v[202:205], v159 offset:19456
	ds_read_b128 v[206:209], v159 offset:20480
	ds_read_b128 v[210:213], v159 offset:21504
	ds_read_b128 v[214:217], v159 offset:22528
	ds_read_b128 v[218:221], v159 offset:23552
	global_load_lds_dwordx4 v[222:223], off
	s_add_i32 m0, s30, 0x2000
	s_add_u32 s30, s20, 0x10000
	v_lshl_add_u64 v[224:225], s[20:21], 0, v[134:135]
	s_addc_u32 s31, s21, 0
	s_add_i32 s33, s61, s34
	global_load_lds_dwordx4 v[224:225], off
	v_lshl_add_u64 v[226:227], s[30:31], 0, v[130:131]
	s_mov_b32 m0, s33
	v_lshl_add_u64 v[228:229], s[22:23], 0, v[132:133]
	global_load_lds_dwordx4 v[226:227], off
	v_lshl_add_u64 v[226:227], s[30:31], 0, v[134:135]
	s_add_i32 m0, s33, 0x2000
	s_nop 0
	global_load_lds_dwordx4 v[226:227], off
	v_lshl_add_u64 v[226:227], s[22:23], 0, v[128:129]
	s_mov_b32 m0, s35
	s_nop 0
	global_load_lds_dwordx4 v[226:227], off
	s_mov_b32 m0, s49
	s_nop 0
	global_load_lds_dwordx4 v[228:229], off
	s_waitcnt vmcnt(8)
	s_waitcnt lgkmcnt(0)
	s_barrier
	s_setprio 1
	s_waitcnt lgkmcnt(0)
	v_mfma_f32_16x16x32_bf16 v[60:63], v[146:149], v[190:193], 0
	v_mfma_f32_16x16x32_bf16 v[56:59], v[166:169], v[190:193], 0
	v_mfma_f32_16x16x32_bf16 v[44:47], v[146:149], v[198:201], 0
	v_mfma_f32_16x16x32_bf16 v[40:43], v[166:169], v[198:201], 0
	v_mfma_f32_16x16x32_bf16 v[28:31], v[146:149], v[206:209], 0
	v_mfma_f32_16x16x32_bf16 v[24:27], v[166:169], v[206:209], 0
	v_mfma_f32_16x16x32_bf16 v[12:15], v[146:149], v[214:217], 0
	v_mfma_f32_16x16x32_bf16 v[8:11], v[166:169], v[214:217], 0
	v_mfma_f32_16x16x32_bf16 v[60:63], v[162:165], v[194:197], v[60:63]
	v_mfma_f32_16x16x32_bf16 v[56:59], v[170:173], v[194:197], v[56:59]
	v_mfma_f32_16x16x32_bf16 v[44:47], v[162:165], v[202:205], v[44:47]
	v_mfma_f32_16x16x32_bf16 v[40:43], v[170:173], v[202:205], v[40:43]
	v_mfma_f32_16x16x32_bf16 v[28:31], v[162:165], v[210:213], v[28:31]
	v_mfma_f32_16x16x32_bf16 v[24:27], v[170:173], v[210:213], v[24:27]
	v_mfma_f32_16x16x32_bf16 v[12:15], v[162:165], v[218:221], v[12:15]
	v_mfma_f32_16x16x32_bf16 v[8:11], v[170:173], v[218:221], v[8:11]
	s_setprio 0
	s_setprio 1
	v_mfma_f32_16x16x32_bf16 v[52:55], v[174:177], v[190:193], 0
	v_mfma_f32_16x16x32_bf16 v[48:51], v[182:185], v[190:193], 0
	v_mfma_f32_16x16x32_bf16 v[36:39], v[174:177], v[198:201], 0
	v_mfma_f32_16x16x32_bf16 v[32:35], v[182:185], v[198:201], 0
	v_mfma_f32_16x16x32_bf16 v[20:23], v[174:177], v[206:209], 0
	v_mfma_f32_16x16x32_bf16 v[16:19], v[182:185], v[206:209], 0
	v_mfma_f32_16x16x32_bf16 v[4:7], v[174:177], v[214:217], 0
	v_mfma_f32_16x16x32_bf16 v[0:3], v[182:185], v[214:217], 0
	v_mfma_f32_16x16x32_bf16 v[52:55], v[178:181], v[194:197], v[52:55]
	v_mfma_f32_16x16x32_bf16 v[48:51], v[186:189], v[194:197], v[48:51]
	v_mfma_f32_16x16x32_bf16 v[36:39], v[178:181], v[202:205], v[36:39]
	v_mfma_f32_16x16x32_bf16 v[32:35], v[186:189], v[202:205], v[32:35]
	v_mfma_f32_16x16x32_bf16 v[20:23], v[178:181], v[210:213], v[20:23]
	v_mfma_f32_16x16x32_bf16 v[16:19], v[186:189], v[210:213], v[16:19]
	v_mfma_f32_16x16x32_bf16 v[4:7], v[178:181], v[218:221], v[4:7]
	v_mfma_f32_16x16x32_bf16 v[0:3], v[186:189], v[218:221], v[0:3]
	s_setprio 0
	s_barrier
	s_branch .Lkmid_P6

; #define PG8_STAGE(bufoff, gbase, voff) do { _Pragma("unroll") for (int _i = 0; _i < 2; ++_i) \
;         __builtin_amdgcn_global_load_lds((const unsigned*)((const char*)(gbase) + (voff)[_i]), (PG8_LAS unsigned*)(lds + (bufoff) + ldsw + _i * 8192), 16, 0, PG8_LOAD_AUX); } while (0)
; #define PG8_LDA(dst, b, h) do { _Pragma("unroll") for (int m = 0; m < 4; ++m) _Pragma("unroll") for (int k = 0; k < 2; ++k) dst[m][k] = *(const PG8_LAS bf16x8*)(lds + PG8_SA(b, h) + aoff + m * 2048 + k * 1024); } while (0)
; #define PG8_LDB(dst, b, h) do { _Pragma("unroll") for (int n = 0; n < 2; ++n) _Pragma("unroll") for (int k = 0; k < 2; ++k) dst[n][k] = *(const PG8_LAS bf16x8*)(lds + PG8_SB(b, h) + boff + n * 2048 + k * 1024); } while (0)
; #define PG8_MMA(ai, bj, At, Bt) do { __builtin_amdgcn_s_setprio(1); _Pragma("unroll") for (int m = 0; m < 4; ++m) _Pragma("unroll") for (int n = 0; n < 2; ++n) _Pragma("unroll") for (int k = 0; k < 2; ++k) \
;         acc[ai][bj][m][n] = __builtin_amdgcn_mfma_f32_16x16x32_bf16(Bt[n][k], At[m][k], acc[ai][bj][m][n], 0, 0, 0); __builtin_amdgcn_s_setprio(0); } while (0)
; #define PG8_WAIT_V(n) asm volatile("s_waitcnt vmcnt(" #n ")" ::: "memory")
; #define PG8_WAIT_L(n) asm volatile("s_waitcnt lgkmcnt(" #n ")" ::: "memory")
; #define PG8_BAR __builtin_amdgcn_s_barrier()
; #define PG8_SCHED __builtin_amdgcn_sched_barrier(0)
; template <class Epi, class Sched, bool ALIGN_EPI = false, bool SP2 = false>
; __device__ __forceinline__ void gemm_phase(PG8_LAS unsigned char* lds, const Gemm g, const Sched& S, const Epi& E) {
;     ...
;             PG8_LDB(B0, 1, 0); PG8_LDB(B1, 1, 1); PG8_SCHED; PG8_LDA(At, 1, 0); PG8_STAGE(PG8_SA(0, 1), a2 + hstepA, voffA);
;             PG8_WAIT_V(8); PG8_WAIT_L(0); PG8_BAR; PG8_MMA(0, 0, At, B0); PG8_MMA(0, 1, At, B1); PG8_BAR; PG8_SCHED;
.Lkmid_P6:
	s_add_i32 s30, 0, 0x18000
	v_add_u32_e32 v161, s30, v152
	s_add_i32 s31, 0, 0x1c000
	ds_read_b128 v[146:149], v161
	ds_read_b128 v[162:165], v161 offset:1024
	ds_read_b128 v[166:169], v161 offset:2048
	ds_read_b128 v[170:173], v161 offset:3072
	v_add_u32_e32 v161, s31, v152
	ds_read_b128 v[174:177], v161
	ds_read_b128 v[178:181], v161 offset:1024
	ds_read_b128 v[182:185], v161 offset:2048
	ds_read_b128 v[186:189], v161 offset:3072
	s_add_u32 s22, s22, 0x40000
	s_addc_u32 s23, s23, 0
	s_mov_b32 m0, s50
	v_lshl_add_u64 v[230:231], s[22:23], 0, v[128:129]
	ds_read_b128 v[190:193], v159 offset:32768
	ds_read_b128 v[194:197], v159 offset:33792
	ds_read_b128 v[198:201], v159 offset:34816
	ds_read_b128 v[202:205], v159 offset:35840
	ds_read_b128 v[206:209], v159 offset:36864
	ds_read_b128 v[210:213], v159 offset:37888
	ds_read_b128 v[214:217], v159 offset:38912
	ds_read_b128 v[218:221], v159 offset:39936
	global_load_lds_dwordx4 v[230:231], off
	v_lshl_add_u64 v[230:231], s[22:23], 0, v[132:133]
	s_mov_b32 m0, s51
	s_nop 0
	global_load_lds_dwordx4 v[230:231], off
	s_waitcnt vmcnt(8)
	s_waitcnt lgkmcnt(0)
	s_barrier
	s_setprio 1
	s_waitcnt lgkmcnt(0)
	v_mfma_f32_16x16x32_bf16 v[124:127], v[146:149], v[190:193], v[124:127]
	v_mfma_f32_16x16x32_bf16 v[120:123], v[166:169], v[190:193], v[120:123]
	v_mfma_f32_16x16x32_bf16 v[108:111], v[146:149], v[198:201], v[108:111]
	v_mfma_f32_16x16x32_bf16 v[104:107], v[166:169], v[198:201], v[104:107]
	v_mfma_f32_16x16x32_bf16 v[92:95], v[146:149], v[206:209], v[92:95]
	v_mfma_f32_16x16x32_bf16 v[88:91], v[166:169], v[206:209], v[88:91]
	v_mfma_f32_16x16x32_bf16 v[76:79], v[146:149], v[214:217], v[76:79]
	v_mfma_f32_16x16x32_bf16 v[72:75], v[166:169], v[214:217], v[72:75]
	v_mfma_f32_16x16x32_bf16 v[124:127], v[162:165], v[194:197], v[124:127]
	v_mfma_f32_16x16x32_bf16 v[120:123], v[170:173], v[194:197], v[120:123]
	v_mfma_f32_16x16x32_bf16 v[108:111], v[162:165], v[202:205], v[108:111]
	v_mfma_f32_16x16x32_bf16 v[104:107], v[170:173], v[202:205], v[104:107]
	v_mfma_f32_16x16x32_bf16 v[92:95], v[162:165], v[210:213], v[92:95]
	v_mfma_f32_16x16x32_bf16 v[88:91], v[170:173], v[210:213], v[88:91]
	v_mfma_f32_16x16x32_bf16 v[76:79], v[162:165], v[218:221], v[76:79]
	v_mfma_f32_16x16x32_bf16 v[72:75], v[170:173], v[218:221], v[72:75]
	s_setprio 0
	s_setprio 1
	v_mfma_f32_16x16x32_bf16 v[116:119], v[174:177], v[190:193], v[116:119]
	v_mfma_f32_16x16x32_bf16 v[112:115], v[182:185], v[190:193], v[112:115]
	v_mfma_f32_16x16x32_bf16 v[100:103], v[174:177], v[198:201], v[100:103]
	v_mfma_f32_16x16x32_bf16 v[96:99], v[182:185], v[198:201], v[96:99]
	v_mfma_f32_16x16x32_bf16 v[84:87], v[174:177], v[206:209], v[84:87]
	v_mfma_f32_16x16x32_bf16 v[80:83], v[182:185], v[206:209], v[80:83]
	v_mfma_f32_16x16x32_bf16 v[68:71], v[174:177], v[214:217], v[68:71]
	v_mfma_f32_16x16x32_bf16 v[64:67], v[182:185], v[214:217], v[64:67]
	v_mfma_f32_16x16x32_bf16 v[116:119], v[178:181], v[194:197], v[116:119]
	v_mfma_f32_16x16x32_bf16 v[112:115], v[186:189], v[194:197], v[112:115]
	v_mfma_f32_16x16x32_bf16 v[100:103], v[178:181], v[202:205], v[100:103]
	v_mfma_f32_16x16x32_bf16 v[96:99], v[186:189], v[202:205], v[96:99]
	v_mfma_f32_16x16x32_bf16 v[84:87], v[178:181], v[210:213], v[84:87]
	v_mfma_f32_16x16x32_bf16 v[80:83], v[186:189], v[210:213], v[80:83]
	v_mfma_f32_16x16x32_bf16 v[68:71], v[178:181], v[218:221], v[68:71]
	v_mfma_f32_16x16x32_bf16 v[64:67], v[186:189], v[218:221], v[64:67]
	s_setprio 0
	s_barrier
; #define PG8_STAGE(bufoff, gbase, voff) do { _Pragma("unroll") for (int _i = 0; _i < 2; ++_i) \
;         __builtin_amdgcn_global_load_lds((const unsigned*)((const char*)(gbase) + (voff)[_i]), (PG8_LAS unsigned*)(lds + (bufoff) + ldsw + _i * 8192), 16, 0, PG8_LOAD_AUX); } while (0)
; #define PG8_LDA(dst, b, h) do { _Pragma("unroll") for (int m = 0; m < 4; ++m) _Pragma("unroll") for (int k = 0; k < 2; ++k) dst[m][k] = *(const PG8_LAS bf16x8*)(lds + PG8_SA(b, h) + aoff + m * 2048 + k * 1024); } while (0)
; #define PG8_MMA(ai, bj, At, Bt) do { __builtin_amdgcn_s_setprio(1); _Pragma("unroll") for (int m = 0; m < 4; ++m) _Pragma("unroll") for (int n = 0; n < 2; ++n) _Pragma("unroll") for (int k = 0; k < 2; ++k) \
;         acc[ai][bj][m][n] = __builtin_amdgcn_mfma_f32_16x16x32_bf16(Bt[n][k], At[m][k], acc[ai][bj][m][n], 0, 0, 0); __builtin_amdgcn_s_setprio(0); } while (0)
; #define PG8_WAIT_V(n) asm volatile("s_waitcnt vmcnt(" #n ")" ::: "memory")
; #define PG8_WAIT_L(n) asm volatile("s_waitcnt lgkmcnt(" #n ")" ::: "memory")
; #define PG8_BAR __builtin_amdgcn_s_barrier()
; #define PG8_SCHED __builtin_amdgcn_sched_barrier(0)
; template <class Epi, class Sched, bool ALIGN_EPI = false, bool SP2 = false>
; __device__ __forceinline__ void gemm_phase(PG8_LAS unsigned char* lds, const Gemm g, const Sched& S, const Epi& E) {
;     ...
;             PG8_LDA(At, 1, 1); PG8_STAGE(PG8_SB(1, 0), b3, voffB); PG8_STAGE(PG8_SB(1, 1), b3 + hstepB, voffB); PG8_STAGE(PG8_SA(1, 0), a3, voffA);
;             PG8_WAIT_V(8); PG8_WAIT_L(0); PG8_BAR; PG8_MMA(1, 0, At, B0); PG8_MMA(1, 1, At, B1); PG8_BAR; PG8_SCHED;
;     ...
;         }
;         if constexpr (ALIGN_EPI) { if (wr == 0) PG8_BAR; }
	s_add_i32 s22, s30, s34
	v_lshl_add_u64 v[222:223], v[222:223], 0, s[14:15]
	s_mov_b32 m0, s22
	ds_read_b128 v[190:193], v159 offset:49152
	ds_read_b128 v[194:197], v159 offset:50176
	ds_read_b128 v[198:201], v159 offset:51200
	ds_read_b128 v[202:205], v159 offset:52224
	ds_read_b128 v[206:209], v159 offset:53248
	ds_read_b128 v[210:213], v159 offset:54272
	ds_read_b128 v[214:217], v159 offset:55296
	ds_read_b128 v[218:221], v159 offset:56320
	global_load_lds_dwordx4 v[222:223], off
	s_add_i32 m0, s22, 0x2000
	s_add_u32 s20, s20, 0x10080
	v_lshl_add_u64 v[222:223], v[224:225], 0, s[14:15]
	s_addc_u32 s21, s21, 0
	s_add_i32 s22, s31, s34
	global_load_lds_dwordx4 v[222:223], off
	v_lshl_add_u64 v[222:223], s[20:21], 0, v[130:131]
	s_mov_b32 m0, s22
	s_nop 0
	global_load_lds_dwordx4 v[222:223], off
	v_lshl_add_u64 v[222:223], s[20:21], 0, v[134:135]
	s_add_i32 m0, s22, 0x2000
	s_nop 0
	global_load_lds_dwordx4 v[222:223], off
	v_lshl_add_u64 v[222:223], v[226:227], 0, s[14:15]
	s_mov_b32 m0, s57
	s_nop 0
	global_load_lds_dwordx4 v[222:223], off
	v_lshl_add_u64 v[222:223], v[228:229], 0, s[14:15]
	s_mov_b32 m0, s58
	s_nop 0
	global_load_lds_dwordx4 v[222:223], off
	s_waitcnt vmcnt(8)
	s_waitcnt lgkmcnt(0)
	s_barrier
	s_setprio 1
	s_waitcnt lgkmcnt(0)
	v_mfma_f32_16x16x32_bf16 v[60:63], v[146:149], v[190:193], v[60:63]
	v_mfma_f32_16x16x32_bf16 v[56:59], v[166:169], v[190:193], v[56:59]
	v_mfma_f32_16x16x32_bf16 v[44:47], v[146:149], v[198:201], v[44:47]
	v_mfma_f32_16x16x32_bf16 v[40:43], v[166:169], v[198:201], v[40:43]
	v_mfma_f32_16x16x32_bf16 v[28:31], v[146:149], v[206:209], v[28:31]
	v_mfma_f32_16x16x32_bf16 v[24:27], v[166:169], v[206:209], v[24:27]
	v_mfma_f32_16x16x32_bf16 v[12:15], v[146:149], v[214:217], v[12:15]
	v_mfma_f32_16x16x32_bf16 v[8:11], v[166:169], v[214:217], v[8:11]
	v_mfma_f32_16x16x32_bf16 v[60:63], v[162:165], v[194:197], v[60:63]
	v_mfma_f32_16x16x32_bf16 v[56:59], v[170:173], v[194:197], v[56:59]
	v_mfma_f32_16x16x32_bf16 v[44:47], v[162:165], v[202:205], v[44:47]
	v_mfma_f32_16x16x32_bf16 v[40:43], v[170:173], v[202:205], v[40:43]
	v_mfma_f32_16x16x32_bf16 v[28:31], v[162:165], v[210:213], v[28:31]
	v_mfma_f32_16x16x32_bf16 v[24:27], v[170:173], v[210:213], v[24:27]
	v_mfma_f32_16x16x32_bf16 v[12:15], v[162:165], v[218:221], v[12:15]
	v_mfma_f32_16x16x32_bf16 v[8:11], v[170:173], v[218:221], v[8:11]
	s_setprio 0
	s_setprio 1
	v_mfma_f32_16x16x32_bf16 v[52:55], v[174:177], v[190:193], v[52:55]
	v_mfma_f32_16x16x32_bf16 v[48:51], v[182:185], v[190:193], v[48:51]
	v_mfma_f32_16x16x32_bf16 v[36:39], v[174:177], v[198:201], v[36:39]
	v_mfma_f32_16x16x32_bf16 v[32:35], v[182:185], v[198:201], v[32:35]
	v_mfma_f32_16x16x32_bf16 v[20:23], v[174:177], v[206:209], v[20:23]
	v_mfma_f32_16x16x32_bf16 v[16:19], v[182:185], v[206:209], v[16:19]
	v_mfma_f32_16x16x32_bf16 v[4:7], v[174:177], v[214:217], v[4:7]
	v_mfma_f32_16x16x32_bf16 v[0:3], v[182:185], v[214:217], v[0:3]
	v_mfma_f32_16x16x32_bf16 v[52:55], v[178:181], v[194:197], v[52:55]
	v_mfma_f32_16x16x32_bf16 v[48:51], v[186:189], v[194:197], v[48:51]
	v_mfma_f32_16x16x32_bf16 v[36:39], v[178:181], v[202:205], v[36:39]
	v_mfma_f32_16x16x32_bf16 v[32:35], v[186:189], v[202:205], v[32:35]
	v_mfma_f32_16x16x32_bf16 v[20:23], v[178:181], v[210:213], v[20:23]
	v_mfma_f32_16x16x32_bf16 v[16:19], v[186:189], v[210:213], v[16:19]
	v_mfma_f32_16x16x32_bf16 v[4:7], v[178:181], v[218:221], v[4:7]
	v_mfma_f32_16x16x32_bf16 v[0:3], v[186:189], v[218:221], v[0:3]
	s_setprio 0
	s_barrier
	s_add_i32 s29, s29, 2
	s_add_u32 s0, s0, 0x100
	s_addc_u32 s1, s1, 0
	s_add_u32 s27, s27, 0x100
	s_addc_u32 s28, s28, 0
	s_cmp_gt_u32 s29, 13
	s_cbranch_scc0 .LBB0_585
	s_and_b64 vcc, exec, s[16:17]
	s_cbranch_vccz .LBB0_588
	s_barrier

; #define PG8_STAGE(bufoff, gbase, voff) do { _Pragma("unroll") for (int _i = 0; _i < 2; ++_i) \
;         __builtin_amdgcn_global_load_lds((const unsigned*)((const char*)(gbase) + (voff)[_i]), (PG8_LAS unsigned*)(lds + (bufoff) + ldsw + _i * 8192), 16, 0, PG8_LOAD_AUX); } while (0)
; #define PG8_LDA(dst, b, h) do { _Pragma("unroll") for (int m = 0; m < 4; ++m) _Pragma("unroll") for (int k = 0; k < 2; ++k) dst[m][k] = *(const PG8_LAS bf16x8*)(lds + PG8_SA(b, h) + aoff + m * 2048 + k * 1024); } while (0)
; #define PG8_LDB(dst, b, h) do { _Pragma("unroll") for (int n = 0; n < 2; ++n) _Pragma("unroll") for (int k = 0; k < 2; ++k) dst[n][k] = *(const PG8_LAS bf16x8*)(lds + PG8_SB(b, h) + boff + n * 2048 + k * 1024); } while (0)
; #define PG8_MMA(ai, bj, At, Bt) do { __builtin_amdgcn_s_setprio(1); _Pragma("unroll") for (int m = 0; m < 4; ++m) _Pragma("unroll") for (int n = 0; n < 2; ++n) _Pragma("unroll") for (int k = 0; k < 2; ++k) \
;         acc[ai][bj][m][n] = __builtin_amdgcn_mfma_f32_16x16x32_bf16(Bt[n][k], At[m][k], acc[ai][bj][m][n], 0, 0, 0); __builtin_amdgcn_s_setprio(0); } while (0)
; #define PG8_WAIT_V(n) asm volatile("s_waitcnt vmcnt(" #n ")" ::: "memory")
; #define PG8_WAIT_L(n) asm volatile("s_waitcnt lgkmcnt(" #n ")" ::: "memory")
; #define PG8_BAR __builtin_amdgcn_s_barrier()
; #define PG8_SCHED __builtin_amdgcn_sched_barrier(0)
; template <class Epi, class Sched, bool ALIGN_EPI = false, bool SP2 = false>
; __device__ __forceinline__ void gemm_phase(PG8_LAS unsigned char* lds, const Gemm g, const Sched& S, const Epi& E) {
;     ...
;             const bool last = (t == nt - 2);
;             const char* a1 = cA + (size_t)(t + 1) * kstep;
;             const char* a2 = last ? nA : cA + (size_t)(t + 2) * kstep; const char* b2 = last ? nB : cB + (size_t)(t + 2) * kstep;
;             const char* a3 = a2 + kstep; const char* b3 = b2 + kstep;
;             if (last && has_next) S.a_ready(nxt);
;             if constexpr (SP2) {
;             PG8_LDB(B0, 0, 0); PG8_LDB(B1, 0, 1); PG8_SCHED; PG8_LDA(At, 0, 0); PG8_STAGE(PG8_SA(1, 1), a1 + hstepA, voffA);
;             PG8_WAIT_V(8); PG8_WAIT_L(0); PG8_BAR; PG8_MMA(0, 0, At, B0); PG8_MMA(0, 1, At, B1); PG8_BAR; PG8_SCHED;
.LBB0_671:
	s_ashr_i32 s17, s16, 31
	s_lshl_b64 s[18:19], s[16:17], 19
	s_add_u32 s18, s30, s18
	s_addc_u32 s19, s31, s19
	s_and_b64 s[24:25], s[2:3], exec
	s_cselect_b32 s17, s19, s21
	s_cselect_b32 s24, s18, s20
	s_ashr_i32 s15, s14, 31
	s_lshl_b64 s[26:27], s[14:15], 19
	v_readlane_b32 s15, v239, 40
	s_add_u32 s36, s15, s26
	v_readlane_b32 s15, v239, 41
	s_addc_u32 s37, s15, s27
	s_and_b64 s[26:27], s[2:3], exec
	s_cselect_b32 s15, s37, s23
	s_cselect_b32 s25, s36, s22
	s_add_u32 s20, s20, 0x40080
	s_addc_u32 s21, s21, 0
	s_add_u32 s26, s22, 0x100
	s_addc_u32 s27, s23, 0
	s_mov_b32 s28, -2
	ds_read_b128 v[146:149], v158
	ds_read_b128 v[164:167], v158 offset:1024
	ds_read_b128 v[168:171], v158 offset:2048
	ds_read_b128 v[172:175], v158 offset:3072
	ds_read_b128 v[176:179], v159
	ds_read_b128 v[180:183], v159 offset:1024
	ds_read_b128 v[184:187], v159 offset:2048
	ds_read_b128 v[188:191], v159 offset:3072
	s_add_u32 s22, s20, 0xfffc0080
	s_addc_u32 s23, s21, -1
	s_cmp_eq_u32 s28, 12
	s_cselect_b32 s35, s17, s23
	s_cselect_b32 s34, s24, s22
	s_cselect_b32 s23, s15, s27
	s_cselect_b32 s22, s25, s26
	v_lshl_add_u64 v[150:151], s[20:21], 0, v[138:139]
	s_add_i32 m0, s43, 0xc000
	ds_read_b128 v[192:195], v160
	ds_read_b128 v[196:199], v160 offset:1024
	ds_read_b128 v[200:203], v160 offset:2048
	ds_read_b128 v[204:207], v160 offset:3072
	ds_read_b128 v[208:211], v160 offset:4096
	ds_read_b128 v[212:215], v160 offset:5120
	ds_read_b128 v[216:219], v160 offset:6144
	ds_read_b128 v[220:223], v160 offset:7168
	global_load_lds_dwordx4 v[150:151], off
	v_lshl_add_u64 v[150:151], s[20:21], 0, v[140:141]
	s_add_i32 m0, s43, 0xe000
	s_nop 0
	global_load_lds_dwordx4 v[150:151], off
	s_waitcnt vmcnt(8)
	s_waitcnt lgkmcnt(0)
	s_barrier
	s_setprio 1
	s_waitcnt lgkmcnt(0)
	v_mfma_f32_16x16x32_bf16 v[124:127], v[146:149], v[192:195], 0
	v_mfma_f32_16x16x32_bf16 v[120:123], v[168:171], v[192:195], 0
	v_mfma_f32_16x16x32_bf16 v[108:111], v[146:149], v[200:203], 0
	v_mfma_f32_16x16x32_bf16 v[104:107], v[168:171], v[200:203], 0
	v_mfma_f32_16x16x32_bf16 v[92:95], v[146:149], v[208:211], 0
	v_mfma_f32_16x16x32_bf16 v[88:91], v[168:171], v[208:211], 0
	v_mfma_f32_16x16x32_bf16 v[76:79], v[146:149], v[216:219], 0
	v_mfma_f32_16x16x32_bf16 v[72:75], v[168:171], v[216:219], 0
	v_mfma_f32_16x16x32_bf16 v[124:127], v[164:167], v[196:199], v[124:127]
	v_mfma_f32_16x16x32_bf16 v[120:123], v[172:175], v[196:199], v[120:123]
	v_mfma_f32_16x16x32_bf16 v[108:111], v[164:167], v[204:207], v[108:111]
	v_mfma_f32_16x16x32_bf16 v[104:107], v[172:175], v[204:207], v[104:107]
	v_mfma_f32_16x16x32_bf16 v[92:95], v[164:167], v[212:215], v[92:95]
	v_mfma_f32_16x16x32_bf16 v[88:91], v[172:175], v[212:215], v[88:91]
	v_mfma_f32_16x16x32_bf16 v[76:79], v[164:167], v[220:223], v[76:79]
	v_mfma_f32_16x16x32_bf16 v[72:75], v[172:175], v[220:223], v[72:75]
	s_setprio 0
	s_setprio 1
	v_mfma_f32_16x16x32_bf16 v[116:119], v[176:179], v[192:195], 0
	v_mfma_f32_16x16x32_bf16 v[112:115], v[184:187], v[192:195], 0
	v_mfma_f32_16x16x32_bf16 v[100:103], v[176:179], v[200:203], 0
	v_mfma_f32_16x16x32_bf16 v[96:99], v[184:187], v[200:203], 0
	v_mfma_f32_16x16x32_bf16 v[84:87], v[176:179], v[208:211], 0
	v_mfma_f32_16x16x32_bf16 v[80:83], v[184:187], v[208:211], 0
	v_mfma_f32_16x16x32_bf16 v[68:71], v[176:179], v[216:219], 0
	v_mfma_f32_16x16x32_bf16 v[64:67], v[184:187], v[216:219], 0
	v_mfma_f32_16x16x32_bf16 v[116:119], v[180:183], v[196:199], v[116:119]
	v_mfma_f32_16x16x32_bf16 v[112:115], v[188:191], v[196:199], v[112:115]
	v_mfma_f32_16x16x32_bf16 v[100:103], v[180:183], v[204:207], v[100:103]
	v_mfma_f32_16x16x32_bf16 v[96:99], v[188:191], v[204:207], v[96:99]
	v_mfma_f32_16x16x32_bf16 v[84:87], v[180:183], v[212:215], v[84:87]
	v_mfma_f32_16x16x32_bf16 v[80:83], v[188:191], v[212:215], v[80:83]
	v_mfma_f32_16x16x32_bf16 v[68:71], v[180:183], v[220:223], v[68:71]
	v_mfma_f32_16x16x32_bf16 v[64:67], v[188:191], v[220:223], v[64:67]
	s_setprio 0
	s_barrier
; #define PG8_STAGE(bufoff, gbase, voff) do { _Pragma("unroll") for (int _i = 0; _i < 2; ++_i) \
;         __builtin_amdgcn_global_load_lds((const unsigned*)((const char*)(gbase) + (voff)[_i]), (PG8_LAS unsigned*)(lds + (bufoff) + ldsw + _i * 8192), 16, 0, PG8_LOAD_AUX); } while (0)
; #define PG8_LDA(dst, b, h) do { _Pragma("unroll") for (int m = 0; m < 4; ++m) _Pragma("unroll") for (int k = 0; k < 2; ++k) dst[m][k] = *(const PG8_LAS bf16x8*)(lds + PG8_SA(b, h) + aoff + m * 2048 + k * 1024); } while (0)
; #define PG8_MMA(ai, bj, At, Bt) do { __builtin_amdgcn_s_setprio(1); _Pragma("unroll") for (int m = 0; m < 4; ++m) _Pragma("unroll") for (int n = 0; n < 2; ++n) _Pragma("unroll") for (int k = 0; k < 2; ++k) \
;         acc[ai][bj][m][n] = __builtin_amdgcn_mfma_f32_16x16x32_bf16(Bt[n][k], At[m][k], acc[ai][bj][m][n], 0, 0, 0); __builtin_amdgcn_s_setprio(0); } while (0)
; #define PG8_WAIT_V(n) asm volatile("s_waitcnt vmcnt(" #n ")" ::: "memory")
; #define PG8_WAIT_L(n) asm volatile("s_waitcnt lgkmcnt(" #n ")" ::: "memory")
; #define PG8_BAR __builtin_amdgcn_s_barrier()
; #define PG8_SCHED __builtin_amdgcn_sched_barrier(0)
; template <class Epi, class Sched, bool ALIGN_EPI = false, bool SP2 = false>
; __device__ __forceinline__ void gemm_phase(PG8_LAS unsigned char* lds, const Gemm g, const Sched& S, const Epi& E) {
;     ...
;             PG8_LDA(At, 0, 1); PG8_STAGE(PG8_SB(0, 0), b2, voffB); PG8_STAGE(PG8_SB(0, 1), b2 + hstepB, voffB); PG8_STAGE(PG8_SA(0, 0), a2, voffA);
;             PG8_WAIT_V(8); PG8_WAIT_L(0); PG8_BAR; PG8_MMA(1, 0, At, B0); PG8_MMA(1, 1, At, B1); PG8_BAR; PG8_SCHED;
	s_add_i32 s29, s54, s40
	v_lshl_add_u64 v[150:151], s[22:23], 0, v[130:131]
	s_mov_b32 m0, s29
	ds_read_b128 v[192:195], v160 offset:16384
	ds_read_b128 v[196:199], v160 offset:17408
	ds_read_b128 v[200:203], v160 offset:18432
	ds_read_b128 v[204:207], v160 offset:19456
	ds_read_b128 v[208:211], v160 offset:20480
	ds_read_b128 v[212:215], v160 offset:21504
	ds_read_b128 v[216:219], v160 offset:22528
	ds_read_b128 v[220:223], v160 offset:23552
	global_load_lds_dwordx4 v[150:151], off
	s_add_i32 m0, s29, 0x2000
	s_add_u32 s30, s22, 0x40000
	v_lshl_add_u64 v[224:225], s[22:23], 0, v[134:135]
	s_addc_u32 s31, s23, 0
	s_add_i32 s29, s55, s40
	global_load_lds_dwordx4 v[224:225], off
	v_lshl_add_u64 v[226:227], s[30:31], 0, v[130:131]
	s_mov_b32 m0, s29
	v_lshl_add_u64 v[228:229], s[34:35], 0, v[132:133]
	global_load_lds_dwordx4 v[226:227], off
	v_lshl_add_u64 v[226:227], s[30:31], 0, v[134:135]
	s_add_i32 m0, s29, 0x2000
	s_nop 0
	global_load_lds_dwordx4 v[226:227], off
	v_lshl_add_u64 v[226:227], s[34:35], 0, v[128:129]
	s_mov_b32 m0, s43
	s_nop 0
	global_load_lds_dwordx4 v[226:227], off
	s_mov_b32 m0, s46
	s_nop 0
	global_load_lds_dwordx4 v[228:229], off
	s_waitcnt vmcnt(8)
	s_waitcnt lgkmcnt(0)
	s_barrier
	s_setprio 1
	s_waitcnt lgkmcnt(0)
	v_mfma_f32_16x16x32_bf16 v[60:63], v[146:149], v[192:195], 0
	v_mfma_f32_16x16x32_bf16 v[56:59], v[168:171], v[192:195], 0
	v_mfma_f32_16x16x32_bf16 v[44:47], v[146:149], v[200:203], 0
	v_mfma_f32_16x16x32_bf16 v[40:43], v[168:171], v[200:203], 0
	v_mfma_f32_16x16x32_bf16 v[28:31], v[146:149], v[208:211], 0
	v_mfma_f32_16x16x32_bf16 v[24:27], v[168:171], v[208:211], 0
	v_mfma_f32_16x16x32_bf16 v[12:15], v[146:149], v[216:219], 0
	v_mfma_f32_16x16x32_bf16 v[8:11], v[168:171], v[216:219], 0
	v_mfma_f32_16x16x32_bf16 v[60:63], v[164:167], v[196:199], v[60:63]
	v_mfma_f32_16x16x32_bf16 v[56:59], v[172:175], v[196:199], v[56:59]
	v_mfma_f32_16x16x32_bf16 v[44:47], v[164:167], v[204:207], v[44:47]
	v_mfma_f32_16x16x32_bf16 v[40:43], v[172:175], v[204:207], v[40:43]
	v_mfma_f32_16x16x32_bf16 v[28:31], v[164:167], v[212:215], v[28:31]
	v_mfma_f32_16x16x32_bf16 v[24:27], v[172:175], v[212:215], v[24:27]
	v_mfma_f32_16x16x32_bf16 v[12:15], v[164:167], v[220:223], v[12:15]
	v_mfma_f32_16x16x32_bf16 v[8:11], v[172:175], v[220:223], v[8:11]
	s_setprio 0
	s_setprio 1
	v_mfma_f32_16x16x32_bf16 v[52:55], v[176:179], v[192:195], 0
	v_mfma_f32_16x16x32_bf16 v[48:51], v[184:187], v[192:195], 0
	v_mfma_f32_16x16x32_bf16 v[36:39], v[176:179], v[200:203], 0
	v_mfma_f32_16x16x32_bf16 v[32:35], v[184:187], v[200:203], 0
	v_mfma_f32_16x16x32_bf16 v[20:23], v[176:179], v[208:211], 0
	v_mfma_f32_16x16x32_bf16 v[16:19], v[184:187], v[208:211], 0
	v_mfma_f32_16x16x32_bf16 v[4:7], v[176:179], v[216:219], 0
	v_mfma_f32_16x16x32_bf16 v[0:3], v[184:187], v[216:219], 0
	v_mfma_f32_16x16x32_bf16 v[52:55], v[180:183], v[196:199], v[52:55]
	v_mfma_f32_16x16x32_bf16 v[48:51], v[188:191], v[196:199], v[48:51]
	v_mfma_f32_16x16x32_bf16 v[36:39], v[180:183], v[204:207], v[36:39]
	v_mfma_f32_16x16x32_bf16 v[32:35], v[188:191], v[204:207], v[32:35]
	v_mfma_f32_16x16x32_bf16 v[20:23], v[180:183], v[212:215], v[20:23]
	v_mfma_f32_16x16x32_bf16 v[16:19], v[188:191], v[212:215], v[16:19]
	v_mfma_f32_16x16x32_bf16 v[4:7], v[180:183], v[220:223], v[4:7]
	v_mfma_f32_16x16x32_bf16 v[0:3], v[188:191], v[220:223], v[0:3]
	s_setprio 0
	s_barrier
	s_branch .Lkmid_P7

; #define PG8_STAGE(bufoff, gbase, voff) do { _Pragma("unroll") for (int _i = 0; _i < 2; ++_i) \
;         __builtin_amdgcn_global_load_lds((const unsigned*)((const char*)(gbase) + (voff)[_i]), (PG8_LAS unsigned*)(lds + (bufoff) + ldsw + _i * 8192), 16, 0, PG8_LOAD_AUX); } while (0)
; #define PG8_LDA(dst, b, h) do { _Pragma("unroll") for (int m = 0; m < 4; ++m) _Pragma("unroll") for (int k = 0; k < 2; ++k) dst[m][k] = *(const PG8_LAS bf16x8*)(lds + PG8_SA(b, h) + aoff + m * 2048 + k * 1024); } while (0)
; #define PG8_LDB(dst, b, h) do { _Pragma("unroll") for (int n = 0; n < 2; ++n) _Pragma("unroll") for (int k = 0; k < 2; ++k) dst[n][k] = *(const PG8_LAS bf16x8*)(lds + PG8_SB(b, h) + boff + n * 2048 + k * 1024); } while (0)
; #define PG8_MMA(ai, bj, At, Bt) do { __builtin_amdgcn_s_setprio(1); _Pragma("unroll") for (int m = 0; m < 4; ++m) _Pragma("unroll") for (int n = 0; n < 2; ++n) _Pragma("unroll") for (int k = 0; k < 2; ++k) \
;         acc[ai][bj][m][n] = __builtin_amdgcn_mfma_f32_16x16x32_bf16(Bt[n][k], At[m][k], acc[ai][bj][m][n], 0, 0, 0); __builtin_amdgcn_s_setprio(0); } while (0)
; #define PG8_WAIT_V(n) asm volatile("s_waitcnt vmcnt(" #n ")" ::: "memory")
; #define PG8_WAIT_L(n) asm volatile("s_waitcnt lgkmcnt(" #n ")" ::: "memory")
; #define PG8_BAR __builtin_amdgcn_s_barrier()
; #define PG8_SCHED __builtin_amdgcn_sched_barrier(0)
; template <class Epi, class Sched, bool ALIGN_EPI = false, bool SP2 = false>
; __device__ __forceinline__ void gemm_phase(PG8_LAS unsigned char* lds, const Gemm g, const Sched& S, const Epi& E) {
;     ...
;             PG8_LDB(B0, 1, 0); PG8_LDB(B1, 1, 1); PG8_SCHED; PG8_LDA(At, 1, 0); PG8_STAGE(PG8_SA(0, 1), a2 + hstepA, voffA);
;             PG8_WAIT_V(8); PG8_WAIT_L(0); PG8_BAR; PG8_MMA(0, 0, At, B0); PG8_MMA(0, 1, At, B1); PG8_BAR; PG8_SCHED;
.Lkmid_P7:
	s_add_i32 s29, 0, 0x18000
	v_add_u32_e32 v163, s29, v156
	s_add_i32 s33, 0, 0x1c000
	ds_read_b128 v[146:149], v163
	ds_read_b128 v[164:167], v163 offset:1024
	ds_read_b128 v[168:171], v163 offset:2048
	ds_read_b128 v[172:175], v163 offset:3072
	v_add_u32_e32 v163, s33, v156
	ds_read_b128 v[176:179], v163
	ds_read_b128 v[180:183], v163 offset:1024
	ds_read_b128 v[184:187], v163 offset:2048
	ds_read_b128 v[188:191], v163 offset:3072
	s_add_u32 s30, s34, 0x40000
	s_addc_u32 s31, s35, 0
	s_mov_b32 m0, s47
	v_lshl_add_u64 v[230:231], s[30:31], 0, v[128:129]
	ds_read_b128 v[192:195], v160 offset:32768
	ds_read_b128 v[196:199], v160 offset:33792
	ds_read_b128 v[200:203], v160 offset:34816
	ds_read_b128 v[204:207], v160 offset:35840
	ds_read_b128 v[208:211], v160 offset:36864
	ds_read_b128 v[212:215], v160 offset:37888
	ds_read_b128 v[216:219], v160 offset:38912
	ds_read_b128 v[220:223], v160 offset:39936
	global_load_lds_dwordx4 v[230:231], off
	v_lshl_add_u64 v[230:231], s[30:31], 0, v[132:133]
	s_mov_b32 m0, s48
	s_nop 0
	global_load_lds_dwordx4 v[230:231], off
	s_waitcnt vmcnt(8)
	s_waitcnt lgkmcnt(0)
	s_barrier
	s_setprio 1
	s_waitcnt lgkmcnt(0)
	v_mfma_f32_16x16x32_bf16 v[124:127], v[146:149], v[192:195], v[124:127]
	v_mfma_f32_16x16x32_bf16 v[120:123], v[168:171], v[192:195], v[120:123]
	v_mfma_f32_16x16x32_bf16 v[108:111], v[146:149], v[200:203], v[108:111]
	v_mfma_f32_16x16x32_bf16 v[104:107], v[168:171], v[200:203], v[104:107]
	v_mfma_f32_16x16x32_bf16 v[92:95], v[146:149], v[208:211], v[92:95]
	v_mfma_f32_16x16x32_bf16 v[88:91], v[168:171], v[208:211], v[88:91]
	v_mfma_f32_16x16x32_bf16 v[76:79], v[146:149], v[216:219], v[76:79]
	v_mfma_f32_16x16x32_bf16 v[72:75], v[168:171], v[216:219], v[72:75]
	v_mfma_f32_16x16x32_bf16 v[124:127], v[164:167], v[196:199], v[124:127]
	v_mfma_f32_16x16x32_bf16 v[120:123], v[172:175], v[196:199], v[120:123]
	v_mfma_f32_16x16x32_bf16 v[108:111], v[164:167], v[204:207], v[108:111]
	v_mfma_f32_16x16x32_bf16 v[104:107], v[172:175], v[204:207], v[104:107]
	v_mfma_f32_16x16x32_bf16 v[92:95], v[164:167], v[212:215], v[92:95]
	v_mfma_f32_16x16x32_bf16 v[88:91], v[172:175], v[212:215], v[88:91]
	v_mfma_f32_16x16x32_bf16 v[76:79], v[164:167], v[220:223], v[76:79]
	v_mfma_f32_16x16x32_bf16 v[72:75], v[172:175], v[220:223], v[72:75]
	s_setprio 0
	s_setprio 1
	v_mfma_f32_16x16x32_bf16 v[116:119], v[176:179], v[192:195], v[116:119]
	v_mfma_f32_16x16x32_bf16 v[112:115], v[184:187], v[192:195], v[112:115]
	v_mfma_f32_16x16x32_bf16 v[100:103], v[176:179], v[200:203], v[100:103]
	v_mfma_f32_16x16x32_bf16 v[96:99], v[184:187], v[200:203], v[96:99]
	v_mfma_f32_16x16x32_bf16 v[84:87], v[176:179], v[208:211], v[84:87]
	v_mfma_f32_16x16x32_bf16 v[80:83], v[184:187], v[208:211], v[80:83]
	v_mfma_f32_16x16x32_bf16 v[68:71], v[176:179], v[216:219], v[68:71]
	v_mfma_f32_16x16x32_bf16 v[64:67], v[184:187], v[216:219], v[64:67]
	v_mfma_f32_16x16x32_bf16 v[116:119], v[180:183], v[196:199], v[116:119]
	v_mfma_f32_16x16x32_bf16 v[112:115], v[188:191], v[196:199], v[112:115]
	v_mfma_f32_16x16x32_bf16 v[100:103], v[180:183], v[204:207], v[100:103]
	v_mfma_f32_16x16x32_bf16 v[96:99], v[188:191], v[204:207], v[96:99]
	v_mfma_f32_16x16x32_bf16 v[84:87], v[180:183], v[212:215], v[84:87]
	v_mfma_f32_16x16x32_bf16 v[80:83], v[188:191], v[212:215], v[80:83]
	v_mfma_f32_16x16x32_bf16 v[68:71], v[180:183], v[220:223], v[68:71]
	v_mfma_f32_16x16x32_bf16 v[64:67], v[188:191], v[220:223], v[64:67]
	s_setprio 0
	s_barrier
; #define PG8_STAGE(bufoff, gbase, voff) do { _Pragma("unroll") for (int _i = 0; _i < 2; ++_i) \
;         __builtin_amdgcn_global_load_lds((const unsigned*)((const char*)(gbase) + (voff)[_i]), (PG8_LAS unsigned*)(lds + (bufoff) + ldsw + _i * 8192), 16, 0, PG8_LOAD_AUX); } while (0)
; #define PG8_LDA(dst, b, h) do { _Pragma("unroll") for (int m = 0; m < 4; ++m) _Pragma("unroll") for (int k = 0; k < 2; ++k) dst[m][k] = *(const PG8_LAS bf16x8*)(lds + PG8_SA(b, h) + aoff + m * 2048 + k * 1024); } while (0)
; #define PG8_MMA(ai, bj, At, Bt) do { __builtin_amdgcn_s_setprio(1); _Pragma("unroll") for (int m = 0; m < 4; ++m) _Pragma("unroll") for (int n = 0; n < 2; ++n) _Pragma("unroll") for (int k = 0; k < 2; ++k) \
;         acc[ai][bj][m][n] = __builtin_amdgcn_mfma_f32_16x16x32_bf16(Bt[n][k], At[m][k], acc[ai][bj][m][n], 0, 0, 0); __builtin_amdgcn_s_setprio(0); } while (0)
; #define PG8_WAIT_V(n) asm volatile("s_waitcnt vmcnt(" #n ")" ::: "memory")
; #define PG8_WAIT_L(n) asm volatile("s_waitcnt lgkmcnt(" #n ")" ::: "memory")
; #define PG8_BAR __builtin_amdgcn_s_barrier()
; #define PG8_SCHED __builtin_amdgcn_sched_barrier(0)
; __device__ __forceinline__ float rstd_from_slots(const float* slots, int row, int fq) {
;     const f32x4 s4 = *(const f32x4*)(slots + (size_t)row * 16 + 4 * fq);
;     float s = (s4[0] + s4[1]) + (s4[2] + s4[3]);
;     s += __shfl_xor(s, 16); s += __shfl_xor(s, 32);
;     return __builtin_amdgcn_rsqf(s * (1.0f / 1024.0f) + RMS_EPS_F);
; template <class Epi, class Sched, bool ALIGN_EPI = false, bool SP2 = false>
; __device__ __forceinline__ void gemm_phase(PG8_LAS unsigned char* lds, const Gemm g, const Sched& S, const Epi& E) {
;     ...
;             PG8_LDA(At, 1, 1); PG8_STAGE(PG8_SB(1, 0), b3, voffB); PG8_STAGE(PG8_SB(1, 1), b3 + hstepB, voffB); PG8_STAGE(PG8_SA(1, 0), a3, voffA);
;             PG8_WAIT_V(8); PG8_WAIT_L(0); PG8_BAR; PG8_MMA(1, 0, At, B0); PG8_MMA(1, 1, At, B1); PG8_BAR; PG8_SCHED;
	s_add_i32 s29, s29, s40
	v_lshl_add_u64 v[150:151], v[150:151], 0, s[8:9]
	s_mov_b32 m0, s29
	ds_read_b128 v[192:195], v160 offset:49152
	ds_read_b128 v[196:199], v160 offset:50176
	ds_read_b128 v[200:203], v160 offset:51200
	ds_read_b128 v[204:207], v160 offset:52224
	ds_read_b128 v[208:211], v160 offset:53248
	ds_read_b128 v[212:215], v160 offset:54272
	ds_read_b128 v[216:219], v160 offset:55296
	ds_read_b128 v[220:223], v160 offset:56320
	global_load_lds_dwordx4 v[150:151], off
	s_add_i32 m0, s29, 0x2000
	s_add_u32 s22, s22, 0x40080
	v_lshl_add_u64 v[150:151], v[224:225], 0, s[8:9]
	s_addc_u32 s23, s23, 0
	s_add_i32 s29, s33, s40
	global_load_lds_dwordx4 v[150:151], off
	v_lshl_add_u64 v[150:151], s[22:23], 0, v[130:131]
	s_mov_b32 m0, s29
	s_nop 0
	global_load_lds_dwordx4 v[150:151], off
	v_lshl_add_u64 v[150:151], s[22:23], 0, v[134:135]
	s_add_i32 m0, s29, 0x2000
	s_nop 0
	global_load_lds_dwordx4 v[150:151], off
	v_lshl_add_u64 v[150:151], v[226:227], 0, s[8:9]
	s_mov_b32 m0, s51
	s_nop 0
	global_load_lds_dwordx4 v[150:151], off
	v_lshl_add_u64 v[150:151], v[228:229], 0, s[8:9]
	s_mov_b32 m0, s52
	s_nop 0
	global_load_lds_dwordx4 v[150:151], off
	s_waitcnt vmcnt(8)
	s_waitcnt lgkmcnt(0)
	s_barrier
	s_setprio 1
	s_waitcnt lgkmcnt(0)
	v_mfma_f32_16x16x32_bf16 v[60:63], v[146:149], v[192:195], v[60:63]
	v_mfma_f32_16x16x32_bf16 v[56:59], v[168:171], v[192:195], v[56:59]
	v_mfma_f32_16x16x32_bf16 v[44:47], v[146:149], v[200:203], v[44:47]
	v_mfma_f32_16x16x32_bf16 v[40:43], v[168:171], v[200:203], v[40:43]
	v_mfma_f32_16x16x32_bf16 v[28:31], v[146:149], v[208:211], v[28:31]
	v_mfma_f32_16x16x32_bf16 v[24:27], v[168:171], v[208:211], v[24:27]
	v_mfma_f32_16x16x32_bf16 v[12:15], v[146:149], v[216:219], v[12:15]
	v_mfma_f32_16x16x32_bf16 v[8:11], v[168:171], v[216:219], v[8:11]
	v_mfma_f32_16x16x32_bf16 v[60:63], v[164:167], v[196:199], v[60:63]
	v_mfma_f32_16x16x32_bf16 v[56:59], v[172:175], v[196:199], v[56:59]
	v_mfma_f32_16x16x32_bf16 v[44:47], v[164:167], v[204:207], v[44:47]
	v_mfma_f32_16x16x32_bf16 v[40:43], v[172:175], v[204:207], v[40:43]
	v_mfma_f32_16x16x32_bf16 v[28:31], v[164:167], v[212:215], v[28:31]
	v_mfma_f32_16x16x32_bf16 v[24:27], v[172:175], v[212:215], v[24:27]
	v_mfma_f32_16x16x32_bf16 v[12:15], v[164:167], v[220:223], v[12:15]
	v_mfma_f32_16x16x32_bf16 v[8:11], v[172:175], v[220:223], v[8:11]
	s_setprio 0
	s_setprio 1
	v_mfma_f32_16x16x32_bf16 v[52:55], v[176:179], v[192:195], v[52:55]
	v_mfma_f32_16x16x32_bf16 v[48:51], v[184:187], v[192:195], v[48:51]
	v_mfma_f32_16x16x32_bf16 v[36:39], v[176:179], v[200:203], v[36:39]
	v_mfma_f32_16x16x32_bf16 v[32:35], v[184:187], v[200:203], v[32:35]
	v_mfma_f32_16x16x32_bf16 v[20:23], v[176:179], v[208:211], v[20:23]
	v_mfma_f32_16x16x32_bf16 v[16:19], v[184:187], v[208:211], v[16:19]
	v_mfma_f32_16x16x32_bf16 v[4:7], v[176:179], v[216:219], v[4:7]
	v_mfma_f32_16x16x32_bf16 v[0:3], v[184:187], v[216:219], v[0:3]
	v_mfma_f32_16x16x32_bf16 v[52:55], v[180:183], v[196:199], v[52:55]
	v_mfma_f32_16x16x32_bf16 v[48:51], v[188:191], v[196:199], v[48:51]
	v_mfma_f32_16x16x32_bf16 v[36:39], v[180:183], v[204:207], v[36:39]
	v_mfma_f32_16x16x32_bf16 v[32:35], v[188:191], v[204:207], v[32:35]
	v_mfma_f32_16x16x32_bf16 v[20:23], v[180:183], v[212:215], v[20:23]
	v_mfma_f32_16x16x32_bf16 v[16:19], v[188:191], v[212:215], v[16:19]
	v_mfma_f32_16x16x32_bf16 v[4:7], v[180:183], v[220:223], v[4:7]
	v_mfma_f32_16x16x32_bf16 v[0:3], v[188:191], v[220:223], v[0:3]
	s_setprio 0
	s_barrier
	s_add_i32 s28, s28, 2
	s_add_u32 s20, s20, 0x100
	s_addc_u32 s21, s21, 0
	s_add_u32 s26, s26, 0x100
	s_addc_u32 s27, s27, 0
	s_cmp_gt_u32 s28, 13
	s_cbranch_scc0 .LBB0_672
	v_lshl_add_u32 v204, s0, 8, v152
	v_ashrrev_i32_e32 v205, 31, v204
	v_lshlrev_b64 v[204:205], 6, v[204:205]
	v_lshl_add_u64 v[204:205], v[136:137], 0, v[204:205]
	v_add_co_u32_e32 v206, vcc, 0x2000, v204
	s_nop 1
	v_addc_co_u32_e32 v207, vcc, 0, v205, vcc
	global_load_dwordx4 v[172:175], v[204:205], off
	global_load_dwordx4 v[176:179], v[204:205], off offset:1024
	global_load_dwordx4 v[180:183], v[204:205], off offset:2048
	global_load_dwordx4 v[184:187], v[204:205], off offset:3072
	global_load_dwordx4 v[188:191], v[206:207], off
	global_load_dwordx4 v[192:195], v[206:207], off offset:1024
	global_load_dwordx4 v[196:199], v[206:207], off offset:2048
	global_load_dwordx4 v[200:203], v[206:207], off offset:3072
	s_and_b64 vcc, exec, s[12:13]
	s_cbranch_vccz .LBB0_675
	s_barrier

; #define PG8_STAGE(bufoff, gbase, voff) do { _Pragma("unroll") for (int _i = 0; _i < 2; ++_i) \
;         __builtin_amdgcn_global_load_lds((const unsigned*)((const char*)(gbase) + (voff)[_i]), (PG8_LAS unsigned*)(lds + (bufoff) + ldsw + _i * 8192), 16, 0, PG8_LOAD_AUX); } while (0)
; #define PG8_LDA(dst, b, h) do { _Pragma("unroll") for (int m = 0; m < 4; ++m) _Pragma("unroll") for (int k = 0; k < 2; ++k) dst[m][k] = *(const PG8_LAS bf16x8*)(lds + PG8_SA(b, h) + aoff + m * 2048 + k * 1024); } while (0)
; #define PG8_LDB(dst, b, h) do { _Pragma("unroll") for (int n = 0; n < 2; ++n) _Pragma("unroll") for (int k = 0; k < 2; ++k) dst[n][k] = *(const PG8_LAS bf16x8*)(lds + PG8_SB(b, h) + boff + n * 2048 + k * 1024); } while (0)
; #define PG8_MMA(ai, bj, At, Bt) do { __builtin_amdgcn_s_setprio(1); _Pragma("unroll") for (int m = 0; m < 4; ++m) _Pragma("unroll") for (int n = 0; n < 2; ++n) _Pragma("unroll") for (int k = 0; k < 2; ++k) \
;         acc[ai][bj][m][n] = __builtin_amdgcn_mfma_f32_16x16x32_bf16(Bt[n][k], At[m][k], acc[ai][bj][m][n], 0, 0, 0); __builtin_amdgcn_s_setprio(0); } while (0)
; #define PG8_WAIT_V(n) asm volatile("s_waitcnt vmcnt(" #n ")" ::: "memory")
; #define PG8_WAIT_L(n) asm volatile("s_waitcnt lgkmcnt(" #n ")" ::: "memory")
; template <class Epi, class Sched, bool ALIGN_EPI = false, bool SP2 = false>
; __device__ __forceinline__ void gemm_phase(PG8_LAS unsigned char* lds, const Gemm g, const Sched& S, const Epi& E) {
;     ...
;             const bool last = (t == nt - 2);
;             const char* a1 = cA + (size_t)(t + 1) * kstep;
;             const char* a2 = last ? nA : cA + (size_t)(t + 2) * kstep; const char* b2 = last ? nB : cB + (size_t)(t + 2) * kstep;
;             const char* a3 = a2 + kstep; const char* b3 = b2 + kstep;
;             if (last && has_next) S.a_ready(nxt);
;             if constexpr (SP2) {
;             PG8_LDB(B0, 0, 0); PG8_LDB(B1, 0, 1); PG8_SCHED; PG8_LDA(At, 0, 0); PG8_STAGE(PG8_SA(1, 1), a1 + hstepA, voffA);
;             PG8_WAIT_V(8); PG8_WAIT_L(0); PG8_BAR; PG8_MMA(0, 0, At, B0); PG8_MMA(0, 1, At, B1); PG8_BAR; PG8_SCHED;
;             PG8_LDA(At, 0, 1); PG8_STAGE(PG8_SB(0, 0), b2, voffB); PG8_STAGE(PG8_SB(0, 1), b2 + hstepB, voffB); PG8_STAGE(PG8_SA(0, 0), a2, voffA);
;             PG8_WAIT_V(8); PG8_WAIT_L(0); PG8_BAR; PG8_MMA(1, 0, At, B0); PG8_MMA(1, 1, At, B1); PG8_BAR; PG8_SCHED;
.LBB0_756:
	s_add_u32 s0, s0, 0xb0080
	s_addc_u32 s1, s1, 0
	s_add_u32 s25, s20, 0x100
	s_addc_u32 s26, s21, 0
	s_mov_b32 s27, -2
	s_waitcnt lgkmcnt(0)
	ds_read_b128 v[146:149], v157
	ds_read_b128 v[162:165], v157 offset:1024
	ds_read_b128 v[166:169], v157 offset:2048
	ds_read_b128 v[170:173], v157 offset:3072
	ds_read_b128 v[174:177], v158
	ds_read_b128 v[178:181], v158 offset:1024
	ds_read_b128 v[182:185], v158 offset:2048
	ds_read_b128 v[186:189], v158 offset:3072
	s_add_u32 s20, s0, 0xfff50080
	s_addc_u32 s21, s1, -1
	s_cmp_eq_u32 s27, 40
	s_cselect_b32 s23, s9, s21
	s_cselect_b32 s22, s8, s20
	s_cselect_b32 s21, s41, s26
	s_cselect_b32 s20, s40, s25
	v_lshl_add_u64 v[222:223], s[0:1], 0, v[138:139]
	s_add_i32 m0, s35, 0xc000
	ds_read_b128 v[190:193], v159
	ds_read_b128 v[194:197], v159 offset:1024
	ds_read_b128 v[198:201], v159 offset:2048
	ds_read_b128 v[202:205], v159 offset:3072
	ds_read_b128 v[206:209], v159 offset:4096
	ds_read_b128 v[210:213], v159 offset:5120
	ds_read_b128 v[214:217], v159 offset:6144
	ds_read_b128 v[218:221], v159 offset:7168
	global_load_lds_dwordx4 v[222:223], off
	v_lshl_add_u64 v[222:223], s[0:1], 0, v[140:141]
	s_add_i32 m0, s35, 0xe000
	s_nop 0
	global_load_lds_dwordx4 v[222:223], off
	s_waitcnt vmcnt(8)
	s_waitcnt lgkmcnt(0)
	s_barrier
	s_setprio 1
	s_waitcnt lgkmcnt(0)
	v_mfma_f32_16x16x32_bf16 v[124:127], v[146:149], v[190:193], 0
	v_mfma_f32_16x16x32_bf16 v[120:123], v[166:169], v[190:193], 0
	v_mfma_f32_16x16x32_bf16 v[108:111], v[146:149], v[198:201], 0
	v_mfma_f32_16x16x32_bf16 v[104:107], v[166:169], v[198:201], 0
	v_mfma_f32_16x16x32_bf16 v[92:95], v[146:149], v[206:209], 0
	v_mfma_f32_16x16x32_bf16 v[88:91], v[166:169], v[206:209], 0
	v_mfma_f32_16x16x32_bf16 v[76:79], v[146:149], v[214:217], 0
	v_mfma_f32_16x16x32_bf16 v[72:75], v[166:169], v[214:217], 0
	v_mfma_f32_16x16x32_bf16 v[124:127], v[162:165], v[194:197], v[124:127]
	v_mfma_f32_16x16x32_bf16 v[120:123], v[170:173], v[194:197], v[120:123]
	v_mfma_f32_16x16x32_bf16 v[108:111], v[162:165], v[202:205], v[108:111]
	v_mfma_f32_16x16x32_bf16 v[104:107], v[170:173], v[202:205], v[104:107]
	v_mfma_f32_16x16x32_bf16 v[92:95], v[162:165], v[210:213], v[92:95]
	v_mfma_f32_16x16x32_bf16 v[88:91], v[170:173], v[210:213], v[88:91]
	v_mfma_f32_16x16x32_bf16 v[76:79], v[162:165], v[218:221], v[76:79]
	v_mfma_f32_16x16x32_bf16 v[72:75], v[170:173], v[218:221], v[72:75]
	s_setprio 0
	s_setprio 1
	v_mfma_f32_16x16x32_bf16 v[116:119], v[174:177], v[190:193], 0
	v_mfma_f32_16x16x32_bf16 v[112:115], v[182:185], v[190:193], 0
	v_mfma_f32_16x16x32_bf16 v[100:103], v[174:177], v[198:201], 0
	v_mfma_f32_16x16x32_bf16 v[96:99], v[182:185], v[198:201], 0
	v_mfma_f32_16x16x32_bf16 v[84:87], v[174:177], v[206:209], 0
	v_mfma_f32_16x16x32_bf16 v[80:83], v[182:185], v[206:209], 0
	v_mfma_f32_16x16x32_bf16 v[68:71], v[174:177], v[214:217], 0
	v_mfma_f32_16x16x32_bf16 v[64:67], v[182:185], v[214:217], 0
	v_mfma_f32_16x16x32_bf16 v[116:119], v[178:181], v[194:197], v[116:119]
	v_mfma_f32_16x16x32_bf16 v[112:115], v[186:189], v[194:197], v[112:115]
	v_mfma_f32_16x16x32_bf16 v[100:103], v[178:181], v[202:205], v[100:103]
	v_mfma_f32_16x16x32_bf16 v[96:99], v[186:189], v[202:205], v[96:99]
	v_mfma_f32_16x16x32_bf16 v[84:87], v[178:181], v[210:213], v[84:87]
	v_mfma_f32_16x16x32_bf16 v[80:83], v[186:189], v[210:213], v[80:83]
	v_mfma_f32_16x16x32_bf16 v[68:71], v[178:181], v[218:221], v[68:71]
	v_mfma_f32_16x16x32_bf16 v[64:67], v[186:189], v[218:221], v[64:67]
	s_setprio 0
	s_barrier
	s_add_i32 s28, s55, s34
	v_lshl_add_u64 v[222:223], s[20:21], 0, v[130:131]
	s_mov_b32 m0, s28
	ds_read_b128 v[190:193], v159 offset:16384
	ds_read_b128 v[194:197], v159 offset:17408
	ds_read_b128 v[198:201], v159 offset:18432
	ds_read_b128 v[202:205], v159 offset:19456
	ds_read_b128 v[206:209], v159 offset:20480
	ds_read_b128 v[210:213], v159 offset:21504
	ds_read_b128 v[214:217], v159 offset:22528
	ds_read_b128 v[218:221], v159 offset:23552
	global_load_lds_dwordx4 v[222:223], off
	s_add_i32 m0, s28, 0x2000
	s_add_u32 s28, s20, 0x2c000
	v_lshl_add_u64 v[224:225], s[20:21], 0, v[134:135]
	s_addc_u32 s29, s21, 0
	s_add_i32 s30, s56, s34
	global_load_lds_dwordx4 v[224:225], off
	v_lshl_add_u64 v[226:227], s[28:29], 0, v[130:131]
	s_mov_b32 m0, s30
	v_lshl_add_u64 v[228:229], s[22:23], 0, v[132:133]
	global_load_lds_dwordx4 v[226:227], off
	v_lshl_add_u64 v[226:227], s[28:29], 0, v[134:135]
	s_add_i32 m0, s30, 0x2000
	s_nop 0
	global_load_lds_dwordx4 v[226:227], off
	v_lshl_add_u64 v[226:227], s[22:23], 0, v[128:129]
	s_mov_b32 m0, s35
	s_nop 0
	global_load_lds_dwordx4 v[226:227], off
	s_mov_b32 m0, s42
	s_nop 0
	global_load_lds_dwordx4 v[228:229], off
	s_waitcnt vmcnt(8)
	s_waitcnt lgkmcnt(0)
	s_barrier
	s_setprio 1
	s_waitcnt lgkmcnt(0)
	v_mfma_f32_16x16x32_bf16 v[60:63], v[146:149], v[190:193], 0
	v_mfma_f32_16x16x32_bf16 v[56:59], v[166:169], v[190:193], 0
	v_mfma_f32_16x16x32_bf16 v[44:47], v[146:149], v[198:201], 0
	v_mfma_f32_16x16x32_bf16 v[40:43], v[166:169], v[198:201], 0
	v_mfma_f32_16x16x32_bf16 v[28:31], v[146:149], v[206:209], 0
	v_mfma_f32_16x16x32_bf16 v[24:27], v[166:169], v[206:209], 0
	v_mfma_f32_16x16x32_bf16 v[12:15], v[146:149], v[214:217], 0
	v_mfma_f32_16x16x32_bf16 v[8:11], v[166:169], v[214:217], 0
	v_mfma_f32_16x16x32_bf16 v[60:63], v[162:165], v[194:197], v[60:63]
	v_mfma_f32_16x16x32_bf16 v[56:59], v[170:173], v[194:197], v[56:59]
	v_mfma_f32_16x16x32_bf16 v[44:47], v[162:165], v[202:205], v[44:47]
	v_mfma_f32_16x16x32_bf16 v[40:43], v[170:173], v[202:205], v[40:43]
	v_mfma_f32_16x16x32_bf16 v[28:31], v[162:165], v[210:213], v[28:31]
	v_mfma_f32_16x16x32_bf16 v[24:27], v[170:173], v[210:213], v[24:27]
	v_mfma_f32_16x16x32_bf16 v[12:15], v[162:165], v[218:221], v[12:15]
	v_mfma_f32_16x16x32_bf16 v[8:11], v[170:173], v[218:221], v[8:11]
	s_setprio 0
	s_setprio 1
	v_mfma_f32_16x16x32_bf16 v[52:55], v[174:177], v[190:193], 0
	v_mfma_f32_16x16x32_bf16 v[48:51], v[182:185], v[190:193], 0
	v_mfma_f32_16x16x32_bf16 v[36:39], v[174:177], v[198:201], 0
	v_mfma_f32_16x16x32_bf16 v[32:35], v[182:185], v[198:201], 0
	v_mfma_f32_16x16x32_bf16 v[20:23], v[174:177], v[206:209], 0
	v_mfma_f32_16x16x32_bf16 v[16:19], v[182:185], v[206:209], 0
	v_mfma_f32_16x16x32_bf16 v[4:7], v[174:177], v[214:217], 0
	v_mfma_f32_16x16x32_bf16 v[0:3], v[182:185], v[214:217], 0
	v_mfma_f32_16x16x32_bf16 v[52:55], v[178:181], v[194:197], v[52:55]
	v_mfma_f32_16x16x32_bf16 v[48:51], v[186:189], v[194:197], v[48:51]
	v_mfma_f32_16x16x32_bf16 v[36:39], v[178:181], v[202:205], v[36:39]
	v_mfma_f32_16x16x32_bf16 v[32:35], v[186:189], v[202:205], v[32:35]
	v_mfma_f32_16x16x32_bf16 v[20:23], v[178:181], v[210:213], v[20:23]
	v_mfma_f32_16x16x32_bf16 v[16:19], v[186:189], v[210:213], v[16:19]
	v_mfma_f32_16x16x32_bf16 v[4:7], v[178:181], v[218:221], v[4:7]
	v_mfma_f32_16x16x32_bf16 v[0:3], v[186:189], v[218:221], v[0:3]
	s_setprio 0
	s_barrier
	s_branch .Lkmid_P8

; #define PG8_STAGE(bufoff, gbase, voff) do { _Pragma("unroll") for (int _i = 0; _i < 2; ++_i) \
;         __builtin_amdgcn_global_load_lds((const unsigned*)((const char*)(gbase) + (voff)[_i]), (PG8_LAS unsigned*)(lds + (bufoff) + ldsw + _i * 8192), 16, 0, PG8_LOAD_AUX); } while (0)
; #define PG8_LDA(dst, b, h) do { _Pragma("unroll") for (int m = 0; m < 4; ++m) _Pragma("unroll") for (int k = 0; k < 2; ++k) dst[m][k] = *(const PG8_LAS bf16x8*)(lds + PG8_SA(b, h) + aoff + m * 2048 + k * 1024); } while (0)
; #define PG8_LDB(dst, b, h) do { _Pragma("unroll") for (int n = 0; n < 2; ++n) _Pragma("unroll") for (int k = 0; k < 2; ++k) dst[n][k] = *(const PG8_LAS bf16x8*)(lds + PG8_SB(b, h) + boff + n * 2048 + k * 1024); } while (0)
; #define PG8_MMA(ai, bj, At, Bt) do { __builtin_amdgcn_s_setprio(1); _Pragma("unroll") for (int m = 0; m < 4; ++m) _Pragma("unroll") for (int n = 0; n < 2; ++n) _Pragma("unroll") for (int k = 0; k < 2; ++k) \
;         acc[ai][bj][m][n] = __builtin_amdgcn_mfma_f32_16x16x32_bf16(Bt[n][k], At[m][k], acc[ai][bj][m][n], 0, 0, 0); __builtin_amdgcn_s_setprio(0); } while (0)
; #define PG8_WAIT_V(n) asm volatile("s_waitcnt vmcnt(" #n ")" ::: "memory")
; #define PG8_WAIT_L(n) asm volatile("s_waitcnt lgkmcnt(" #n ")" ::: "memory")
; #define PG8_BAR __builtin_amdgcn_s_barrier()
; #define PG8_SCHED __builtin_amdgcn_sched_barrier(0)
; template <class Epi, class Sched, bool ALIGN_EPI = false, bool SP2 = false>
; __device__ __forceinline__ void gemm_phase(PG8_LAS unsigned char* lds, const Gemm g, const Sched& S, const Epi& E) {
;     ...
;             PG8_LDB(B0, 1, 0); PG8_LDB(B1, 1, 1); PG8_SCHED; PG8_LDA(At, 1, 0); PG8_STAGE(PG8_SA(0, 1), a2 + hstepA, voffA);
;             PG8_WAIT_V(8); PG8_WAIT_L(0); PG8_BAR; PG8_MMA(0, 0, At, B0); PG8_MMA(0, 1, At, B1); PG8_BAR; PG8_SCHED;
.Lkmid_P8:
	s_add_i32 s28, 0, 0x18000
	v_add_u32_e32 v161, s28, v151
	s_add_i32 s29, 0, 0x1c000
	ds_read_b128 v[146:149], v161
	ds_read_b128 v[162:165], v161 offset:1024
	ds_read_b128 v[166:169], v161 offset:2048
	ds_read_b128 v[170:173], v161 offset:3072
	v_add_u32_e32 v161, s29, v151
	ds_read_b128 v[174:177], v161
	ds_read_b128 v[178:181], v161 offset:1024
	ds_read_b128 v[182:185], v161 offset:2048
	ds_read_b128 v[186:189], v161 offset:3072
	s_add_u32 s22, s22, 0xb0000
	s_addc_u32 s23, s23, 0
	s_mov_b32 m0, s43
	v_lshl_add_u64 v[230:231], s[22:23], 0, v[128:129]
	ds_read_b128 v[190:193], v159 offset:32768
	ds_read_b128 v[194:197], v159 offset:33792
	ds_read_b128 v[198:201], v159 offset:34816
	ds_read_b128 v[202:205], v159 offset:35840
	ds_read_b128 v[206:209], v159 offset:36864
	ds_read_b128 v[210:213], v159 offset:37888
	ds_read_b128 v[214:217], v159 offset:38912
	ds_read_b128 v[218:221], v159 offset:39936
	global_load_lds_dwordx4 v[230:231], off
	v_lshl_add_u64 v[230:231], s[22:23], 0, v[132:133]
	s_mov_b32 m0, s46
	s_nop 0
	global_load_lds_dwordx4 v[230:231], off
	s_waitcnt vmcnt(8)
	s_waitcnt lgkmcnt(0)
	s_barrier
	s_setprio 1
	s_waitcnt lgkmcnt(0)
	v_mfma_f32_16x16x32_bf16 v[124:127], v[146:149], v[190:193], v[124:127]
	v_mfma_f32_16x16x32_bf16 v[120:123], v[166:169], v[190:193], v[120:123]
	v_mfma_f32_16x16x32_bf16 v[108:111], v[146:149], v[198:201], v[108:111]
	v_mfma_f32_16x16x32_bf16 v[104:107], v[166:169], v[198:201], v[104:107]
	v_mfma_f32_16x16x32_bf16 v[92:95], v[146:149], v[206:209], v[92:95]
	v_mfma_f32_16x16x32_bf16 v[88:91], v[166:169], v[206:209], v[88:91]
	v_mfma_f32_16x16x32_bf16 v[76:79], v[146:149], v[214:217], v[76:79]
	v_mfma_f32_16x16x32_bf16 v[72:75], v[166:169], v[214:217], v[72:75]
	v_mfma_f32_16x16x32_bf16 v[124:127], v[162:165], v[194:197], v[124:127]
	v_mfma_f32_16x16x32_bf16 v[120:123], v[170:173], v[194:197], v[120:123]
	v_mfma_f32_16x16x32_bf16 v[108:111], v[162:165], v[202:205], v[108:111]
	v_mfma_f32_16x16x32_bf16 v[104:107], v[170:173], v[202:205], v[104:107]
	v_mfma_f32_16x16x32_bf16 v[92:95], v[162:165], v[210:213], v[92:95]
	v_mfma_f32_16x16x32_bf16 v[88:91], v[170:173], v[210:213], v[88:91]
	v_mfma_f32_16x16x32_bf16 v[76:79], v[162:165], v[218:221], v[76:79]
	v_mfma_f32_16x16x32_bf16 v[72:75], v[170:173], v[218:221], v[72:75]
	s_setprio 0
	s_setprio 1
	v_mfma_f32_16x16x32_bf16 v[116:119], v[174:177], v[190:193], v[116:119]
	v_mfma_f32_16x16x32_bf16 v[112:115], v[182:185], v[190:193], v[112:115]
	v_mfma_f32_16x16x32_bf16 v[100:103], v[174:177], v[198:201], v[100:103]
	v_mfma_f32_16x16x32_bf16 v[96:99], v[182:185], v[198:201], v[96:99]
	v_mfma_f32_16x16x32_bf16 v[84:87], v[174:177], v[206:209], v[84:87]
	v_mfma_f32_16x16x32_bf16 v[80:83], v[182:185], v[206:209], v[80:83]
	v_mfma_f32_16x16x32_bf16 v[68:71], v[174:177], v[214:217], v[68:71]
	v_mfma_f32_16x16x32_bf16 v[64:67], v[182:185], v[214:217], v[64:67]
	v_mfma_f32_16x16x32_bf16 v[116:119], v[178:181], v[194:197], v[116:119]
	v_mfma_f32_16x16x32_bf16 v[112:115], v[186:189], v[194:197], v[112:115]
	v_mfma_f32_16x16x32_bf16 v[100:103], v[178:181], v[202:205], v[100:103]
	v_mfma_f32_16x16x32_bf16 v[96:99], v[186:189], v[202:205], v[96:99]
	v_mfma_f32_16x16x32_bf16 v[84:87], v[178:181], v[210:213], v[84:87]
	v_mfma_f32_16x16x32_bf16 v[80:83], v[186:189], v[210:213], v[80:83]
	v_mfma_f32_16x16x32_bf16 v[68:71], v[178:181], v[218:221], v[68:71]
	v_mfma_f32_16x16x32_bf16 v[64:67], v[186:189], v[218:221], v[64:67]
	s_setprio 0
	s_barrier
; #define PG8_STAGE(bufoff, gbase, voff) do { _Pragma("unroll") for (int _i = 0; _i < 2; ++_i) \
;         __builtin_amdgcn_global_load_lds((const unsigned*)((const char*)(gbase) + (voff)[_i]), (PG8_LAS unsigned*)(lds + (bufoff) + ldsw + _i * 8192), 16, 0, PG8_LOAD_AUX); } while (0)
; #define PG8_LDA(dst, b, h) do { _Pragma("unroll") for (int m = 0; m < 4; ++m) _Pragma("unroll") for (int k = 0; k < 2; ++k) dst[m][k] = *(const PG8_LAS bf16x8*)(lds + PG8_SA(b, h) + aoff + m * 2048 + k * 1024); } while (0)
; #define PG8_MMA(ai, bj, At, Bt) do { __builtin_amdgcn_s_setprio(1); _Pragma("unroll") for (int m = 0; m < 4; ++m) _Pragma("unroll") for (int n = 0; n < 2; ++n) _Pragma("unroll") for (int k = 0; k < 2; ++k) \
;         acc[ai][bj][m][n] = __builtin_amdgcn_mfma_f32_16x16x32_bf16(Bt[n][k], At[m][k], acc[ai][bj][m][n], 0, 0, 0); __builtin_amdgcn_s_setprio(0); } while (0)
; #define PG8_WAIT_V(n) asm volatile("s_waitcnt vmcnt(" #n ")" ::: "memory")
; #define PG8_WAIT_L(n) asm volatile("s_waitcnt lgkmcnt(" #n ")" ::: "memory")
; #define PG8_BAR __builtin_amdgcn_s_barrier()
; #define PG8_SCHED __builtin_amdgcn_sched_barrier(0)
; template <class Epi, class Sched, bool ALIGN_EPI = false, bool SP2 = false>
; __device__ __forceinline__ void gemm_phase(PG8_LAS unsigned char* lds, const Gemm g, const Sched& S, const Epi& E) {
;     ...
;             PG8_LDA(At, 1, 1); PG8_STAGE(PG8_SB(1, 0), b3, voffB); PG8_STAGE(PG8_SB(1, 1), b3 + hstepB, voffB); PG8_STAGE(PG8_SA(1, 0), a3, voffA);
;             PG8_WAIT_V(8); PG8_WAIT_L(0); PG8_BAR; PG8_MMA(1, 0, At, B0); PG8_MMA(1, 1, At, B1); PG8_BAR; PG8_SCHED;
;     ...
;         }
;         if constexpr (ALIGN_EPI) { if (wr == 0) PG8_BAR; }
	s_add_i32 s22, s28, s34
	v_lshl_add_u64 v[222:223], v[222:223], 0, s[18:19]
	s_mov_b32 m0, s22
	ds_read_b128 v[190:193], v159 offset:49152
	ds_read_b128 v[194:197], v159 offset:50176
	ds_read_b128 v[198:201], v159 offset:51200
	ds_read_b128 v[202:205], v159 offset:52224
	ds_read_b128 v[206:209], v159 offset:53248
	ds_read_b128 v[210:213], v159 offset:54272
	ds_read_b128 v[214:217], v159 offset:55296
	ds_read_b128 v[218:221], v159 offset:56320
	global_load_lds_dwordx4 v[222:223], off
	s_add_i32 m0, s22, 0x2000
	s_add_u32 s20, s20, 0x2c080
	v_lshl_add_u64 v[222:223], v[224:225], 0, s[18:19]
	s_addc_u32 s21, s21, 0
	s_add_i32 s22, s29, s34
	global_load_lds_dwordx4 v[222:223], off
	v_lshl_add_u64 v[222:223], s[20:21], 0, v[130:131]
	s_mov_b32 m0, s22
	s_nop 0
	global_load_lds_dwordx4 v[222:223], off
	v_lshl_add_u64 v[222:223], s[20:21], 0, v[134:135]
	s_add_i32 m0, s22, 0x2000
	s_nop 0
	global_load_lds_dwordx4 v[222:223], off
	v_lshl_add_u64 v[222:223], v[226:227], 0, s[18:19]
	s_mov_b32 m0, s50
	s_nop 0
	global_load_lds_dwordx4 v[222:223], off
	v_lshl_add_u64 v[222:223], v[228:229], 0, s[18:19]
	s_mov_b32 m0, s51
	s_nop 0
	global_load_lds_dwordx4 v[222:223], off
	s_waitcnt vmcnt(8)
	s_waitcnt lgkmcnt(0)
	s_barrier
	s_setprio 1
	s_waitcnt lgkmcnt(0)
	v_mfma_f32_16x16x32_bf16 v[60:63], v[146:149], v[190:193], v[60:63]
	v_mfma_f32_16x16x32_bf16 v[56:59], v[166:169], v[190:193], v[56:59]
	v_mfma_f32_16x16x32_bf16 v[44:47], v[146:149], v[198:201], v[44:47]
	v_mfma_f32_16x16x32_bf16 v[40:43], v[166:169], v[198:201], v[40:43]
	v_mfma_f32_16x16x32_bf16 v[28:31], v[146:149], v[206:209], v[28:31]
	v_mfma_f32_16x16x32_bf16 v[24:27], v[166:169], v[206:209], v[24:27]
	v_mfma_f32_16x16x32_bf16 v[12:15], v[146:149], v[214:217], v[12:15]
	v_mfma_f32_16x16x32_bf16 v[8:11], v[166:169], v[214:217], v[8:11]
	v_mfma_f32_16x16x32_bf16 v[60:63], v[162:165], v[194:197], v[60:63]
	v_mfma_f32_16x16x32_bf16 v[56:59], v[170:173], v[194:197], v[56:59]
	v_mfma_f32_16x16x32_bf16 v[44:47], v[162:165], v[202:205], v[44:47]
	v_mfma_f32_16x16x32_bf16 v[40:43], v[170:173], v[202:205], v[40:43]
	v_mfma_f32_16x16x32_bf16 v[28:31], v[162:165], v[210:213], v[28:31]
	v_mfma_f32_16x16x32_bf16 v[24:27], v[170:173], v[210:213], v[24:27]
	v_mfma_f32_16x16x32_bf16 v[12:15], v[162:165], v[218:221], v[12:15]
	v_mfma_f32_16x16x32_bf16 v[8:11], v[170:173], v[218:221], v[8:11]
	s_setprio 0
	s_setprio 1
	v_mfma_f32_16x16x32_bf16 v[52:55], v[174:177], v[190:193], v[52:55]
	v_mfma_f32_16x16x32_bf16 v[48:51], v[182:185], v[190:193], v[48:51]
	v_mfma_f32_16x16x32_bf16 v[36:39], v[174:177], v[198:201], v[36:39]
	v_mfma_f32_16x16x32_bf16 v[32:35], v[182:185], v[198:201], v[32:35]
	v_mfma_f32_16x16x32_bf16 v[20:23], v[174:177], v[206:209], v[20:23]
	v_mfma_f32_16x16x32_bf16 v[16:19], v[182:185], v[206:209], v[16:19]
	v_mfma_f32_16x16x32_bf16 v[4:7], v[174:177], v[214:217], v[4:7]
	v_mfma_f32_16x16x32_bf16 v[0:3], v[182:185], v[214:217], v[0:3]
	v_mfma_f32_16x16x32_bf16 v[52:55], v[178:181], v[194:197], v[52:55]
	v_mfma_f32_16x16x32_bf16 v[48:51], v[186:189], v[194:197], v[48:51]
	v_mfma_f32_16x16x32_bf16 v[36:39], v[178:181], v[202:205], v[36:39]
	v_mfma_f32_16x16x32_bf16 v[32:35], v[186:189], v[202:205], v[32:35]
	v_mfma_f32_16x16x32_bf16 v[20:23], v[178:181], v[210:213], v[20:23]
	v_mfma_f32_16x16x32_bf16 v[16:19], v[186:189], v[210:213], v[16:19]
	v_mfma_f32_16x16x32_bf16 v[4:7], v[178:181], v[218:221], v[4:7]
	v_mfma_f32_16x16x32_bf16 v[0:3], v[186:189], v[218:221], v[0:3]
	s_setprio 0
	s_barrier
	s_add_i32 s27, s27, 2
	s_add_u32 s0, s0, 0x100
	s_addc_u32 s1, s1, 0
	s_add_u32 s25, s25, 0x100
	s_addc_u32 s26, s26, 0
	s_cmp_gt_u32 s27, 41
	s_cbranch_scc0 .LBB0_757
	s_and_b64 vcc, exec, s[36:37]
	s_cbranch_vccz .LBB0_760
	s_barrier

; #define PG8_STAGE(bufoff, gbase, voff) do { _Pragma("unroll") for (int _i = 0; _i < 2; ++_i) \
;         __builtin_amdgcn_global_load_lds((const unsigned*)((const char*)(gbase) + (voff)[_i]), (PG8_LAS unsigned*)(lds + (bufoff) + ldsw + _i * 8192), 16, 0, PG8_LOAD_AUX); } while (0)
; #define PG8_LDA(dst, b, h) do { _Pragma("unroll") for (int m = 0; m < 4; ++m) _Pragma("unroll") for (int k = 0; k < 2; ++k) dst[m][k] = *(const PG8_LAS bf16x8*)(lds + PG8_SA(b, h) + aoff + m * 2048 + k * 1024); } while (0)
; #define PG8_LDB(dst, b, h) do { _Pragma("unroll") for (int n = 0; n < 2; ++n) _Pragma("unroll") for (int k = 0; k < 2; ++k) dst[n][k] = *(const PG8_LAS bf16x8*)(lds + PG8_SB(b, h) + boff + n * 2048 + k * 1024); } while (0)
; #define PG8_MMA(ai, bj, At, Bt) do { __builtin_amdgcn_s_setprio(1); _Pragma("unroll") for (int m = 0; m < 4; ++m) _Pragma("unroll") for (int n = 0; n < 2; ++n) _Pragma("unroll") for (int k = 0; k < 2; ++k) \
;         acc[ai][bj][m][n] = __builtin_amdgcn_mfma_f32_16x16x32_bf16(Bt[n][k], At[m][k], acc[ai][bj][m][n], 0, 0, 0); __builtin_amdgcn_s_setprio(0); } while (0)
; #define PG8_WAIT_V(n) asm volatile("s_waitcnt vmcnt(" #n ")" ::: "memory")
; #define PG8_WAIT_L(n) asm volatile("s_waitcnt lgkmcnt(" #n ")" ::: "memory")
; #define PG8_BAR __builtin_amdgcn_s_barrier()
; #define PG8_SCHED __builtin_amdgcn_sched_barrier(0)
; template <class Epi, class Sched, bool ALIGN_EPI = false, bool SP2 = false>
; __device__ __forceinline__ void gemm_phase(PG8_LAS unsigned char* lds, const Gemm g, const Sched& S, const Epi& E) {
;     ...
;             const bool last = (t == nt - 2);
;             const char* a1 = cA + (size_t)(t + 1) * kstep;
;             const char* a2 = last ? nA : cA + (size_t)(t + 2) * kstep; const char* b2 = last ? nB : cB + (size_t)(t + 2) * kstep;
;             const char* a3 = a2 + kstep; const char* b3 = b2 + kstep;
;             if (last && has_next) S.a_ready(nxt);
;             if constexpr (SP2) {
;             PG8_LDB(B0, 0, 0); PG8_LDB(B1, 0, 1); PG8_SCHED; PG8_LDA(At, 0, 0); PG8_STAGE(PG8_SA(1, 1), a1 + hstepA, voffA);
;             PG8_WAIT_V(8); PG8_WAIT_L(0); PG8_BAR; PG8_MMA(0, 0, At, B0); PG8_MMA(0, 1, At, B1); PG8_BAR; PG8_SCHED;
.LBB0_849:
	s_ashr_i32 s41, s40, 31
	s_lshl_b64 s[22:23], s[40:41], 19
	s_add_u32 s42, s30, s22
	s_addc_u32 s43, s31, s23
	s_and_b64 s[22:23], s[4:5], exec
	s_cselect_b32 s7, s43, s1
	s_cselect_b32 s24, s42, s0
	s_ashr_i32 s37, s36, 31
	s_lshl_b64 s[22:23], s[36:37], 19
	v_readlane_b32 s26, v239, 36
	v_readlane_b32 s27, v239, 37
	s_add_u32 s46, s26, s22
	s_addc_u32 s47, s27, s23
	s_and_b64 s[22:23], s[4:5], exec
	s_cselect_b32 s25, s47, s21
	s_cselect_b32 s26, s46, s20
	s_add_u32 s0, s0, 0x40080
	s_addc_u32 s1, s1, 0
	s_add_u32 s27, s20, 0x100
	s_addc_u32 s28, s21, 0
	s_mov_b32 s29, -2
	s_waitcnt lgkmcnt(0)
	ds_read_b128 v[164:167], v159
	ds_read_b128 v[168:171], v159 offset:1024
	ds_read_b128 v[172:175], v159 offset:2048
	ds_read_b128 v[176:179], v159 offset:3072
	ds_read_b128 v[180:183], v160
	ds_read_b128 v[184:187], v160 offset:1024
	ds_read_b128 v[188:191], v160 offset:2048
	ds_read_b128 v[192:195], v160 offset:3072
	s_add_u32 s20, s0, 0xfffc0080
	s_addc_u32 s21, s1, -1
	s_cmp_eq_u32 s29, 12
	s_cselect_b32 s23, s7, s21
	s_cselect_b32 s22, s24, s20
	s_cselect_b32 s21, s25, s28
	s_cselect_b32 s20, s26, s27
	v_lshl_add_u64 v[148:149], s[0:1], 0, v[140:141]
	s_add_i32 m0, s35, 0xc000
	ds_read_b128 v[196:199], v161
	ds_read_b128 v[200:203], v161 offset:1024
	ds_read_b128 v[204:207], v161 offset:2048
	ds_read_b128 v[208:211], v161 offset:3072
	ds_read_b128 v[212:215], v161 offset:4096
	ds_read_b128 v[216:219], v161 offset:5120
	ds_read_b128 v[220:223], v161 offset:6144
	ds_read_b128 v[224:227], v161 offset:7168
	global_load_lds_dwordx4 v[148:149], off
	v_lshl_add_u64 v[148:149], s[0:1], 0, v[142:143]
	s_add_i32 m0, s35, 0xe000
	s_nop 0
	global_load_lds_dwordx4 v[148:149], off
	s_waitcnt vmcnt(8)
	s_waitcnt lgkmcnt(0)
	s_barrier
	s_setprio 1
	s_waitcnt lgkmcnt(0)
	v_mfma_f32_16x16x32_bf16 v[124:127], v[164:167], v[196:199], 0
	v_mfma_f32_16x16x32_bf16 v[120:123], v[172:175], v[196:199], 0
	v_mfma_f32_16x16x32_bf16 v[108:111], v[164:167], v[204:207], 0
	v_mfma_f32_16x16x32_bf16 v[104:107], v[172:175], v[204:207], 0
	v_mfma_f32_16x16x32_bf16 v[92:95], v[164:167], v[212:215], 0
	v_mfma_f32_16x16x32_bf16 v[88:91], v[172:175], v[212:215], 0
	v_mfma_f32_16x16x32_bf16 v[76:79], v[164:167], v[220:223], 0
	v_mfma_f32_16x16x32_bf16 v[72:75], v[172:175], v[220:223], 0
	v_mfma_f32_16x16x32_bf16 v[124:127], v[168:171], v[200:203], v[124:127]
	v_mfma_f32_16x16x32_bf16 v[120:123], v[176:179], v[200:203], v[120:123]
	v_mfma_f32_16x16x32_bf16 v[108:111], v[168:171], v[208:211], v[108:111]
	v_mfma_f32_16x16x32_bf16 v[104:107], v[176:179], v[208:211], v[104:107]
	v_mfma_f32_16x16x32_bf16 v[92:95], v[168:171], v[216:219], v[92:95]
	v_mfma_f32_16x16x32_bf16 v[88:91], v[176:179], v[216:219], v[88:91]
	v_mfma_f32_16x16x32_bf16 v[76:79], v[168:171], v[224:227], v[76:79]
	v_mfma_f32_16x16x32_bf16 v[72:75], v[176:179], v[224:227], v[72:75]
	s_setprio 0
	s_setprio 1
	v_mfma_f32_16x16x32_bf16 v[116:119], v[180:183], v[196:199], 0
	v_mfma_f32_16x16x32_bf16 v[112:115], v[188:191], v[196:199], 0
	v_mfma_f32_16x16x32_bf16 v[100:103], v[180:183], v[204:207], 0
	v_mfma_f32_16x16x32_bf16 v[96:99], v[188:191], v[204:207], 0
	v_mfma_f32_16x16x32_bf16 v[84:87], v[180:183], v[212:215], 0
	v_mfma_f32_16x16x32_bf16 v[80:83], v[188:191], v[212:215], 0
	v_mfma_f32_16x16x32_bf16 v[68:71], v[180:183], v[220:223], 0
	v_mfma_f32_16x16x32_bf16 v[64:67], v[188:191], v[220:223], 0
	v_mfma_f32_16x16x32_bf16 v[116:119], v[184:187], v[200:203], v[116:119]
	v_mfma_f32_16x16x32_bf16 v[112:115], v[192:195], v[200:203], v[112:115]
	v_mfma_f32_16x16x32_bf16 v[100:103], v[184:187], v[208:211], v[100:103]
	v_mfma_f32_16x16x32_bf16 v[96:99], v[192:195], v[208:211], v[96:99]
	v_mfma_f32_16x16x32_bf16 v[84:87], v[184:187], v[216:219], v[84:87]
	v_mfma_f32_16x16x32_bf16 v[80:83], v[192:195], v[216:219], v[80:83]
	v_mfma_f32_16x16x32_bf16 v[68:71], v[184:187], v[224:227], v[68:71]
	v_mfma_f32_16x16x32_bf16 v[64:67], v[192:195], v[224:227], v[64:67]
	s_setprio 0
	s_barrier
; #define PG8_STAGE(bufoff, gbase, voff) do { _Pragma("unroll") for (int _i = 0; _i < 2; ++_i) \
;         __builtin_amdgcn_global_load_lds((const unsigned*)((const char*)(gbase) + (voff)[_i]), (PG8_LAS unsigned*)(lds + (bufoff) + ldsw + _i * 8192), 16, 0, PG8_LOAD_AUX); } while (0)
; #define PG8_LDA(dst, b, h) do { _Pragma("unroll") for (int m = 0; m < 4; ++m) _Pragma("unroll") for (int k = 0; k < 2; ++k) dst[m][k] = *(const PG8_LAS bf16x8*)(lds + PG8_SA(b, h) + aoff + m * 2048 + k * 1024); } while (0)
; #define PG8_MMA(ai, bj, At, Bt) do { __builtin_amdgcn_s_setprio(1); _Pragma("unroll") for (int m = 0; m < 4; ++m) _Pragma("unroll") for (int n = 0; n < 2; ++n) _Pragma("unroll") for (int k = 0; k < 2; ++k) \
;         acc[ai][bj][m][n] = __builtin_amdgcn_mfma_f32_16x16x32_bf16(Bt[n][k], At[m][k], acc[ai][bj][m][n], 0, 0, 0); __builtin_amdgcn_s_setprio(0); } while (0)
; #define PG8_WAIT_V(n) asm volatile("s_waitcnt vmcnt(" #n ")" ::: "memory")
; #define PG8_WAIT_L(n) asm volatile("s_waitcnt lgkmcnt(" #n ")" ::: "memory")
; #define PG8_BAR __builtin_amdgcn_s_barrier()
; #define PG8_SCHED __builtin_amdgcn_sched_barrier(0)
; template <class Epi, class Sched, bool ALIGN_EPI = false, bool SP2 = false>
; __device__ __forceinline__ void gemm_phase(PG8_LAS unsigned char* lds, const Gemm g, const Sched& S, const Epi& E) {
;     ...
;             PG8_LDA(At, 0, 1); PG8_STAGE(PG8_SB(0, 0), b2, voffB); PG8_STAGE(PG8_SB(0, 1), b2 + hstepB, voffB); PG8_STAGE(PG8_SA(0, 0), a2, voffA);
;             PG8_WAIT_V(8); PG8_WAIT_L(0); PG8_BAR; PG8_MMA(1, 0, At, B0); PG8_MMA(1, 1, At, B1); PG8_BAR; PG8_SCHED;
	s_add_i32 s30, s61, s34
	v_lshl_add_u64 v[148:149], s[20:21], 0, v[130:131]
	s_mov_b32 m0, s30
	ds_read_b128 v[196:199], v161 offset:16384
	ds_read_b128 v[200:203], v161 offset:17408
	ds_read_b128 v[204:207], v161 offset:18432
	ds_read_b128 v[208:211], v161 offset:19456
	ds_read_b128 v[212:215], v161 offset:20480
	ds_read_b128 v[216:219], v161 offset:21504
	ds_read_b128 v[220:223], v161 offset:22528
	ds_read_b128 v[224:227], v161 offset:23552
	global_load_lds_dwordx4 v[148:149], off
	s_add_i32 m0, s30, 0x2000
	s_add_u32 s30, s20, 0x10000
	v_lshl_add_u64 v[228:229], s[20:21], 0, v[134:135]
	s_addc_u32 s31, s21, 0
	s_add_i32 s37, s62, s34
	global_load_lds_dwordx4 v[228:229], off
	v_lshl_add_u64 v[230:231], s[30:31], 0, v[130:131]
	s_mov_b32 m0, s37
	v_lshl_add_u64 v[232:233], s[22:23], 0, v[132:133]
	global_load_lds_dwordx4 v[230:231], off
	v_lshl_add_u64 v[230:231], s[30:31], 0, v[134:135]
	s_add_i32 m0, s37, 0x2000
	s_nop 0
	global_load_lds_dwordx4 v[230:231], off
	v_lshl_add_u64 v[230:231], s[22:23], 0, v[128:129]
	s_mov_b32 m0, s35
	s_nop 0
	global_load_lds_dwordx4 v[230:231], off
	s_mov_b32 m0, s49
	s_nop 0
	global_load_lds_dwordx4 v[232:233], off
	s_waitcnt vmcnt(8)
	s_waitcnt lgkmcnt(0)
	s_barrier
	s_setprio 1
	s_waitcnt lgkmcnt(0)
	v_mfma_f32_16x16x32_bf16 v[60:63], v[164:167], v[196:199], 0
	v_mfma_f32_16x16x32_bf16 v[56:59], v[172:175], v[196:199], 0
	v_mfma_f32_16x16x32_bf16 v[44:47], v[164:167], v[204:207], 0
	v_mfma_f32_16x16x32_bf16 v[40:43], v[172:175], v[204:207], 0
	v_mfma_f32_16x16x32_bf16 v[28:31], v[164:167], v[212:215], 0
	v_mfma_f32_16x16x32_bf16 v[24:27], v[172:175], v[212:215], 0
	v_mfma_f32_16x16x32_bf16 v[12:15], v[164:167], v[220:223], 0
	v_mfma_f32_16x16x32_bf16 v[8:11], v[172:175], v[220:223], 0
	v_mfma_f32_16x16x32_bf16 v[60:63], v[168:171], v[200:203], v[60:63]
	v_mfma_f32_16x16x32_bf16 v[56:59], v[176:179], v[200:203], v[56:59]
	v_mfma_f32_16x16x32_bf16 v[44:47], v[168:171], v[208:211], v[44:47]
	v_mfma_f32_16x16x32_bf16 v[40:43], v[176:179], v[208:211], v[40:43]
	v_mfma_f32_16x16x32_bf16 v[28:31], v[168:171], v[216:219], v[28:31]
	v_mfma_f32_16x16x32_bf16 v[24:27], v[176:179], v[216:219], v[24:27]
	v_mfma_f32_16x16x32_bf16 v[12:15], v[168:171], v[224:227], v[12:15]
	v_mfma_f32_16x16x32_bf16 v[8:11], v[176:179], v[224:227], v[8:11]
	s_setprio 0
	s_setprio 1
	v_mfma_f32_16x16x32_bf16 v[52:55], v[180:183], v[196:199], 0
	v_mfma_f32_16x16x32_bf16 v[48:51], v[188:191], v[196:199], 0
	v_mfma_f32_16x16x32_bf16 v[36:39], v[180:183], v[204:207], 0
	v_mfma_f32_16x16x32_bf16 v[32:35], v[188:191], v[204:207], 0
	v_mfma_f32_16x16x32_bf16 v[20:23], v[180:183], v[212:215], 0
	v_mfma_f32_16x16x32_bf16 v[16:19], v[188:191], v[212:215], 0
	v_mfma_f32_16x16x32_bf16 v[4:7], v[180:183], v[220:223], 0
	v_mfma_f32_16x16x32_bf16 v[0:3], v[188:191], v[220:223], 0
	v_mfma_f32_16x16x32_bf16 v[52:55], v[184:187], v[200:203], v[52:55]
	v_mfma_f32_16x16x32_bf16 v[48:51], v[192:195], v[200:203], v[48:51]
	v_mfma_f32_16x16x32_bf16 v[36:39], v[184:187], v[208:211], v[36:39]
	v_mfma_f32_16x16x32_bf16 v[32:35], v[192:195], v[208:211], v[32:35]
	v_mfma_f32_16x16x32_bf16 v[20:23], v[184:187], v[216:219], v[20:23]
	v_mfma_f32_16x16x32_bf16 v[16:19], v[192:195], v[216:219], v[16:19]
	v_mfma_f32_16x16x32_bf16 v[4:7], v[184:187], v[224:227], v[4:7]
	v_mfma_f32_16x16x32_bf16 v[0:3], v[192:195], v[224:227], v[0:3]
	s_setprio 0
	s_barrier
	s_branch .Lkmid_P9

; #define PG8_STAGE(bufoff, gbase, voff) do { _Pragma("unroll") for (int _i = 0; _i < 2; ++_i) \
;         __builtin_amdgcn_global_load_lds((const unsigned*)((const char*)(gbase) + (voff)[_i]), (PG8_LAS unsigned*)(lds + (bufoff) + ldsw + _i * 8192), 16, 0, PG8_LOAD_AUX); } while (0)
; #define PG8_LDA(dst, b, h) do { _Pragma("unroll") for (int m = 0; m < 4; ++m) _Pragma("unroll") for (int k = 0; k < 2; ++k) dst[m][k] = *(const PG8_LAS bf16x8*)(lds + PG8_SA(b, h) + aoff + m * 2048 + k * 1024); } while (0)
; #define PG8_LDB(dst, b, h) do { _Pragma("unroll") for (int n = 0; n < 2; ++n) _Pragma("unroll") for (int k = 0; k < 2; ++k) dst[n][k] = *(const PG8_LAS bf16x8*)(lds + PG8_SB(b, h) + boff + n * 2048 + k * 1024); } while (0)
; #define PG8_MMA(ai, bj, At, Bt) do { __builtin_amdgcn_s_setprio(1); _Pragma("unroll") for (int m = 0; m < 4; ++m) _Pragma("unroll") for (int n = 0; n < 2; ++n) _Pragma("unroll") for (int k = 0; k < 2; ++k) \
;         acc[ai][bj][m][n] = __builtin_amdgcn_mfma_f32_16x16x32_bf16(Bt[n][k], At[m][k], acc[ai][bj][m][n], 0, 0, 0); __builtin_amdgcn_s_setprio(0); } while (0)
; #define PG8_WAIT_V(n) asm volatile("s_waitcnt vmcnt(" #n ")" ::: "memory")
; #define PG8_WAIT_L(n) asm volatile("s_waitcnt lgkmcnt(" #n ")" ::: "memory")
; #define PG8_BAR __builtin_amdgcn_s_barrier()
; #define PG8_SCHED __builtin_amdgcn_sched_barrier(0)
; template <class Epi, class Sched, bool ALIGN_EPI = false, bool SP2 = false>
; __device__ __forceinline__ void gemm_phase(PG8_LAS unsigned char* lds, const Gemm g, const Sched& S, const Epi& E) {
;     ...
;             PG8_LDB(B0, 1, 0); PG8_LDB(B1, 1, 1); PG8_SCHED; PG8_LDA(At, 1, 0); PG8_STAGE(PG8_SA(0, 1), a2 + hstepA, voffA);
;             PG8_WAIT_V(8); PG8_WAIT_L(0); PG8_BAR; PG8_MMA(0, 0, At, B0); PG8_MMA(0, 1, At, B1); PG8_BAR; PG8_SCHED;
.Lkmid_P9:
	s_add_i32 s30, 0, 0x18000
	v_add_u32_e32 v150, s30, v157
	s_add_i32 s31, 0, 0x1c000
	ds_read_b128 v[164:167], v150
	ds_read_b128 v[168:171], v150 offset:1024
	ds_read_b128 v[172:175], v150 offset:2048
	ds_read_b128 v[176:179], v150 offset:3072
	v_add_u32_e32 v150, s31, v157
	ds_read_b128 v[180:183], v150
	ds_read_b128 v[184:187], v150 offset:1024
	ds_read_b128 v[188:191], v150 offset:2048
	ds_read_b128 v[192:195], v150 offset:3072
	s_add_u32 s22, s22, 0x40000
	s_addc_u32 s23, s23, 0
	s_mov_b32 m0, s50
	v_lshl_add_u64 v[234:235], s[22:23], 0, v[128:129]
	ds_read_b128 v[196:199], v161 offset:32768
	ds_read_b128 v[200:203], v161 offset:33792
	ds_read_b128 v[204:207], v161 offset:34816
	ds_read_b128 v[208:211], v161 offset:35840
	ds_read_b128 v[212:215], v161 offset:36864
	ds_read_b128 v[216:219], v161 offset:37888
	ds_read_b128 v[220:223], v161 offset:38912
	ds_read_b128 v[224:227], v161 offset:39936
	global_load_lds_dwordx4 v[234:235], off
	v_lshl_add_u64 v[234:235], s[22:23], 0, v[132:133]
	s_mov_b32 m0, s51
	s_nop 0
	global_load_lds_dwordx4 v[234:235], off
	s_waitcnt vmcnt(8)
	s_waitcnt lgkmcnt(0)
	s_barrier
	s_setprio 1
	s_waitcnt lgkmcnt(0)
	v_mfma_f32_16x16x32_bf16 v[124:127], v[164:167], v[196:199], v[124:127]
	v_mfma_f32_16x16x32_bf16 v[120:123], v[172:175], v[196:199], v[120:123]
	v_mfma_f32_16x16x32_bf16 v[108:111], v[164:167], v[204:207], v[108:111]
	v_mfma_f32_16x16x32_bf16 v[104:107], v[172:175], v[204:207], v[104:107]
	v_mfma_f32_16x16x32_bf16 v[92:95], v[164:167], v[212:215], v[92:95]
	v_mfma_f32_16x16x32_bf16 v[88:91], v[172:175], v[212:215], v[88:91]
	v_mfma_f32_16x16x32_bf16 v[76:79], v[164:167], v[220:223], v[76:79]
	v_mfma_f32_16x16x32_bf16 v[72:75], v[172:175], v[220:223], v[72:75]
	v_mfma_f32_16x16x32_bf16 v[124:127], v[168:171], v[200:203], v[124:127]
	v_mfma_f32_16x16x32_bf16 v[120:123], v[176:179], v[200:203], v[120:123]
	v_mfma_f32_16x16x32_bf16 v[108:111], v[168:171], v[208:211], v[108:111]
	v_mfma_f32_16x16x32_bf16 v[104:107], v[176:179], v[208:211], v[104:107]
	v_mfma_f32_16x16x32_bf16 v[92:95], v[168:171], v[216:219], v[92:95]
	v_mfma_f32_16x16x32_bf16 v[88:91], v[176:179], v[216:219], v[88:91]
	v_mfma_f32_16x16x32_bf16 v[76:79], v[168:171], v[224:227], v[76:79]
	v_mfma_f32_16x16x32_bf16 v[72:75], v[176:179], v[224:227], v[72:75]
	s_setprio 0
	s_setprio 1
	v_mfma_f32_16x16x32_bf16 v[116:119], v[180:183], v[196:199], v[116:119]
	v_mfma_f32_16x16x32_bf16 v[112:115], v[188:191], v[196:199], v[112:115]
	v_mfma_f32_16x16x32_bf16 v[100:103], v[180:183], v[204:207], v[100:103]
	v_mfma_f32_16x16x32_bf16 v[96:99], v[188:191], v[204:207], v[96:99]
	v_mfma_f32_16x16x32_bf16 v[84:87], v[180:183], v[212:215], v[84:87]
	v_mfma_f32_16x16x32_bf16 v[80:83], v[188:191], v[212:215], v[80:83]
	v_mfma_f32_16x16x32_bf16 v[68:71], v[180:183], v[220:223], v[68:71]
	v_mfma_f32_16x16x32_bf16 v[64:67], v[188:191], v[220:223], v[64:67]
	v_mfma_f32_16x16x32_bf16 v[116:119], v[184:187], v[200:203], v[116:119]
	v_mfma_f32_16x16x32_bf16 v[112:115], v[192:195], v[200:203], v[112:115]
	v_mfma_f32_16x16x32_bf16 v[100:103], v[184:187], v[208:211], v[100:103]
	v_mfma_f32_16x16x32_bf16 v[96:99], v[192:195], v[208:211], v[96:99]
	v_mfma_f32_16x16x32_bf16 v[84:87], v[184:187], v[216:219], v[84:87]
	v_mfma_f32_16x16x32_bf16 v[80:83], v[192:195], v[216:219], v[80:83]
	v_mfma_f32_16x16x32_bf16 v[68:71], v[184:187], v[224:227], v[68:71]
	v_mfma_f32_16x16x32_bf16 v[64:67], v[192:195], v[224:227], v[64:67]
	s_setprio 0
	s_barrier
; #define PG8_STAGE(bufoff, gbase, voff) do { _Pragma("unroll") for (int _i = 0; _i < 2; ++_i) \
;         __builtin_amdgcn_global_load_lds((const unsigned*)((const char*)(gbase) + (voff)[_i]), (PG8_LAS unsigned*)(lds + (bufoff) + ldsw + _i * 8192), 16, 0, PG8_LOAD_AUX); } while (0)
; #define PG8_LDA(dst, b, h) do { _Pragma("unroll") for (int m = 0; m < 4; ++m) _Pragma("unroll") for (int k = 0; k < 2; ++k) dst[m][k] = *(const PG8_LAS bf16x8*)(lds + PG8_SA(b, h) + aoff + m * 2048 + k * 1024); } while (0)
; #define PG8_MMA(ai, bj, At, Bt) do { __builtin_amdgcn_s_setprio(1); _Pragma("unroll") for (int m = 0; m < 4; ++m) _Pragma("unroll") for (int n = 0; n < 2; ++n) _Pragma("unroll") for (int k = 0; k < 2; ++k) \
;         acc[ai][bj][m][n] = __builtin_amdgcn_mfma_f32_16x16x32_bf16(Bt[n][k], At[m][k], acc[ai][bj][m][n], 0, 0, 0); __builtin_amdgcn_s_setprio(0); } while (0)
; #define PG8_WAIT_V(n) asm volatile("s_waitcnt vmcnt(" #n ")" ::: "memory")
; #define PG8_WAIT_L(n) asm volatile("s_waitcnt lgkmcnt(" #n ")" ::: "memory")
; #define PG8_BAR __builtin_amdgcn_s_barrier()
; #define PG8_SCHED __builtin_amdgcn_sched_barrier(0)
; template <class Epi, class Sched, bool ALIGN_EPI = false, bool SP2 = false>
; __device__ __forceinline__ void gemm_phase(PG8_LAS unsigned char* lds, const Gemm g, const Sched& S, const Epi& E) {
;     ...
;             PG8_LDA(At, 1, 1); PG8_STAGE(PG8_SB(1, 0), b3, voffB); PG8_STAGE(PG8_SB(1, 1), b3 + hstepB, voffB); PG8_STAGE(PG8_SA(1, 0), a3, voffA);
;             PG8_WAIT_V(8); PG8_WAIT_L(0); PG8_BAR; PG8_MMA(1, 0, At, B0); PG8_MMA(1, 1, At, B1); PG8_BAR; PG8_SCHED;
;     ...
;         }
;         if constexpr (ALIGN_EPI) { if (wr == 0) PG8_BAR; }
	s_add_i32 s22, s30, s34
	v_lshl_add_u64 v[148:149], v[148:149], 0, s[16:17]
	s_mov_b32 m0, s22
	ds_read_b128 v[196:199], v161 offset:49152
	ds_read_b128 v[200:203], v161 offset:50176
	ds_read_b128 v[204:207], v161 offset:51200
	ds_read_b128 v[208:211], v161 offset:52224
	ds_read_b128 v[212:215], v161 offset:53248
	ds_read_b128 v[216:219], v161 offset:54272
	ds_read_b128 v[220:223], v161 offset:55296
	ds_read_b128 v[224:227], v161 offset:56320
	global_load_lds_dwordx4 v[148:149], off
	s_add_i32 m0, s22, 0x2000
	s_add_u32 s20, s20, 0x10080
	v_lshl_add_u64 v[148:149], v[228:229], 0, s[16:17]
	s_addc_u32 s21, s21, 0
	s_add_i32 s22, s31, s34
	global_load_lds_dwordx4 v[148:149], off
	v_lshl_add_u64 v[148:149], s[20:21], 0, v[130:131]
	s_mov_b32 m0, s22
	s_nop 0
	global_load_lds_dwordx4 v[148:149], off
	v_lshl_add_u64 v[148:149], s[20:21], 0, v[134:135]
	s_add_i32 m0, s22, 0x2000
	s_nop 0
	global_load_lds_dwordx4 v[148:149], off
	v_lshl_add_u64 v[148:149], v[230:231], 0, s[16:17]
	s_mov_b32 m0, s56
	s_nop 0
	global_load_lds_dwordx4 v[148:149], off
	v_lshl_add_u64 v[148:149], v[232:233], 0, s[16:17]
	s_mov_b32 m0, s57
	s_nop 0
	global_load_lds_dwordx4 v[148:149], off
	s_waitcnt vmcnt(8)
	s_waitcnt lgkmcnt(0)
	s_barrier
	s_setprio 1
	s_waitcnt lgkmcnt(0)
	v_mfma_f32_16x16x32_bf16 v[60:63], v[164:167], v[196:199], v[60:63]
	v_mfma_f32_16x16x32_bf16 v[56:59], v[172:175], v[196:199], v[56:59]
	v_mfma_f32_16x16x32_bf16 v[44:47], v[164:167], v[204:207], v[44:47]
	v_mfma_f32_16x16x32_bf16 v[40:43], v[172:175], v[204:207], v[40:43]
	v_mfma_f32_16x16x32_bf16 v[28:31], v[164:167], v[212:215], v[28:31]
	v_mfma_f32_16x16x32_bf16 v[24:27], v[172:175], v[212:215], v[24:27]
	v_mfma_f32_16x16x32_bf16 v[12:15], v[164:167], v[220:223], v[12:15]
	v_mfma_f32_16x16x32_bf16 v[8:11], v[172:175], v[220:223], v[8:11]
	v_mfma_f32_16x16x32_bf16 v[60:63], v[168:171], v[200:203], v[60:63]
	v_mfma_f32_16x16x32_bf16 v[56:59], v[176:179], v[200:203], v[56:59]
	v_mfma_f32_16x16x32_bf16 v[44:47], v[168:171], v[208:211], v[44:47]
	v_mfma_f32_16x16x32_bf16 v[40:43], v[176:179], v[208:211], v[40:43]
	v_mfma_f32_16x16x32_bf16 v[28:31], v[168:171], v[216:219], v[28:31]
	v_mfma_f32_16x16x32_bf16 v[24:27], v[176:179], v[216:219], v[24:27]
	v_mfma_f32_16x16x32_bf16 v[12:15], v[168:171], v[224:227], v[12:15]
	v_mfma_f32_16x16x32_bf16 v[8:11], v[176:179], v[224:227], v[8:11]
	s_setprio 0
	s_setprio 1
	v_mfma_f32_16x16x32_bf16 v[52:55], v[180:183], v[196:199], v[52:55]
	v_mfma_f32_16x16x32_bf16 v[48:51], v[188:191], v[196:199], v[48:51]
	v_mfma_f32_16x16x32_bf16 v[36:39], v[180:183], v[204:207], v[36:39]
	v_mfma_f32_16x16x32_bf16 v[32:35], v[188:191], v[204:207], v[32:35]
	v_mfma_f32_16x16x32_bf16 v[20:23], v[180:183], v[212:215], v[20:23]
	v_mfma_f32_16x16x32_bf16 v[16:19], v[188:191], v[212:215], v[16:19]
	v_mfma_f32_16x16x32_bf16 v[4:7], v[180:183], v[220:223], v[4:7]
	v_mfma_f32_16x16x32_bf16 v[0:3], v[188:191], v[220:223], v[0:3]
	v_mfma_f32_16x16x32_bf16 v[52:55], v[184:187], v[200:203], v[52:55]
	v_mfma_f32_16x16x32_bf16 v[48:51], v[192:195], v[200:203], v[48:51]
	v_mfma_f32_16x16x32_bf16 v[36:39], v[184:187], v[208:211], v[36:39]
	v_mfma_f32_16x16x32_bf16 v[32:35], v[192:195], v[208:211], v[32:35]
	v_mfma_f32_16x16x32_bf16 v[20:23], v[184:187], v[216:219], v[20:23]
	v_mfma_f32_16x16x32_bf16 v[16:19], v[192:195], v[216:219], v[16:19]
	v_mfma_f32_16x16x32_bf16 v[4:7], v[184:187], v[224:227], v[4:7]
	v_mfma_f32_16x16x32_bf16 v[0:3], v[192:195], v[224:227], v[0:3]
	s_setprio 0
	s_barrier
	s_add_i32 s29, s29, 2
	s_add_u32 s0, s0, 0x100
	s_addc_u32 s1, s1, 0
	s_add_u32 s27, s27, 0x100
	s_addc_u32 s28, s28, 0
	s_cmp_gt_u32 s29, 13
	s_cbranch_scc0 .LBB0_850
	s_and_b64 vcc, exec, s[18:19]
	s_cbranch_vccz .LBB0_853
	s_barrier

; #define PG8_STAGE(bufoff, gbase, voff) do { _Pragma("unroll") for (int _i = 0; _i < 2; ++_i) \
;         __builtin_amdgcn_global_load_lds((const unsigned*)((const char*)(gbase) + (voff)[_i]), (PG8_LAS unsigned*)(lds + (bufoff) + ldsw + _i * 8192), 16, 0, PG8_LOAD_AUX); } while (0)
; #define PG8_LDA(dst, b, h) do { _Pragma("unroll") for (int m = 0; m < 4; ++m) _Pragma("unroll") for (int k = 0; k < 2; ++k) dst[m][k] = *(const PG8_LAS bf16x8*)(lds + PG8_SA(b, h) + aoff + m * 2048 + k * 1024); } while (0)
; #define PG8_LDB(dst, b, h) do { _Pragma("unroll") for (int n = 0; n < 2; ++n) _Pragma("unroll") for (int k = 0; k < 2; ++k) dst[n][k] = *(const PG8_LAS bf16x8*)(lds + PG8_SB(b, h) + boff + n * 2048 + k * 1024); } while (0)
; #define PG8_MMA(ai, bj, At, Bt) do { __builtin_amdgcn_s_setprio(1); _Pragma("unroll") for (int m = 0; m < 4; ++m) _Pragma("unroll") for (int n = 0; n < 2; ++n) _Pragma("unroll") for (int k = 0; k < 2; ++k) \
;         acc[ai][bj][m][n] = __builtin_amdgcn_mfma_f32_16x16x32_bf16(Bt[n][k], At[m][k], acc[ai][bj][m][n], 0, 0, 0); __builtin_amdgcn_s_setprio(0); } while (0)
; #define PG8_WAIT_V(n) asm volatile("s_waitcnt vmcnt(" #n ")" ::: "memory")
; #define PG8_WAIT_L(n) asm volatile("s_waitcnt lgkmcnt(" #n ")" ::: "memory")
; #define PG8_BAR __builtin_amdgcn_s_barrier()
; template <class Epi, class Sched, bool ALIGN_EPI = false, bool SP2 = false>
; __device__ __forceinline__ void gemm_phase(PG8_LAS unsigned char* lds, const Gemm g, const Sched& S, const Epi& E) {
;     ...
;         const char* nA = has_next ? (const char*)g.A + (size_t)nxt.pm * tstepA + (size_t)nxt.pn * apn : cA; const char* nB = has_next ? (const char*)g.Bt + (size_t)nxt.pn * tstepB : cB;
;         for (int t = 0; t < nt; t += 2) {
;             const bool last = (t == nt - 2);
;             const char* a1 = cA + (size_t)(t + 1) * kstep;
;             const char* a2 = last ? nA : cA + (size_t)(t + 2) * kstep; const char* b2 = last ? nB : cB + (size_t)(t + 2) * kstep;
;             const char* a3 = a2 + kstep; const char* b3 = b2 + kstep;
;             if (last && has_next) S.a_ready(nxt);
;             if constexpr (SP2) {
;             PG8_LDB(B0, 0, 0); PG8_LDB(B1, 0, 1); PG8_SCHED; PG8_LDA(At, 0, 0); PG8_STAGE(PG8_SA(1, 1), a1 + hstepA, voffA);
;             PG8_WAIT_V(8); PG8_WAIT_L(0); PG8_BAR; PG8_MMA(0, 0, At, B0); PG8_MMA(0, 1, At, B1); PG8_BAR; PG8_SCHED;
.LBB0_1017:
	s_lshl_b64 s[22:23], s[40:41], 17
	v_readlane_b32 s24, v239, 38
	s_add_u32 s44, s24, s22
	v_readlane_b32 s22, v239, 39
	s_addc_u32 s45, s22, s23
	s_and_b64 s[22:23], s[6:7], exec
	s_cselect_b32 s24, s45, s1
	s_cselect_b32 s25, s44, s0
	s_mov_b32 s26, 0
	s_mov_b64 s[22:23], -1
	s_mov_b64 s[34:35], 0
	s_waitcnt lgkmcnt(0)
	s_add_u32 s30, s20, s26
	s_addc_u32 s31, s21, 0
	s_add_u32 s27, s30, 0x100
	s_addc_u32 s33, s31, 0
	s_and_b64 s[28:29], s[34:35], exec
	s_cselect_b32 s51, s9, s33
	s_cselect_b32 s50, s8, s27
	s_add_u32 s26, s0, s26
	s_addc_u32 s27, s1, 0
	s_add_u32 s28, s26, 0x100
	s_addc_u32 s29, s27, 0
	s_and_b64 s[26:27], s[34:35], exec
	s_cselect_b32 s53, s24, s29
	s_cselect_b32 s52, s25, s28
	s_add_u32 s56, s30, 0x40080
	ds_read_b128 v[142:145], v150
	ds_read_b128 v[156:159], v150 offset:1024
	ds_read_b128 v[160:163], v150 offset:2048
	ds_read_b128 v[164:167], v150 offset:3072
	ds_read_b128 v[168:171], v151
	ds_read_b128 v[172:175], v151 offset:1024
	ds_read_b128 v[176:179], v151 offset:2048
	ds_read_b128 v[180:183], v151 offset:3072
	s_addc_u32 s57, s31, 0
	s_add_i32 s38, s70, s58
	s_add_i32 m0, s47, 0xc000
	s_add_i32 s43, s47, 0xe000
	s_add_i32 s30, s38, 0x2000
	s_add_u32 s54, s52, 0x4000
	s_addc_u32 s55, s53, 0
	s_add_i32 s33, s71, s58
	s_add_i32 s31, s33, 0x2000
	s_add_i32 s29, 0, 0x18000
	s_add_i32 s28, 0, 0x1c000
	s_add_u32 s48, s50, 0x40000
	s_addc_u32 s49, s51, 0
	s_add_i32 s27, s29, s58
	s_add_i32 s26, s27, 0x2000
	s_add_u32 s34, s52, 0x4080
	s_addc_u32 s35, s53, 0
	s_add_i32 s41, s28, s58
	s_add_i32 s39, s41, 0x2000
	v_lshl_add_u64 v[216:217], s[56:57], 0, v[128:129]
	ds_read_b128 v[184:187], v152
	ds_read_b128 v[188:191], v152 offset:1024
	ds_read_b128 v[192:195], v152 offset:2048
	ds_read_b128 v[196:199], v152 offset:3072
	ds_read_b128 v[200:203], v152 offset:4096
	ds_read_b128 v[204:207], v152 offset:5120
	ds_read_b128 v[208:211], v152 offset:6144
	ds_read_b128 v[212:215], v152 offset:7168
	global_load_lds_dwordx4 v[216:217], off
	v_lshl_add_u64 v[216:217], s[56:57], 0, v[132:133]
	s_mov_b32 m0, s43
	s_nop 0
	global_load_lds_dwordx4 v[216:217], off
	s_waitcnt vmcnt(8)
	s_waitcnt lgkmcnt(0)
	s_barrier
	s_setprio 1
	s_waitcnt lgkmcnt(0)
	v_mfma_f32_16x16x32_bf16 v[124:127], v[142:145], v[184:187], 0
	v_mfma_f32_16x16x32_bf16 v[120:123], v[160:163], v[184:187], 0
	v_mfma_f32_16x16x32_bf16 v[108:111], v[142:145], v[192:195], 0
	v_mfma_f32_16x16x32_bf16 v[104:107], v[160:163], v[192:195], 0
	v_mfma_f32_16x16x32_bf16 v[92:95], v[142:145], v[200:203], 0
	v_mfma_f32_16x16x32_bf16 v[88:91], v[160:163], v[200:203], 0
	v_mfma_f32_16x16x32_bf16 v[76:79], v[142:145], v[208:211], 0
	v_mfma_f32_16x16x32_bf16 v[72:75], v[160:163], v[208:211], 0
	v_mfma_f32_16x16x32_bf16 v[124:127], v[156:159], v[188:191], v[124:127]
	v_mfma_f32_16x16x32_bf16 v[120:123], v[164:167], v[188:191], v[120:123]
	v_mfma_f32_16x16x32_bf16 v[108:111], v[156:159], v[196:199], v[108:111]
	v_mfma_f32_16x16x32_bf16 v[104:107], v[164:167], v[196:199], v[104:107]
	v_mfma_f32_16x16x32_bf16 v[92:95], v[156:159], v[204:207], v[92:95]
	v_mfma_f32_16x16x32_bf16 v[88:91], v[164:167], v[204:207], v[88:91]
	v_mfma_f32_16x16x32_bf16 v[76:79], v[156:159], v[212:215], v[76:79]
	v_mfma_f32_16x16x32_bf16 v[72:75], v[164:167], v[212:215], v[72:75]
	s_setprio 0
	s_setprio 1
	v_mfma_f32_16x16x32_bf16 v[116:119], v[168:171], v[184:187], 0
	v_mfma_f32_16x16x32_bf16 v[112:115], v[176:179], v[184:187], 0
	v_mfma_f32_16x16x32_bf16 v[100:103], v[168:171], v[192:195], 0
	v_mfma_f32_16x16x32_bf16 v[96:99], v[176:179], v[192:195], 0
	v_mfma_f32_16x16x32_bf16 v[84:87], v[168:171], v[200:203], 0
	v_mfma_f32_16x16x32_bf16 v[80:83], v[176:179], v[200:203], 0
	v_mfma_f32_16x16x32_bf16 v[68:71], v[168:171], v[208:211], 0
	v_mfma_f32_16x16x32_bf16 v[64:67], v[176:179], v[208:211], 0
	v_mfma_f32_16x16x32_bf16 v[116:119], v[172:175], v[188:191], v[116:119]
	v_mfma_f32_16x16x32_bf16 v[112:115], v[180:183], v[188:191], v[112:115]
	v_mfma_f32_16x16x32_bf16 v[100:103], v[172:175], v[196:199], v[100:103]
	v_mfma_f32_16x16x32_bf16 v[96:99], v[180:183], v[196:199], v[96:99]
	v_mfma_f32_16x16x32_bf16 v[84:87], v[172:175], v[204:207], v[84:87]
	v_mfma_f32_16x16x32_bf16 v[80:83], v[180:183], v[204:207], v[80:83]
	v_mfma_f32_16x16x32_bf16 v[68:71], v[172:175], v[212:215], v[68:71]
	v_mfma_f32_16x16x32_bf16 v[64:67], v[180:183], v[212:215], v[64:67]
	s_setprio 0
	s_barrier
; #define PG8_STAGE(bufoff, gbase, voff) do { _Pragma("unroll") for (int _i = 0; _i < 2; ++_i) \
;         __builtin_amdgcn_global_load_lds((const unsigned*)((const char*)(gbase) + (voff)[_i]), (PG8_LAS unsigned*)(lds + (bufoff) + ldsw + _i * 8192), 16, 0, PG8_LOAD_AUX); } while (0)
; #define PG8_LDA(dst, b, h) do { _Pragma("unroll") for (int m = 0; m < 4; ++m) _Pragma("unroll") for (int k = 0; k < 2; ++k) dst[m][k] = *(const PG8_LAS bf16x8*)(lds + PG8_SA(b, h) + aoff + m * 2048 + k * 1024); } while (0)
; #define PG8_MMA(ai, bj, At, Bt) do { __builtin_amdgcn_s_setprio(1); _Pragma("unroll") for (int m = 0; m < 4; ++m) _Pragma("unroll") for (int n = 0; n < 2; ++n) _Pragma("unroll") for (int k = 0; k < 2; ++k) \
;         acc[ai][bj][m][n] = __builtin_amdgcn_mfma_f32_16x16x32_bf16(Bt[n][k], At[m][k], acc[ai][bj][m][n], 0, 0, 0); __builtin_amdgcn_s_setprio(0); } while (0)
; #define PG8_WAIT_V(n) asm volatile("s_waitcnt vmcnt(" #n ")" ::: "memory")
; #define PG8_WAIT_L(n) asm volatile("s_waitcnt lgkmcnt(" #n ")" ::: "memory")
; #define PG8_BAR __builtin_amdgcn_s_barrier()
; #define PG8_SCHED __builtin_amdgcn_sched_barrier(0)
; template <class Epi, class Sched, bool ALIGN_EPI = false, bool SP2 = false>
; __device__ __forceinline__ void gemm_phase(PG8_LAS unsigned char* lds, const Gemm g, const Sched& S, const Epi& E) {
;     ...
;             PG8_LDA(At, 0, 1); PG8_STAGE(PG8_SB(0, 0), b2, voffB); PG8_STAGE(PG8_SB(0, 1), b2 + hstepB, voffB); PG8_STAGE(PG8_SA(0, 0), a2, voffA);
;             PG8_WAIT_V(8); PG8_WAIT_L(0); PG8_BAR; PG8_MMA(1, 0, At, B0); PG8_MMA(1, 1, At, B1); PG8_BAR; PG8_SCHED;
	s_mov_b32 m0, s38
	v_lshl_add_u64 v[216:217], s[52:53], 0, v[130:131]
	ds_read_b128 v[184:187], v152 offset:16384
	ds_read_b128 v[188:191], v152 offset:17408
	ds_read_b128 v[192:195], v152 offset:18432
	ds_read_b128 v[196:199], v152 offset:19456
	ds_read_b128 v[200:203], v152 offset:20480
	ds_read_b128 v[204:207], v152 offset:21504
	ds_read_b128 v[208:211], v152 offset:22528
	ds_read_b128 v[212:215], v152 offset:23552
	global_load_lds_dwordx4 v[216:217], off
	v_lshl_add_u64 v[218:219], s[52:53], 0, v[134:135]
	s_mov_b32 m0, s30
	v_lshl_add_u64 v[220:221], s[54:55], 0, v[130:131]
	global_load_lds_dwordx4 v[218:219], off
	s_mov_b32 m0, s33
	v_lshl_add_u64 v[222:223], s[50:51], 0, v[132:133]
	global_load_lds_dwordx4 v[220:221], off
	v_lshl_add_u64 v[220:221], s[54:55], 0, v[134:135]
	s_mov_b32 m0, s31
	s_nop 0
	global_load_lds_dwordx4 v[220:221], off
	v_lshl_add_u64 v[220:221], s[50:51], 0, v[128:129]
	s_mov_b32 m0, s47
	s_nop 0
	global_load_lds_dwordx4 v[220:221], off
	s_mov_b32 m0, s59
	s_nop 0
	global_load_lds_dwordx4 v[222:223], off
	s_waitcnt vmcnt(8)
	s_waitcnt lgkmcnt(0)
	s_barrier
	s_setprio 1
	s_waitcnt lgkmcnt(0)
	v_mfma_f32_16x16x32_bf16 v[60:63], v[142:145], v[184:187], 0
	v_mfma_f32_16x16x32_bf16 v[56:59], v[160:163], v[184:187], 0
	v_mfma_f32_16x16x32_bf16 v[44:47], v[142:145], v[192:195], 0
	v_mfma_f32_16x16x32_bf16 v[40:43], v[160:163], v[192:195], 0
	v_mfma_f32_16x16x32_bf16 v[28:31], v[142:145], v[200:203], 0
	v_mfma_f32_16x16x32_bf16 v[24:27], v[160:163], v[200:203], 0
	v_mfma_f32_16x16x32_bf16 v[12:15], v[142:145], v[208:211], 0
	v_mfma_f32_16x16x32_bf16 v[8:11], v[160:163], v[208:211], 0
	v_mfma_f32_16x16x32_bf16 v[60:63], v[156:159], v[188:191], v[60:63]
	v_mfma_f32_16x16x32_bf16 v[56:59], v[164:167], v[188:191], v[56:59]
	v_mfma_f32_16x16x32_bf16 v[44:47], v[156:159], v[196:199], v[44:47]
	v_mfma_f32_16x16x32_bf16 v[40:43], v[164:167], v[196:199], v[40:43]
	v_mfma_f32_16x16x32_bf16 v[28:31], v[156:159], v[204:207], v[28:31]
	v_mfma_f32_16x16x32_bf16 v[24:27], v[164:167], v[204:207], v[24:27]
	v_mfma_f32_16x16x32_bf16 v[12:15], v[156:159], v[212:215], v[12:15]
	v_mfma_f32_16x16x32_bf16 v[8:11], v[164:167], v[212:215], v[8:11]
	s_setprio 0
	s_setprio 1
	v_mfma_f32_16x16x32_bf16 v[52:55], v[168:171], v[184:187], 0
	v_mfma_f32_16x16x32_bf16 v[48:51], v[176:179], v[184:187], 0
	v_mfma_f32_16x16x32_bf16 v[36:39], v[168:171], v[192:195], 0
	v_mfma_f32_16x16x32_bf16 v[32:35], v[176:179], v[192:195], 0
	v_mfma_f32_16x16x32_bf16 v[20:23], v[168:171], v[200:203], 0
	v_mfma_f32_16x16x32_bf16 v[16:19], v[176:179], v[200:203], 0
	v_mfma_f32_16x16x32_bf16 v[4:7], v[168:171], v[208:211], 0
	v_mfma_f32_16x16x32_bf16 v[0:3], v[176:179], v[208:211], 0
	v_mfma_f32_16x16x32_bf16 v[52:55], v[172:175], v[188:191], v[52:55]
	v_mfma_f32_16x16x32_bf16 v[48:51], v[180:183], v[188:191], v[48:51]
	v_mfma_f32_16x16x32_bf16 v[36:39], v[172:175], v[196:199], v[36:39]
	v_mfma_f32_16x16x32_bf16 v[32:35], v[180:183], v[196:199], v[32:35]
	v_mfma_f32_16x16x32_bf16 v[20:23], v[172:175], v[204:207], v[20:23]
	v_mfma_f32_16x16x32_bf16 v[16:19], v[180:183], v[204:207], v[16:19]
	v_mfma_f32_16x16x32_bf16 v[4:7], v[172:175], v[212:215], v[4:7]
	v_mfma_f32_16x16x32_bf16 v[0:3], v[180:183], v[212:215], v[0:3]
	s_setprio 0
	s_barrier
	s_branch .Lkmid_P11

; #define PG8_STAGE(bufoff, gbase, voff) do { _Pragma("unroll") for (int _i = 0; _i < 2; ++_i) \
;         __builtin_amdgcn_global_load_lds((const unsigned*)((const char*)(gbase) + (voff)[_i]), (PG8_LAS unsigned*)(lds + (bufoff) + ldsw + _i * 8192), 16, 0, PG8_LOAD_AUX); } while (0)
; #define PG8_LDA(dst, b, h) do { _Pragma("unroll") for (int m = 0; m < 4; ++m) _Pragma("unroll") for (int k = 0; k < 2; ++k) dst[m][k] = *(const PG8_LAS bf16x8*)(lds + PG8_SA(b, h) + aoff + m * 2048 + k * 1024); } while (0)
; #define PG8_LDB(dst, b, h) do { _Pragma("unroll") for (int n = 0; n < 2; ++n) _Pragma("unroll") for (int k = 0; k < 2; ++k) dst[n][k] = *(const PG8_LAS bf16x8*)(lds + PG8_SB(b, h) + boff + n * 2048 + k * 1024); } while (0)
; #define PG8_MMA(ai, bj, At, Bt) do { __builtin_amdgcn_s_setprio(1); _Pragma("unroll") for (int m = 0; m < 4; ++m) _Pragma("unroll") for (int n = 0; n < 2; ++n) _Pragma("unroll") for (int k = 0; k < 2; ++k) \
;         acc[ai][bj][m][n] = __builtin_amdgcn_mfma_f32_16x16x32_bf16(Bt[n][k], At[m][k], acc[ai][bj][m][n], 0, 0, 0); __builtin_amdgcn_s_setprio(0); } while (0)
; #define PG8_WAIT_V(n) asm volatile("s_waitcnt vmcnt(" #n ")" ::: "memory")
; #define PG8_WAIT_L(n) asm volatile("s_waitcnt lgkmcnt(" #n ")" ::: "memory")
; #define PG8_BAR __builtin_amdgcn_s_barrier()
; #define PG8_SCHED __builtin_amdgcn_sched_barrier(0)
; template <class Epi, class Sched, bool ALIGN_EPI = false, bool SP2 = false>
; __device__ __forceinline__ void gemm_phase(PG8_LAS unsigned char* lds, const Gemm g, const Sched& S, const Epi& E) {
;     ...
;             PG8_LDB(B0, 1, 0); PG8_LDB(B1, 1, 1); PG8_SCHED; PG8_LDA(At, 1, 0); PG8_STAGE(PG8_SA(0, 1), a2 + hstepA, voffA);
;             PG8_WAIT_V(8); PG8_WAIT_L(0); PG8_BAR; PG8_MMA(0, 0, At, B0); PG8_MMA(0, 1, At, B1); PG8_BAR; PG8_SCHED;
;             PG8_LDA(At, 1, 1); PG8_STAGE(PG8_SB(1, 0), b3, voffB); PG8_STAGE(PG8_SB(1, 1), b3 + hstepB, voffB); PG8_STAGE(PG8_SA(1, 0), a3, voffA);
;             PG8_WAIT_V(8); PG8_WAIT_L(0); PG8_BAR; PG8_MMA(1, 0, At, B0); PG8_MMA(1, 1, At, B1); PG8_BAR; PG8_SCHED;
;     ...
;         if constexpr (ALIGN_EPI) { if (wr == 0) PG8_BAR; }
.Lkmid_P11:
	v_add_u32_e32 v164, s29, v147
	v_add_u32_e32 v180, s28, v147
	ds_read_b128 v[142:145], v164
	ds_read_b128 v[156:159], v164 offset:1024
	ds_read_b128 v[160:163], v164 offset:2048
	ds_read_b128 v[164:167], v164 offset:3072
	ds_read_b128 v[168:171], v180
	ds_read_b128 v[172:175], v180 offset:1024
	ds_read_b128 v[176:179], v180 offset:2048
	ds_read_b128 v[180:183], v180 offset:3072
	s_mov_b32 m0, s60
	v_lshl_add_u64 v[224:225], s[48:49], 0, v[128:129]
	ds_read_b128 v[184:187], v152 offset:32768
	ds_read_b128 v[188:191], v152 offset:33792
	ds_read_b128 v[192:195], v152 offset:34816
	ds_read_b128 v[196:199], v152 offset:35840
	ds_read_b128 v[200:203], v152 offset:36864
	ds_read_b128 v[204:207], v152 offset:37888
	ds_read_b128 v[208:211], v152 offset:38912
	ds_read_b128 v[212:215], v152 offset:39936
	global_load_lds_dwordx4 v[224:225], off
	v_lshl_add_u64 v[224:225], s[48:49], 0, v[132:133]
	s_mov_b32 m0, s61
	s_nop 0
	global_load_lds_dwordx4 v[224:225], off
	s_waitcnt vmcnt(8)
	s_waitcnt lgkmcnt(0)
	s_barrier
	s_setprio 1
	s_waitcnt lgkmcnt(0)
	v_mfma_f32_16x16x32_bf16 v[124:127], v[142:145], v[184:187], v[124:127]
	v_mfma_f32_16x16x32_bf16 v[120:123], v[160:163], v[184:187], v[120:123]
	v_mfma_f32_16x16x32_bf16 v[108:111], v[142:145], v[192:195], v[108:111]
	v_mfma_f32_16x16x32_bf16 v[104:107], v[160:163], v[192:195], v[104:107]
	v_mfma_f32_16x16x32_bf16 v[92:95], v[142:145], v[200:203], v[92:95]
	v_mfma_f32_16x16x32_bf16 v[88:91], v[160:163], v[200:203], v[88:91]
	v_mfma_f32_16x16x32_bf16 v[76:79], v[142:145], v[208:211], v[76:79]
	v_mfma_f32_16x16x32_bf16 v[72:75], v[160:163], v[208:211], v[72:75]
	v_mfma_f32_16x16x32_bf16 v[124:127], v[156:159], v[188:191], v[124:127]
	v_mfma_f32_16x16x32_bf16 v[120:123], v[164:167], v[188:191], v[120:123]
	v_mfma_f32_16x16x32_bf16 v[108:111], v[156:159], v[196:199], v[108:111]
	v_mfma_f32_16x16x32_bf16 v[104:107], v[164:167], v[196:199], v[104:107]
	v_mfma_f32_16x16x32_bf16 v[92:95], v[156:159], v[204:207], v[92:95]
	v_mfma_f32_16x16x32_bf16 v[88:91], v[164:167], v[204:207], v[88:91]
	v_mfma_f32_16x16x32_bf16 v[76:79], v[156:159], v[212:215], v[76:79]
	v_mfma_f32_16x16x32_bf16 v[72:75], v[164:167], v[212:215], v[72:75]
	s_setprio 0
	s_setprio 1
	v_mfma_f32_16x16x32_bf16 v[116:119], v[168:171], v[184:187], v[116:119]
	v_mfma_f32_16x16x32_bf16 v[112:115], v[176:179], v[184:187], v[112:115]
	v_mfma_f32_16x16x32_bf16 v[100:103], v[168:171], v[192:195], v[100:103]
	v_mfma_f32_16x16x32_bf16 v[96:99], v[176:179], v[192:195], v[96:99]
	v_mfma_f32_16x16x32_bf16 v[84:87], v[168:171], v[200:203], v[84:87]
	v_mfma_f32_16x16x32_bf16 v[80:83], v[176:179], v[200:203], v[80:83]
	v_mfma_f32_16x16x32_bf16 v[68:71], v[168:171], v[208:211], v[68:71]
	v_mfma_f32_16x16x32_bf16 v[64:67], v[176:179], v[208:211], v[64:67]
	v_mfma_f32_16x16x32_bf16 v[116:119], v[172:175], v[188:191], v[116:119]
	v_mfma_f32_16x16x32_bf16 v[112:115], v[180:183], v[188:191], v[112:115]
	v_mfma_f32_16x16x32_bf16 v[100:103], v[172:175], v[196:199], v[100:103]
	v_mfma_f32_16x16x32_bf16 v[96:99], v[180:183], v[196:199], v[96:99]
	v_mfma_f32_16x16x32_bf16 v[84:87], v[172:175], v[204:207], v[84:87]
	v_mfma_f32_16x16x32_bf16 v[80:83], v[180:183], v[204:207], v[80:83]
	v_mfma_f32_16x16x32_bf16 v[68:71], v[172:175], v[212:215], v[68:71]
	v_mfma_f32_16x16x32_bf16 v[64:67], v[180:183], v[212:215], v[64:67]
	s_setprio 0
	s_barrier
	s_mov_b32 m0, s27
	v_lshl_add_u64 v[216:217], v[216:217], 0, s[18:19]
	ds_read_b128 v[184:187], v152 offset:49152
	ds_read_b128 v[188:191], v152 offset:50176
	ds_read_b128 v[192:195], v152 offset:51200
	ds_read_b128 v[196:199], v152 offset:52224
	ds_read_b128 v[200:203], v152 offset:53248
	ds_read_b128 v[204:207], v152 offset:54272
	ds_read_b128 v[208:211], v152 offset:55296
	ds_read_b128 v[212:215], v152 offset:56320
	global_load_lds_dwordx4 v[216:217], off
	v_lshl_add_u64 v[216:217], v[218:219], 0, s[18:19]
	s_mov_b32 m0, s26
	s_nop 0
	global_load_lds_dwordx4 v[216:217], off
	v_lshl_add_u64 v[216:217], s[34:35], 0, v[130:131]
	s_mov_b32 m0, s41
	s_nop 0
	global_load_lds_dwordx4 v[216:217], off
	v_lshl_add_u64 v[216:217], s[34:35], 0, v[134:135]
	s_mov_b32 m0, s39
	s_nop 0
	global_load_lds_dwordx4 v[216:217], off
	v_lshl_add_u64 v[216:217], v[220:221], 0, s[18:19]
	s_mov_b32 m0, s65
	s_nop 0
	global_load_lds_dwordx4 v[216:217], off
	v_lshl_add_u64 v[216:217], v[222:223], 0, s[18:19]
	s_mov_b32 m0, s66
	s_nop 0
	global_load_lds_dwordx4 v[216:217], off
	s_waitcnt vmcnt(8)
	s_waitcnt lgkmcnt(0)
	s_barrier
	s_setprio 1
	s_waitcnt lgkmcnt(0)
	v_mfma_f32_16x16x32_bf16 v[60:63], v[142:145], v[184:187], v[60:63]
	v_mfma_f32_16x16x32_bf16 v[56:59], v[160:163], v[184:187], v[56:59]
	v_mfma_f32_16x16x32_bf16 v[44:47], v[142:145], v[192:195], v[44:47]
	v_mfma_f32_16x16x32_bf16 v[40:43], v[160:163], v[192:195], v[40:43]
	v_mfma_f32_16x16x32_bf16 v[28:31], v[142:145], v[200:203], v[28:31]
	v_mfma_f32_16x16x32_bf16 v[24:27], v[160:163], v[200:203], v[24:27]
	v_mfma_f32_16x16x32_bf16 v[12:15], v[142:145], v[208:211], v[12:15]
	v_mfma_f32_16x16x32_bf16 v[8:11], v[160:163], v[208:211], v[8:11]
	v_mfma_f32_16x16x32_bf16 v[60:63], v[156:159], v[188:191], v[60:63]
	v_mfma_f32_16x16x32_bf16 v[56:59], v[164:167], v[188:191], v[56:59]
	v_mfma_f32_16x16x32_bf16 v[44:47], v[156:159], v[196:199], v[44:47]
	v_mfma_f32_16x16x32_bf16 v[40:43], v[164:167], v[196:199], v[40:43]
	v_mfma_f32_16x16x32_bf16 v[28:31], v[156:159], v[204:207], v[28:31]
	v_mfma_f32_16x16x32_bf16 v[24:27], v[164:167], v[204:207], v[24:27]
	v_mfma_f32_16x16x32_bf16 v[12:15], v[156:159], v[212:215], v[12:15]
	v_mfma_f32_16x16x32_bf16 v[8:11], v[164:167], v[212:215], v[8:11]
	s_setprio 0
	s_setprio 1
	v_mfma_f32_16x16x32_bf16 v[52:55], v[168:171], v[184:187], v[52:55]
	v_mfma_f32_16x16x32_bf16 v[48:51], v[176:179], v[184:187], v[48:51]
	v_mfma_f32_16x16x32_bf16 v[36:39], v[168:171], v[192:195], v[36:39]
	v_mfma_f32_16x16x32_bf16 v[32:35], v[176:179], v[192:195], v[32:35]
	v_mfma_f32_16x16x32_bf16 v[20:23], v[168:171], v[200:203], v[20:23]
	v_mfma_f32_16x16x32_bf16 v[16:19], v[176:179], v[200:203], v[16:19]
	v_mfma_f32_16x16x32_bf16 v[4:7], v[168:171], v[208:211], v[4:7]
	v_mfma_f32_16x16x32_bf16 v[0:3], v[176:179], v[208:211], v[0:3]
	v_mfma_f32_16x16x32_bf16 v[52:55], v[172:175], v[188:191], v[52:55]
	v_mfma_f32_16x16x32_bf16 v[48:51], v[180:183], v[188:191], v[48:51]
	v_mfma_f32_16x16x32_bf16 v[36:39], v[172:175], v[196:199], v[36:39]
	v_mfma_f32_16x16x32_bf16 v[32:35], v[180:183], v[196:199], v[32:35]
	v_mfma_f32_16x16x32_bf16 v[20:23], v[172:175], v[204:207], v[20:23]
	v_mfma_f32_16x16x32_bf16 v[16:19], v[180:183], v[204:207], v[16:19]
	v_mfma_f32_16x16x32_bf16 v[4:7], v[172:175], v[212:215], v[4:7]
	v_mfma_f32_16x16x32_bf16 v[0:3], v[180:183], v[212:215], v[0:3]
	s_setprio 0
	s_barrier
	s_movk_i32 s26, 0x100
	s_andn2_b64 vcc, exec, s[22:23]
	s_mov_b64 s[34:35], -1
	s_mov_b64 s[22:23], 0
	s_cbranch_vccz .LBB0_1018
	s_and_b64 vcc, exec, s[36:37]
	s_cbranch_vccz .LBB0_1021
	s_barrier

; #define PG8_STAGE(bufoff, gbase, voff) do { _Pragma("unroll") for (int _i = 0; _i < 2; ++_i) \
;         __builtin_amdgcn_global_load_lds((const unsigned*)((const char*)(gbase) + (voff)[_i]), (PG8_LAS unsigned*)(lds + (bufoff) + ldsw + _i * 8192), 16, 0, PG8_LOAD_AUX); } while (0)
; #define PG8_LDA(dst, b, h) do { _Pragma("unroll") for (int m = 0; m < 4; ++m) _Pragma("unroll") for (int k = 0; k < 2; ++k) dst[m][k] = *(const PG8_LAS bf16x8*)(lds + PG8_SA(b, h) + aoff + m * 2048 + k * 1024); } while (0)
; #define PG8_LDB(dst, b, h) do { _Pragma("unroll") for (int n = 0; n < 2; ++n) _Pragma("unroll") for (int k = 0; k < 2; ++k) dst[n][k] = *(const PG8_LAS bf16x8*)(lds + PG8_SB(b, h) + boff + n * 2048 + k * 1024); } while (0)
; #define PG8_MMA(ai, bj, At, Bt) do { __builtin_amdgcn_s_setprio(1); _Pragma("unroll") for (int m = 0; m < 4; ++m) _Pragma("unroll") for (int n = 0; n < 2; ++n) _Pragma("unroll") for (int k = 0; k < 2; ++k) \
;         acc[ai][bj][m][n] = __builtin_amdgcn_mfma_f32_16x16x32_bf16(Bt[n][k], At[m][k], acc[ai][bj][m][n], 0, 0, 0); __builtin_amdgcn_s_setprio(0); } while (0)
; #define PG8_WAIT_V(n) asm volatile("s_waitcnt vmcnt(" #n ")" ::: "memory")
; #define PG8_WAIT_L(n) asm volatile("s_waitcnt lgkmcnt(" #n ")" ::: "memory")
; template <class Epi, class Sched, bool ALIGN_EPI = false, bool SP2 = false>
; __device__ __forceinline__ void gemm_phase(PG8_LAS unsigned char* lds, const Gemm g, const Sched& S, const Epi& E) {
;     ...
;         const bool has_next = S.next(ui + 1, nxt);
;         const char* nA = has_next ? (const char*)g.A + (size_t)nxt.pm * tstepA + (size_t)nxt.pn * apn : cA; const char* nB = has_next ? (const char*)g.Bt + (size_t)nxt.pn * tstepB : cB;
;         for (int t = 0; t < nt; t += 2) {
;             const bool last = (t == nt - 2);
;             const char* a1 = cA + (size_t)(t + 1) * kstep;
;             const char* a2 = last ? nA : cA + (size_t)(t + 2) * kstep; const char* b2 = last ? nB : cB + (size_t)(t + 2) * kstep;
;             const char* a3 = a2 + kstep; const char* b3 = b2 + kstep;
;             if (last && has_next) S.a_ready(nxt);
;             if constexpr (SP2) {
;             PG8_LDB(B0, 0, 0); PG8_LDB(B1, 0, 1); PG8_SCHED; PG8_LDA(At, 0, 0); PG8_STAGE(PG8_SA(1, 1), a1 + hstepA, voffA);
;             PG8_WAIT_V(8); PG8_WAIT_L(0); PG8_BAR; PG8_MMA(0, 0, At, B0); PG8_MMA(0, 1, At, B1); PG8_BAR; PG8_SCHED;
.LBB0_1110:
	s_ashr_i32 s17, s16, 31
	s_lshl_b64 s[18:19], s[16:17], 19
	s_add_u32 s18, s30, s18
	s_addc_u32 s19, s31, s19
	s_and_b64 s[24:25], s[2:3], exec
	s_cselect_b32 s17, s19, s21
	s_cselect_b32 s24, s18, s20
	s_ashr_i32 s15, s14, 31
	s_lshl_b64 s[26:27], s[14:15], 19
	s_add_u32 s36, s40, s26
	s_addc_u32 s37, s41, s27
	s_and_b64 s[26:27], s[2:3], exec
	s_cselect_b32 s15, s37, s23
	s_cselect_b32 s25, s36, s22
	s_add_u32 s20, s20, 0x40080
	s_addc_u32 s21, s21, 0
	s_add_u32 s26, s22, 0x100
	s_addc_u32 s27, s23, 0
	s_mov_b32 s28, -2
	ds_read_b128 v[146:149], v157
	ds_read_b128 v[162:165], v157 offset:1024
	ds_read_b128 v[166:169], v157 offset:2048
	ds_read_b128 v[170:173], v157 offset:3072
	ds_read_b128 v[174:177], v158
	ds_read_b128 v[178:181], v158 offset:1024
	ds_read_b128 v[182:185], v158 offset:2048
	ds_read_b128 v[186:189], v158 offset:3072
	s_add_u32 s22, s20, 0xfffc0080
	s_addc_u32 s23, s21, -1
	s_cmp_eq_u32 s28, 12
	s_cselect_b32 s35, s17, s23
	s_cselect_b32 s34, s24, s22
	s_cselect_b32 s23, s15, s27
	s_cselect_b32 s22, s25, s26
	v_lshl_add_u64 v[150:151], s[20:21], 0, v[138:139]
	s_add_i32 m0, s45, 0xc000
	ds_read_b128 v[190:193], v159
	ds_read_b128 v[194:197], v159 offset:1024
	ds_read_b128 v[198:201], v159 offset:2048
	ds_read_b128 v[202:205], v159 offset:3072
	ds_read_b128 v[206:209], v159 offset:4096
	ds_read_b128 v[210:213], v159 offset:5120
	ds_read_b128 v[214:217], v159 offset:6144
	ds_read_b128 v[218:221], v159 offset:7168
	global_load_lds_dwordx4 v[150:151], off
	v_lshl_add_u64 v[150:151], s[20:21], 0, v[140:141]
	s_add_i32 m0, s45, 0xe000
	s_nop 0
	global_load_lds_dwordx4 v[150:151], off
	s_waitcnt vmcnt(8)
	s_waitcnt lgkmcnt(0)
	s_barrier
	s_setprio 1
	s_waitcnt lgkmcnt(0)
	v_mfma_f32_16x16x32_bf16 v[124:127], v[146:149], v[190:193], 0
	v_mfma_f32_16x16x32_bf16 v[120:123], v[166:169], v[190:193], 0
	v_mfma_f32_16x16x32_bf16 v[108:111], v[146:149], v[198:201], 0
	v_mfma_f32_16x16x32_bf16 v[104:107], v[166:169], v[198:201], 0
	v_mfma_f32_16x16x32_bf16 v[92:95], v[146:149], v[206:209], 0
	v_mfma_f32_16x16x32_bf16 v[88:91], v[166:169], v[206:209], 0
	v_mfma_f32_16x16x32_bf16 v[76:79], v[146:149], v[214:217], 0
	v_mfma_f32_16x16x32_bf16 v[72:75], v[166:169], v[214:217], 0
	v_mfma_f32_16x16x32_bf16 v[124:127], v[162:165], v[194:197], v[124:127]
	v_mfma_f32_16x16x32_bf16 v[120:123], v[170:173], v[194:197], v[120:123]
	v_mfma_f32_16x16x32_bf16 v[108:111], v[162:165], v[202:205], v[108:111]
	v_mfma_f32_16x16x32_bf16 v[104:107], v[170:173], v[202:205], v[104:107]
	v_mfma_f32_16x16x32_bf16 v[92:95], v[162:165], v[210:213], v[92:95]
	v_mfma_f32_16x16x32_bf16 v[88:91], v[170:173], v[210:213], v[88:91]
	v_mfma_f32_16x16x32_bf16 v[76:79], v[162:165], v[218:221], v[76:79]
	v_mfma_f32_16x16x32_bf16 v[72:75], v[170:173], v[218:221], v[72:75]
	s_setprio 0
	s_setprio 1
	v_mfma_f32_16x16x32_bf16 v[116:119], v[174:177], v[190:193], 0
	v_mfma_f32_16x16x32_bf16 v[112:115], v[182:185], v[190:193], 0
	v_mfma_f32_16x16x32_bf16 v[100:103], v[174:177], v[198:201], 0
	v_mfma_f32_16x16x32_bf16 v[96:99], v[182:185], v[198:201], 0
	v_mfma_f32_16x16x32_bf16 v[84:87], v[174:177], v[206:209], 0
	v_mfma_f32_16x16x32_bf16 v[80:83], v[182:185], v[206:209], 0
	v_mfma_f32_16x16x32_bf16 v[68:71], v[174:177], v[214:217], 0
	v_mfma_f32_16x16x32_bf16 v[64:67], v[182:185], v[214:217], 0
	v_mfma_f32_16x16x32_bf16 v[116:119], v[178:181], v[194:197], v[116:119]
	v_mfma_f32_16x16x32_bf16 v[112:115], v[186:189], v[194:197], v[112:115]
	v_mfma_f32_16x16x32_bf16 v[100:103], v[178:181], v[202:205], v[100:103]
	v_mfma_f32_16x16x32_bf16 v[96:99], v[186:189], v[202:205], v[96:99]
	v_mfma_f32_16x16x32_bf16 v[84:87], v[178:181], v[210:213], v[84:87]
	v_mfma_f32_16x16x32_bf16 v[80:83], v[186:189], v[210:213], v[80:83]
	v_mfma_f32_16x16x32_bf16 v[68:71], v[178:181], v[218:221], v[68:71]
	v_mfma_f32_16x16x32_bf16 v[64:67], v[186:189], v[218:221], v[64:67]
	s_setprio 0
	s_barrier
; #define PG8_STAGE(bufoff, gbase, voff) do { _Pragma("unroll") for (int _i = 0; _i < 2; ++_i) \
;         __builtin_amdgcn_global_load_lds((const unsigned*)((const char*)(gbase) + (voff)[_i]), (PG8_LAS unsigned*)(lds + (bufoff) + ldsw + _i * 8192), 16, 0, PG8_LOAD_AUX); } while (0)
; #define PG8_LDA(dst, b, h) do { _Pragma("unroll") for (int m = 0; m < 4; ++m) _Pragma("unroll") for (int k = 0; k < 2; ++k) dst[m][k] = *(const PG8_LAS bf16x8*)(lds + PG8_SA(b, h) + aoff + m * 2048 + k * 1024); } while (0)
; #define PG8_MMA(ai, bj, At, Bt) do { __builtin_amdgcn_s_setprio(1); _Pragma("unroll") for (int m = 0; m < 4; ++m) _Pragma("unroll") for (int n = 0; n < 2; ++n) _Pragma("unroll") for (int k = 0; k < 2; ++k) \
;         acc[ai][bj][m][n] = __builtin_amdgcn_mfma_f32_16x16x32_bf16(Bt[n][k], At[m][k], acc[ai][bj][m][n], 0, 0, 0); __builtin_amdgcn_s_setprio(0); } while (0)
; #define PG8_WAIT_V(n) asm volatile("s_waitcnt vmcnt(" #n ")" ::: "memory")
; #define PG8_WAIT_L(n) asm volatile("s_waitcnt lgkmcnt(" #n ")" ::: "memory")
; #define PG8_BAR __builtin_amdgcn_s_barrier()
; #define PG8_SCHED __builtin_amdgcn_sched_barrier(0)
; template <class Epi, class Sched, bool ALIGN_EPI = false, bool SP2 = false>
; __device__ __forceinline__ void gemm_phase(PG8_LAS unsigned char* lds, const Gemm g, const Sched& S, const Epi& E) {
;     ...
;             PG8_LDA(At, 0, 1); PG8_STAGE(PG8_SB(0, 0), b2, voffB); PG8_STAGE(PG8_SB(0, 1), b2 + hstepB, voffB); PG8_STAGE(PG8_SA(0, 0), a2, voffA);
;             PG8_WAIT_V(8); PG8_WAIT_L(0); PG8_BAR; PG8_MMA(1, 0, At, B0); PG8_MMA(1, 1, At, B1); PG8_BAR; PG8_SCHED;
	s_add_i32 s29, s54, s42
	v_lshl_add_u64 v[150:151], s[22:23], 0, v[132:133]
	s_mov_b32 m0, s29
	ds_read_b128 v[190:193], v159 offset:16384
	ds_read_b128 v[194:197], v159 offset:17408
	ds_read_b128 v[198:201], v159 offset:18432
	ds_read_b128 v[202:205], v159 offset:19456
	ds_read_b128 v[206:209], v159 offset:20480
	ds_read_b128 v[210:213], v159 offset:21504
	ds_read_b128 v[214:217], v159 offset:22528
	ds_read_b128 v[218:221], v159 offset:23552
	global_load_lds_dwordx4 v[150:151], off
	s_add_i32 m0, s29, 0x2000
	s_add_u32 s30, s22, 0x40000
	v_lshl_add_u64 v[222:223], s[22:23], 0, v[128:129]
	s_addc_u32 s31, s23, 0
	s_add_i32 s29, s55, s42
	global_load_lds_dwordx4 v[222:223], off
	v_lshl_add_u64 v[224:225], s[30:31], 0, v[132:133]
	s_mov_b32 m0, s29
	v_lshl_add_u64 v[226:227], s[34:35], 0, v[130:131]
	global_load_lds_dwordx4 v[224:225], off
	v_lshl_add_u64 v[224:225], s[30:31], 0, v[128:129]
	s_add_i32 m0, s29, 0x2000
	s_nop 0
	global_load_lds_dwordx4 v[224:225], off
	v_lshl_add_u64 v[224:225], s[34:35], 0, v[134:135]
	s_mov_b32 m0, s45
	s_nop 0
	global_load_lds_dwordx4 v[224:225], off
	s_mov_b32 m0, s46
	s_nop 0
	global_load_lds_dwordx4 v[226:227], off
	s_waitcnt vmcnt(8)
	s_waitcnt lgkmcnt(0)
	s_barrier
	s_setprio 1
	s_waitcnt lgkmcnt(0)
	v_mfma_f32_16x16x32_bf16 v[60:63], v[146:149], v[190:193], 0
	v_mfma_f32_16x16x32_bf16 v[56:59], v[166:169], v[190:193], 0
	v_mfma_f32_16x16x32_bf16 v[44:47], v[146:149], v[198:201], 0
	v_mfma_f32_16x16x32_bf16 v[40:43], v[166:169], v[198:201], 0
	v_mfma_f32_16x16x32_bf16 v[28:31], v[146:149], v[206:209], 0
	v_mfma_f32_16x16x32_bf16 v[24:27], v[166:169], v[206:209], 0
	v_mfma_f32_16x16x32_bf16 v[12:15], v[146:149], v[214:217], 0
	v_mfma_f32_16x16x32_bf16 v[8:11], v[166:169], v[214:217], 0
	v_mfma_f32_16x16x32_bf16 v[60:63], v[162:165], v[194:197], v[60:63]
	v_mfma_f32_16x16x32_bf16 v[56:59], v[170:173], v[194:197], v[56:59]
	v_mfma_f32_16x16x32_bf16 v[44:47], v[162:165], v[202:205], v[44:47]
	v_mfma_f32_16x16x32_bf16 v[40:43], v[170:173], v[202:205], v[40:43]
	v_mfma_f32_16x16x32_bf16 v[28:31], v[162:165], v[210:213], v[28:31]
	v_mfma_f32_16x16x32_bf16 v[24:27], v[170:173], v[210:213], v[24:27]
	v_mfma_f32_16x16x32_bf16 v[12:15], v[162:165], v[218:221], v[12:15]
	v_mfma_f32_16x16x32_bf16 v[8:11], v[170:173], v[218:221], v[8:11]
	s_setprio 0
	s_setprio 1
	v_mfma_f32_16x16x32_bf16 v[52:55], v[174:177], v[190:193], 0
	v_mfma_f32_16x16x32_bf16 v[48:51], v[182:185], v[190:193], 0
	v_mfma_f32_16x16x32_bf16 v[36:39], v[174:177], v[198:201], 0
	v_mfma_f32_16x16x32_bf16 v[32:35], v[182:185], v[198:201], 0
	v_mfma_f32_16x16x32_bf16 v[20:23], v[174:177], v[206:209], 0
	v_mfma_f32_16x16x32_bf16 v[16:19], v[182:185], v[206:209], 0
	v_mfma_f32_16x16x32_bf16 v[4:7], v[174:177], v[214:217], 0
	v_mfma_f32_16x16x32_bf16 v[0:3], v[182:185], v[214:217], 0
	v_mfma_f32_16x16x32_bf16 v[52:55], v[178:181], v[194:197], v[52:55]
	v_mfma_f32_16x16x32_bf16 v[48:51], v[186:189], v[194:197], v[48:51]
	v_mfma_f32_16x16x32_bf16 v[36:39], v[178:181], v[202:205], v[36:39]
	v_mfma_f32_16x16x32_bf16 v[32:35], v[186:189], v[202:205], v[32:35]
	v_mfma_f32_16x16x32_bf16 v[20:23], v[178:181], v[210:213], v[20:23]
	v_mfma_f32_16x16x32_bf16 v[16:19], v[186:189], v[210:213], v[16:19]
	v_mfma_f32_16x16x32_bf16 v[4:7], v[178:181], v[218:221], v[4:7]
	v_mfma_f32_16x16x32_bf16 v[0:3], v[186:189], v[218:221], v[0:3]
	s_setprio 0
	s_barrier
	s_branch .Lkmid_P12

; #define PG8_STAGE(bufoff, gbase, voff) do { _Pragma("unroll") for (int _i = 0; _i < 2; ++_i) \
;         __builtin_amdgcn_global_load_lds((const unsigned*)((const char*)(gbase) + (voff)[_i]), (PG8_LAS unsigned*)(lds + (bufoff) + ldsw + _i * 8192), 16, 0, PG8_LOAD_AUX); } while (0)
; #define PG8_LDA(dst, b, h) do { _Pragma("unroll") for (int m = 0; m < 4; ++m) _Pragma("unroll") for (int k = 0; k < 2; ++k) dst[m][k] = *(const PG8_LAS bf16x8*)(lds + PG8_SA(b, h) + aoff + m * 2048 + k * 1024); } while (0)
; #define PG8_LDB(dst, b, h) do { _Pragma("unroll") for (int n = 0; n < 2; ++n) _Pragma("unroll") for (int k = 0; k < 2; ++k) dst[n][k] = *(const PG8_LAS bf16x8*)(lds + PG8_SB(b, h) + boff + n * 2048 + k * 1024); } while (0)
; #define PG8_MMA(ai, bj, At, Bt) do { __builtin_amdgcn_s_setprio(1); _Pragma("unroll") for (int m = 0; m < 4; ++m) _Pragma("unroll") for (int n = 0; n < 2; ++n) _Pragma("unroll") for (int k = 0; k < 2; ++k) \
;         acc[ai][bj][m][n] = __builtin_amdgcn_mfma_f32_16x16x32_bf16(Bt[n][k], At[m][k], acc[ai][bj][m][n], 0, 0, 0); __builtin_amdgcn_s_setprio(0); } while (0)
; #define PG8_WAIT_V(n) asm volatile("s_waitcnt vmcnt(" #n ")" ::: "memory")
; #define PG8_WAIT_L(n) asm volatile("s_waitcnt lgkmcnt(" #n ")" ::: "memory")
; #define PG8_BAR __builtin_amdgcn_s_barrier()
; #define PG8_SCHED __builtin_amdgcn_sched_barrier(0)
; template <class Epi, class Sched, bool ALIGN_EPI = false, bool SP2 = false>
; __device__ __forceinline__ void gemm_phase(PG8_LAS unsigned char* lds, const Gemm g, const Sched& S, const Epi& E) {
;     ...
;             PG8_LDB(B0, 1, 0); PG8_LDB(B1, 1, 1); PG8_SCHED; PG8_LDA(At, 1, 0); PG8_STAGE(PG8_SA(0, 1), a2 + hstepA, voffA);
;             PG8_WAIT_V(8); PG8_WAIT_L(0); PG8_BAR; PG8_MMA(0, 0, At, B0); PG8_MMA(0, 1, At, B1); PG8_BAR; PG8_SCHED;
.Lkmid_P12:
	s_add_i32 s29, 0, 0x18000
	s_add_i32 s33, 0, 0x1c000
	v_add_u32_e32 v170, s29, v155
	v_add_u32_e32 v186, s33, v155
	ds_read_b128 v[146:149], v170
	ds_read_b128 v[162:165], v170 offset:1024
	ds_read_b128 v[166:169], v170 offset:2048
	ds_read_b128 v[170:173], v170 offset:3072
	ds_read_b128 v[174:177], v186
	ds_read_b128 v[178:181], v186 offset:1024
	ds_read_b128 v[182:185], v186 offset:2048
	ds_read_b128 v[186:189], v186 offset:3072
	s_add_u32 s30, s34, 0x40000
	s_addc_u32 s31, s35, 0
	s_mov_b32 m0, s47
	v_lshl_add_u64 v[228:229], s[30:31], 0, v[134:135]
	ds_read_b128 v[190:193], v159 offset:32768
	ds_read_b128 v[194:197], v159 offset:33792
	ds_read_b128 v[198:201], v159 offset:34816
	ds_read_b128 v[202:205], v159 offset:35840
	ds_read_b128 v[206:209], v159 offset:36864
	ds_read_b128 v[210:213], v159 offset:37888
	ds_read_b128 v[214:217], v159 offset:38912
	ds_read_b128 v[218:221], v159 offset:39936
	global_load_lds_dwordx4 v[228:229], off
	v_lshl_add_u64 v[228:229], s[30:31], 0, v[130:131]
	s_mov_b32 m0, s48
	s_nop 0
	global_load_lds_dwordx4 v[228:229], off
	s_waitcnt vmcnt(8)
	s_waitcnt lgkmcnt(0)
	s_barrier
	s_setprio 1
	s_waitcnt lgkmcnt(0)
	v_mfma_f32_16x16x32_bf16 v[124:127], v[146:149], v[190:193], v[124:127]
	v_mfma_f32_16x16x32_bf16 v[120:123], v[166:169], v[190:193], v[120:123]
	v_mfma_f32_16x16x32_bf16 v[108:111], v[146:149], v[198:201], v[108:111]
	v_mfma_f32_16x16x32_bf16 v[104:107], v[166:169], v[198:201], v[104:107]
	v_mfma_f32_16x16x32_bf16 v[92:95], v[146:149], v[206:209], v[92:95]
	v_mfma_f32_16x16x32_bf16 v[88:91], v[166:169], v[206:209], v[88:91]
	v_mfma_f32_16x16x32_bf16 v[76:79], v[146:149], v[214:217], v[76:79]
	v_mfma_f32_16x16x32_bf16 v[72:75], v[166:169], v[214:217], v[72:75]
	v_mfma_f32_16x16x32_bf16 v[124:127], v[162:165], v[194:197], v[124:127]
	v_mfma_f32_16x16x32_bf16 v[120:123], v[170:173], v[194:197], v[120:123]
	v_mfma_f32_16x16x32_bf16 v[108:111], v[162:165], v[202:205], v[108:111]
	v_mfma_f32_16x16x32_bf16 v[104:107], v[170:173], v[202:205], v[104:107]
	v_mfma_f32_16x16x32_bf16 v[92:95], v[162:165], v[210:213], v[92:95]
	v_mfma_f32_16x16x32_bf16 v[88:91], v[170:173], v[210:213], v[88:91]
	v_mfma_f32_16x16x32_bf16 v[76:79], v[162:165], v[218:221], v[76:79]
	v_mfma_f32_16x16x32_bf16 v[72:75], v[170:173], v[218:221], v[72:75]
	s_setprio 0
	s_setprio 1
	v_mfma_f32_16x16x32_bf16 v[116:119], v[174:177], v[190:193], v[116:119]
	v_mfma_f32_16x16x32_bf16 v[112:115], v[182:185], v[190:193], v[112:115]
	v_mfma_f32_16x16x32_bf16 v[100:103], v[174:177], v[198:201], v[100:103]
	v_mfma_f32_16x16x32_bf16 v[96:99], v[182:185], v[198:201], v[96:99]
	v_mfma_f32_16x16x32_bf16 v[84:87], v[174:177], v[206:209], v[84:87]
	v_mfma_f32_16x16x32_bf16 v[80:83], v[182:185], v[206:209], v[80:83]
	v_mfma_f32_16x16x32_bf16 v[68:71], v[174:177], v[214:217], v[68:71]
	v_mfma_f32_16x16x32_bf16 v[64:67], v[182:185], v[214:217], v[64:67]
	v_mfma_f32_16x16x32_bf16 v[116:119], v[178:181], v[194:197], v[116:119]
	v_mfma_f32_16x16x32_bf16 v[112:115], v[186:189], v[194:197], v[112:115]
	v_mfma_f32_16x16x32_bf16 v[100:103], v[178:181], v[202:205], v[100:103]
	v_mfma_f32_16x16x32_bf16 v[96:99], v[186:189], v[202:205], v[96:99]
	v_mfma_f32_16x16x32_bf16 v[84:87], v[178:181], v[210:213], v[84:87]
	v_mfma_f32_16x16x32_bf16 v[80:83], v[186:189], v[210:213], v[80:83]
	v_mfma_f32_16x16x32_bf16 v[68:71], v[178:181], v[218:221], v[68:71]
	v_mfma_f32_16x16x32_bf16 v[64:67], v[186:189], v[218:221], v[64:67]
	s_setprio 0
	s_barrier
; #define PG8_STAGE(bufoff, gbase, voff) do { _Pragma("unroll") for (int _i = 0; _i < 2; ++_i) \
;         __builtin_amdgcn_global_load_lds((const unsigned*)((const char*)(gbase) + (voff)[_i]), (PG8_LAS unsigned*)(lds + (bufoff) + ldsw + _i * 8192), 16, 0, PG8_LOAD_AUX); } while (0)
; #define PG8_LDA(dst, b, h) do { _Pragma("unroll") for (int m = 0; m < 4; ++m) _Pragma("unroll") for (int k = 0; k < 2; ++k) dst[m][k] = *(const PG8_LAS bf16x8*)(lds + PG8_SA(b, h) + aoff + m * 2048 + k * 1024); } while (0)
; #define PG8_MMA(ai, bj, At, Bt) do { __builtin_amdgcn_s_setprio(1); _Pragma("unroll") for (int m = 0; m < 4; ++m) _Pragma("unroll") for (int n = 0; n < 2; ++n) _Pragma("unroll") for (int k = 0; k < 2; ++k) \
;         acc[ai][bj][m][n] = __builtin_amdgcn_mfma_f32_16x16x32_bf16(Bt[n][k], At[m][k], acc[ai][bj][m][n], 0, 0, 0); __builtin_amdgcn_s_setprio(0); } while (0)
; #define PG8_WAIT_V(n) asm volatile("s_waitcnt vmcnt(" #n ")" ::: "memory")
; #define PG8_WAIT_L(n) asm volatile("s_waitcnt lgkmcnt(" #n ")" ::: "memory")
; #define PG8_BAR __builtin_amdgcn_s_barrier()
; #define PG8_SCHED __builtin_amdgcn_sched_barrier(0)
; template <class Epi, class Sched, bool ALIGN_EPI = false, bool SP2 = false>
; __device__ __forceinline__ void gemm_phase(PG8_LAS unsigned char* lds, const Gemm g, const Sched& S, const Epi& E) {
;     ...
;             PG8_LDA(At, 1, 1); PG8_STAGE(PG8_SB(1, 0), b3, voffB); PG8_STAGE(PG8_SB(1, 1), b3 + hstepB, voffB); PG8_STAGE(PG8_SA(1, 0), a3, voffA);
;             PG8_WAIT_V(8); PG8_WAIT_L(0); PG8_BAR; PG8_MMA(1, 0, At, B0); PG8_MMA(1, 1, At, B1); PG8_BAR; PG8_SCHED;
;     ...
;         if constexpr (ALIGN_EPI) { if (wr == 0) PG8_BAR; }
;         if constexpr (!Epi::AFTER_DRAIN) { E(acc, cur, wr, wc, fr, fq); S.done(cur); }
	s_add_i32 s29, s29, s42
	v_lshl_add_u64 v[150:151], v[150:151], 0, s[8:9]
	s_mov_b32 m0, s29
	ds_read_b128 v[190:193], v159 offset:49152
	ds_read_b128 v[194:197], v159 offset:50176
	ds_read_b128 v[198:201], v159 offset:51200
	ds_read_b128 v[202:205], v159 offset:52224
	ds_read_b128 v[206:209], v159 offset:53248
	ds_read_b128 v[210:213], v159 offset:54272
	ds_read_b128 v[214:217], v159 offset:55296
	ds_read_b128 v[218:221], v159 offset:56320
	global_load_lds_dwordx4 v[150:151], off
	s_add_i32 m0, s29, 0x2000
	s_add_u32 s22, s22, 0x40080
	v_lshl_add_u64 v[150:151], v[222:223], 0, s[8:9]
	s_addc_u32 s23, s23, 0
	s_add_i32 s29, s33, s42
	global_load_lds_dwordx4 v[150:151], off
	v_lshl_add_u64 v[150:151], s[22:23], 0, v[132:133]
	s_mov_b32 m0, s29
	s_nop 0
	global_load_lds_dwordx4 v[150:151], off
	v_lshl_add_u64 v[150:151], s[22:23], 0, v[128:129]
	s_add_i32 m0, s29, 0x2000
	s_nop 0
	global_load_lds_dwordx4 v[150:151], off
	v_lshl_add_u64 v[150:151], v[224:225], 0, s[8:9]
	s_mov_b32 m0, s50
	s_nop 0
	global_load_lds_dwordx4 v[150:151], off
	v_lshl_add_u64 v[150:151], v[226:227], 0, s[8:9]
	s_mov_b32 m0, s51
	s_nop 0
	global_load_lds_dwordx4 v[150:151], off
	s_waitcnt vmcnt(8)
	s_waitcnt lgkmcnt(0)
	s_barrier
	s_setprio 1
	s_waitcnt lgkmcnt(0)
	v_mfma_f32_16x16x32_bf16 v[60:63], v[146:149], v[190:193], v[60:63]
	v_mfma_f32_16x16x32_bf16 v[56:59], v[166:169], v[190:193], v[56:59]
	v_mfma_f32_16x16x32_bf16 v[44:47], v[146:149], v[198:201], v[44:47]
	v_mfma_f32_16x16x32_bf16 v[40:43], v[166:169], v[198:201], v[40:43]
	v_mfma_f32_16x16x32_bf16 v[28:31], v[146:149], v[206:209], v[28:31]
	v_mfma_f32_16x16x32_bf16 v[24:27], v[166:169], v[206:209], v[24:27]
	v_mfma_f32_16x16x32_bf16 v[12:15], v[146:149], v[214:217], v[12:15]
	v_mfma_f32_16x16x32_bf16 v[8:11], v[166:169], v[214:217], v[8:11]
	v_mfma_f32_16x16x32_bf16 v[60:63], v[162:165], v[194:197], v[60:63]
	v_mfma_f32_16x16x32_bf16 v[56:59], v[170:173], v[194:197], v[56:59]
	v_mfma_f32_16x16x32_bf16 v[44:47], v[162:165], v[202:205], v[44:47]
	v_mfma_f32_16x16x32_bf16 v[40:43], v[170:173], v[202:205], v[40:43]
	v_mfma_f32_16x16x32_bf16 v[28:31], v[162:165], v[210:213], v[28:31]
	v_mfma_f32_16x16x32_bf16 v[24:27], v[170:173], v[210:213], v[24:27]
	v_mfma_f32_16x16x32_bf16 v[12:15], v[162:165], v[218:221], v[12:15]
	v_mfma_f32_16x16x32_bf16 v[8:11], v[170:173], v[218:221], v[8:11]
	s_setprio 0
	s_setprio 1
	v_mfma_f32_16x16x32_bf16 v[52:55], v[174:177], v[190:193], v[52:55]
	v_mfma_f32_16x16x32_bf16 v[48:51], v[182:185], v[190:193], v[48:51]
	v_mfma_f32_16x16x32_bf16 v[36:39], v[174:177], v[198:201], v[36:39]
	v_mfma_f32_16x16x32_bf16 v[32:35], v[182:185], v[198:201], v[32:35]
	v_mfma_f32_16x16x32_bf16 v[20:23], v[174:177], v[206:209], v[20:23]
	v_mfma_f32_16x16x32_bf16 v[16:19], v[182:185], v[206:209], v[16:19]
	v_mfma_f32_16x16x32_bf16 v[4:7], v[174:177], v[214:217], v[4:7]
	v_mfma_f32_16x16x32_bf16 v[0:3], v[182:185], v[214:217], v[0:3]
	v_mfma_f32_16x16x32_bf16 v[52:55], v[178:181], v[194:197], v[52:55]
	v_mfma_f32_16x16x32_bf16 v[48:51], v[186:189], v[194:197], v[48:51]
	v_mfma_f32_16x16x32_bf16 v[36:39], v[178:181], v[202:205], v[36:39]
	v_mfma_f32_16x16x32_bf16 v[32:35], v[186:189], v[202:205], v[32:35]
	v_mfma_f32_16x16x32_bf16 v[20:23], v[178:181], v[210:213], v[20:23]
	v_mfma_f32_16x16x32_bf16 v[16:19], v[186:189], v[210:213], v[16:19]
	v_mfma_f32_16x16x32_bf16 v[4:7], v[178:181], v[218:221], v[4:7]
	v_mfma_f32_16x16x32_bf16 v[0:3], v[186:189], v[218:221], v[0:3]
	s_setprio 0
	s_barrier
	s_add_i32 s28, s28, 2
	s_add_u32 s20, s20, 0x100
	s_addc_u32 s21, s21, 0
	s_add_u32 s26, s26, 0x100
	s_addc_u32 s27, s27, 0
	s_cmp_gt_u32 s28, 13
	s_cbranch_scc0 .LBB0_1111
	v_lshl_add_u32 v204, s0, 8, v152
	v_ashrrev_i32_e32 v205, 31, v204
	v_lshlrev_b64 v[204:205], 6, v[204:205]
	v_lshl_add_u64 v[204:205], v[136:137], 0, v[204:205]
	v_add_co_u32_e32 v206, vcc, 0x2000, v204
	s_nop 1
	v_addc_co_u32_e32 v207, vcc, 0, v205, vcc
	global_load_dwordx4 v[172:175], v[204:205], off
	global_load_dwordx4 v[176:179], v[204:205], off offset:1024
	global_load_dwordx4 v[180:183], v[204:205], off offset:2048
	global_load_dwordx4 v[184:187], v[204:205], off offset:3072
	global_load_dwordx4 v[188:191], v[206:207], off
	global_load_dwordx4 v[192:195], v[206:207], off offset:1024
	global_load_dwordx4 v[196:199], v[206:207], off offset:2048
	global_load_dwordx4 v[200:203], v[206:207], off offset:3072
	s_and_b64 vcc, exec, s[12:13]
	s_cbranch_vccz .LBB0_1114
	s_barrier

; #define PG8_STAGE(bufoff, gbase, voff) do { _Pragma("unroll") for (int _i = 0; _i < 2; ++_i) \
;         __builtin_amdgcn_global_load_lds((const unsigned*)((const char*)(gbase) + (voff)[_i]), (PG8_LAS unsigned*)(lds + (bufoff) + ldsw + _i * 8192), 16, 0, PG8_LOAD_AUX); } while (0)
; #define PG8_LDA(dst, b, h) do { _Pragma("unroll") for (int m = 0; m < 4; ++m) _Pragma("unroll") for (int k = 0; k < 2; ++k) dst[m][k] = *(const PG8_LAS bf16x8*)(lds + PG8_SA(b, h) + aoff + m * 2048 + k * 1024); } while (0)
; #define PG8_LDB(dst, b, h) do { _Pragma("unroll") for (int n = 0; n < 2; ++n) _Pragma("unroll") for (int k = 0; k < 2; ++k) dst[n][k] = *(const PG8_LAS bf16x8*)(lds + PG8_SB(b, h) + boff + n * 2048 + k * 1024); } while (0)
; #define PG8_WAIT_V(n) asm volatile("s_waitcnt vmcnt(" #n ")" ::: "memory")
; #define PG8_WAIT_L(n) asm volatile("s_waitcnt lgkmcnt(" #n ")" ::: "memory")
; #define PG8_BAR __builtin_amdgcn_s_barrier()
; #define PG8_SCHED __builtin_amdgcn_sched_barrier(0)
; template <class Epi, class Sched, bool ALIGN_EPI = false, bool SP2 = false>
; __device__ __forceinline__ void gemm_phase(PG8_LAS unsigned char* lds, const Gemm g, const Sched& S, const Epi& E) {
;     ...
;         const bool has_next = S.next(ui + 1, nxt);
;         const char* nA = has_next ? (const char*)g.A + (size_t)nxt.pm * tstepA + (size_t)nxt.pn * apn : cA; const char* nB = has_next ? (const char*)g.Bt + (size_t)nxt.pn * tstepB : cB;
;         for (int t = 0; t < nt; t += 2) {
;             const bool last = (t == nt - 2);
;             const char* a1 = cA + (size_t)(t + 1) * kstep;
;             const char* a2 = last ? nA : cA + (size_t)(t + 2) * kstep; const char* b2 = last ? nB : cB + (size_t)(t + 2) * kstep;
;             const char* a3 = a2 + kstep; const char* b3 = b2 + kstep;
;             if (last && has_next) S.a_ready(nxt);
;             if constexpr (SP2) {
;             PG8_LDB(B0, 0, 0); PG8_LDB(B1, 0, 1); PG8_SCHED; PG8_LDA(At, 0, 0); PG8_STAGE(PG8_SA(1, 1), a1 + hstepA, voffA);
;             PG8_WAIT_V(8); PG8_WAIT_L(0); PG8_BAR; PG8_MMA(0, 0, At, B0); PG8_MMA(0, 1, At, B1); PG8_BAR; PG8_SCHED;
;             PG8_LDA(At, 0, 1); PG8_STAGE(PG8_SB(0, 0), b2, voffB); PG8_STAGE(PG8_SB(0, 1), b2 + hstepB, voffB); PG8_STAGE(PG8_SA(0, 0), a2, voffA);
;             PG8_WAIT_V(8); PG8_WAIT_L(0); PG8_BAR; PG8_MMA(1, 0, At, B0); PG8_MMA(1, 1, At, B1); PG8_BAR; PG8_SCHED;
.LBB0_1195:
	s_add_u32 s0, s0, 0xb0080
	s_addc_u32 s1, s1, 0
	s_add_u32 s25, s20, 0x100
	s_addc_u32 s26, s21, 0
	s_mov_b32 s27, -2
	s_waitcnt lgkmcnt(0)
	ds_read_b128 v[146:149], v155
	ds_read_b128 v[160:163], v155 offset:1024
	ds_read_b128 v[164:167], v155 offset:2048
	ds_read_b128 v[168:171], v155 offset:3072
	ds_read_b128 v[172:175], v156
	ds_read_b128 v[176:179], v156 offset:1024
	ds_read_b128 v[180:183], v156 offset:2048
	ds_read_b128 v[184:187], v156 offset:3072
	s_add_u32 s20, s0, 0xfff50080
	s_addc_u32 s21, s1, -1
	s_cmp_eq_u32 s27, 40
	s_cselect_b32 s23, s9, s21
	s_cselect_b32 s22, s8, s20
	s_cselect_b32 s21, s41, s26
	s_cselect_b32 s20, s40, s25
	v_lshl_add_u64 v[220:221], s[0:1], 0, v[138:139]
	s_add_i32 m0, s43, 0xc000
	ds_read_b128 v[188:191], v157
	ds_read_b128 v[192:195], v157 offset:1024
	ds_read_b128 v[196:199], v157 offset:2048
	ds_read_b128 v[200:203], v157 offset:3072
	ds_read_b128 v[204:207], v157 offset:4096
	ds_read_b128 v[208:211], v157 offset:5120
	ds_read_b128 v[212:215], v157 offset:6144
	ds_read_b128 v[216:219], v157 offset:7168
	global_load_lds_dwordx4 v[220:221], off
	v_lshl_add_u64 v[220:221], s[0:1], 0, v[140:141]
	s_add_i32 m0, s43, 0xe000
	s_nop 0
	global_load_lds_dwordx4 v[220:221], off
	s_waitcnt vmcnt(8)
	s_waitcnt lgkmcnt(0)
	s_barrier
	s_setprio 1
	s_waitcnt lgkmcnt(0)
	v_mfma_f32_16x16x32_bf16 v[124:127], v[146:149], v[188:191], 0
	v_mfma_f32_16x16x32_bf16 v[120:123], v[164:167], v[188:191], 0
	v_mfma_f32_16x16x32_bf16 v[108:111], v[146:149], v[196:199], 0
	v_mfma_f32_16x16x32_bf16 v[104:107], v[164:167], v[196:199], 0
	v_mfma_f32_16x16x32_bf16 v[92:95], v[146:149], v[204:207], 0
	v_mfma_f32_16x16x32_bf16 v[88:91], v[164:167], v[204:207], 0
	v_mfma_f32_16x16x32_bf16 v[76:79], v[146:149], v[212:215], 0
	v_mfma_f32_16x16x32_bf16 v[72:75], v[164:167], v[212:215], 0
	v_mfma_f32_16x16x32_bf16 v[124:127], v[160:163], v[192:195], v[124:127]
	v_mfma_f32_16x16x32_bf16 v[120:123], v[168:171], v[192:195], v[120:123]
	v_mfma_f32_16x16x32_bf16 v[108:111], v[160:163], v[200:203], v[108:111]
	v_mfma_f32_16x16x32_bf16 v[104:107], v[168:171], v[200:203], v[104:107]
	v_mfma_f32_16x16x32_bf16 v[92:95], v[160:163], v[208:211], v[92:95]
	v_mfma_f32_16x16x32_bf16 v[88:91], v[168:171], v[208:211], v[88:91]
	v_mfma_f32_16x16x32_bf16 v[76:79], v[160:163], v[216:219], v[76:79]
	v_mfma_f32_16x16x32_bf16 v[72:75], v[168:171], v[216:219], v[72:75]
	s_setprio 0
	s_setprio 1
	v_mfma_f32_16x16x32_bf16 v[116:119], v[172:175], v[188:191], 0
	v_mfma_f32_16x16x32_bf16 v[112:115], v[180:183], v[188:191], 0
	v_mfma_f32_16x16x32_bf16 v[100:103], v[172:175], v[196:199], 0
	v_mfma_f32_16x16x32_bf16 v[96:99], v[180:183], v[196:199], 0
	v_mfma_f32_16x16x32_bf16 v[84:87], v[172:175], v[204:207], 0
	v_mfma_f32_16x16x32_bf16 v[80:83], v[180:183], v[204:207], 0
	v_mfma_f32_16x16x32_bf16 v[68:71], v[172:175], v[212:215], 0
	v_mfma_f32_16x16x32_bf16 v[64:67], v[180:183], v[212:215], 0
	v_mfma_f32_16x16x32_bf16 v[116:119], v[176:179], v[192:195], v[116:119]
	v_mfma_f32_16x16x32_bf16 v[112:115], v[184:187], v[192:195], v[112:115]
	v_mfma_f32_16x16x32_bf16 v[100:103], v[176:179], v[200:203], v[100:103]
	v_mfma_f32_16x16x32_bf16 v[96:99], v[184:187], v[200:203], v[96:99]
	v_mfma_f32_16x16x32_bf16 v[84:87], v[176:179], v[208:211], v[84:87]
	v_mfma_f32_16x16x32_bf16 v[80:83], v[184:187], v[208:211], v[80:83]
	v_mfma_f32_16x16x32_bf16 v[68:71], v[176:179], v[216:219], v[68:71]
	v_mfma_f32_16x16x32_bf16 v[64:67], v[184:187], v[216:219], v[64:67]
	s_setprio 0
	s_barrier
	s_add_i32 s28, s55, s42
	v_lshl_add_u64 v[220:221], s[20:21], 0, v[130:131]
	s_mov_b32 m0, s28
	ds_read_b128 v[188:191], v157 offset:16384
	ds_read_b128 v[192:195], v157 offset:17408
	ds_read_b128 v[196:199], v157 offset:18432
	ds_read_b128 v[200:203], v157 offset:19456
	ds_read_b128 v[204:207], v157 offset:20480
	ds_read_b128 v[208:211], v157 offset:21504
	ds_read_b128 v[212:215], v157 offset:22528
	ds_read_b128 v[216:219], v157 offset:23552
	global_load_lds_dwordx4 v[220:221], off
	s_add_i32 m0, s28, 0x2000
	s_add_u32 s28, s20, 0x2c000
	v_lshl_add_u64 v[222:223], s[20:21], 0, v[134:135]
	s_addc_u32 s29, s21, 0
	s_add_i32 s30, s56, s42
	global_load_lds_dwordx4 v[222:223], off
	v_lshl_add_u64 v[224:225], s[28:29], 0, v[130:131]
	s_mov_b32 m0, s30
	v_lshl_add_u64 v[226:227], s[22:23], 0, v[132:133]
	global_load_lds_dwordx4 v[224:225], off
	v_lshl_add_u64 v[224:225], s[28:29], 0, v[134:135]
	s_add_i32 m0, s30, 0x2000
	s_nop 0
	global_load_lds_dwordx4 v[224:225], off
	v_lshl_add_u64 v[224:225], s[22:23], 0, v[128:129]
	s_mov_b32 m0, s43
	s_nop 0
	global_load_lds_dwordx4 v[224:225], off
	s_mov_b32 m0, s44
	s_nop 0
	global_load_lds_dwordx4 v[226:227], off
	s_waitcnt vmcnt(8)
	s_waitcnt lgkmcnt(0)
	s_barrier
	s_setprio 1
	s_waitcnt lgkmcnt(0)
	v_mfma_f32_16x16x32_bf16 v[60:63], v[146:149], v[188:191], 0
	v_mfma_f32_16x16x32_bf16 v[56:59], v[164:167], v[188:191], 0
	v_mfma_f32_16x16x32_bf16 v[44:47], v[146:149], v[196:199], 0
	v_mfma_f32_16x16x32_bf16 v[40:43], v[164:167], v[196:199], 0
	v_mfma_f32_16x16x32_bf16 v[28:31], v[146:149], v[204:207], 0
	v_mfma_f32_16x16x32_bf16 v[24:27], v[164:167], v[204:207], 0
	v_mfma_f32_16x16x32_bf16 v[12:15], v[146:149], v[212:215], 0
	v_mfma_f32_16x16x32_bf16 v[8:11], v[164:167], v[212:215], 0
	v_mfma_f32_16x16x32_bf16 v[60:63], v[160:163], v[192:195], v[60:63]
	v_mfma_f32_16x16x32_bf16 v[56:59], v[168:171], v[192:195], v[56:59]
	v_mfma_f32_16x16x32_bf16 v[44:47], v[160:163], v[200:203], v[44:47]
	v_mfma_f32_16x16x32_bf16 v[40:43], v[168:171], v[200:203], v[40:43]
	v_mfma_f32_16x16x32_bf16 v[28:31], v[160:163], v[208:211], v[28:31]
	v_mfma_f32_16x16x32_bf16 v[24:27], v[168:171], v[208:211], v[24:27]
	v_mfma_f32_16x16x32_bf16 v[12:15], v[160:163], v[216:219], v[12:15]
	v_mfma_f32_16x16x32_bf16 v[8:11], v[168:171], v[216:219], v[8:11]
	s_setprio 0
	s_setprio 1
	v_mfma_f32_16x16x32_bf16 v[52:55], v[172:175], v[188:191], 0
	v_mfma_f32_16x16x32_bf16 v[48:51], v[180:183], v[188:191], 0
	v_mfma_f32_16x16x32_bf16 v[36:39], v[172:175], v[196:199], 0
	v_mfma_f32_16x16x32_bf16 v[32:35], v[180:183], v[196:199], 0
	v_mfma_f32_16x16x32_bf16 v[20:23], v[172:175], v[204:207], 0
	v_mfma_f32_16x16x32_bf16 v[16:19], v[180:183], v[204:207], 0
	v_mfma_f32_16x16x32_bf16 v[4:7], v[172:175], v[212:215], 0
	v_mfma_f32_16x16x32_bf16 v[0:3], v[180:183], v[212:215], 0
	v_mfma_f32_16x16x32_bf16 v[52:55], v[176:179], v[192:195], v[52:55]
	v_mfma_f32_16x16x32_bf16 v[48:51], v[184:187], v[192:195], v[48:51]
	v_mfma_f32_16x16x32_bf16 v[36:39], v[176:179], v[200:203], v[36:39]
	v_mfma_f32_16x16x32_bf16 v[32:35], v[184:187], v[200:203], v[32:35]
	v_mfma_f32_16x16x32_bf16 v[20:23], v[176:179], v[208:211], v[20:23]
	v_mfma_f32_16x16x32_bf16 v[16:19], v[184:187], v[208:211], v[16:19]
	v_mfma_f32_16x16x32_bf16 v[4:7], v[176:179], v[216:219], v[4:7]
	v_mfma_f32_16x16x32_bf16 v[0:3], v[184:187], v[216:219], v[0:3]
	s_setprio 0
	s_barrier
	s_branch .Lkmid_P13

; #define PG8_STAGE(bufoff, gbase, voff) do { _Pragma("unroll") for (int _i = 0; _i < 2; ++_i) \
;         __builtin_amdgcn_global_load_lds((const unsigned*)((const char*)(gbase) + (voff)[_i]), (PG8_LAS unsigned*)(lds + (bufoff) + ldsw + _i * 8192), 16, 0, PG8_LOAD_AUX); } while (0)
; #define PG8_LDA(dst, b, h) do { _Pragma("unroll") for (int m = 0; m < 4; ++m) _Pragma("unroll") for (int k = 0; k < 2; ++k) dst[m][k] = *(const PG8_LAS bf16x8*)(lds + PG8_SA(b, h) + aoff + m * 2048 + k * 1024); } while (0)
; #define PG8_LDB(dst, b, h) do { _Pragma("unroll") for (int n = 0; n < 2; ++n) _Pragma("unroll") for (int k = 0; k < 2; ++k) dst[n][k] = *(const PG8_LAS bf16x8*)(lds + PG8_SB(b, h) + boff + n * 2048 + k * 1024); } while (0)
; #define PG8_MMA(ai, bj, At, Bt) do { __builtin_amdgcn_s_setprio(1); _Pragma("unroll") for (int m = 0; m < 4; ++m) _Pragma("unroll") for (int n = 0; n < 2; ++n) _Pragma("unroll") for (int k = 0; k < 2; ++k) \
;         acc[ai][bj][m][n] = __builtin_amdgcn_mfma_f32_16x16x32_bf16(Bt[n][k], At[m][k], acc[ai][bj][m][n], 0, 0, 0); __builtin_amdgcn_s_setprio(0); } while (0)
; #define PG8_WAIT_V(n) asm volatile("s_waitcnt vmcnt(" #n ")" ::: "memory")
; #define PG8_WAIT_L(n) asm volatile("s_waitcnt lgkmcnt(" #n ")" ::: "memory")
; #define PG8_BAR __builtin_amdgcn_s_barrier()
; #define PG8_SCHED __builtin_amdgcn_sched_barrier(0)
; template <class Epi, class Sched, bool ALIGN_EPI = false, bool SP2 = false>
; __device__ __forceinline__ void gemm_phase(PG8_LAS unsigned char* lds, const Gemm g, const Sched& S, const Epi& E) {
;     ...
;             PG8_LDB(B0, 1, 0); PG8_LDB(B1, 1, 1); PG8_SCHED; PG8_LDA(At, 1, 0); PG8_STAGE(PG8_SA(0, 1), a2 + hstepA, voffA);
;             PG8_WAIT_V(8); PG8_WAIT_L(0); PG8_BAR; PG8_MMA(0, 0, At, B0); PG8_MMA(0, 1, At, B1); PG8_BAR; PG8_SCHED;
.Lkmid_P13:
	s_add_i32 s28, 0, 0x18000
	v_add_u32_e32 v159, s28, v151
	s_add_i32 s29, 0, 0x1c000
	ds_read_b128 v[146:149], v159
	ds_read_b128 v[160:163], v159 offset:1024
	ds_read_b128 v[164:167], v159 offset:2048
	ds_read_b128 v[168:171], v159 offset:3072
	v_add_u32_e32 v159, s29, v151
	ds_read_b128 v[172:175], v159
	ds_read_b128 v[176:179], v159 offset:1024
	ds_read_b128 v[180:183], v159 offset:2048
	ds_read_b128 v[184:187], v159 offset:3072
	s_add_u32 s22, s22, 0xb0000
	s_addc_u32 s23, s23, 0
	s_mov_b32 m0, s45
	v_lshl_add_u64 v[228:229], s[22:23], 0, v[128:129]
	ds_read_b128 v[188:191], v157 offset:32768
	ds_read_b128 v[192:195], v157 offset:33792
	ds_read_b128 v[196:199], v157 offset:34816
	ds_read_b128 v[200:203], v157 offset:35840
	ds_read_b128 v[204:207], v157 offset:36864
	ds_read_b128 v[208:211], v157 offset:37888
	ds_read_b128 v[212:215], v157 offset:38912
	ds_read_b128 v[216:219], v157 offset:39936
	global_load_lds_dwordx4 v[228:229], off
	v_lshl_add_u64 v[228:229], s[22:23], 0, v[132:133]
	s_mov_b32 m0, s46
	s_nop 0
	global_load_lds_dwordx4 v[228:229], off
	s_waitcnt vmcnt(8)
	s_waitcnt lgkmcnt(0)
	s_barrier
	s_setprio 1
	s_waitcnt lgkmcnt(0)
	v_mfma_f32_16x16x32_bf16 v[124:127], v[146:149], v[188:191], v[124:127]
	v_mfma_f32_16x16x32_bf16 v[120:123], v[164:167], v[188:191], v[120:123]
	v_mfma_f32_16x16x32_bf16 v[108:111], v[146:149], v[196:199], v[108:111]
	v_mfma_f32_16x16x32_bf16 v[104:107], v[164:167], v[196:199], v[104:107]
	v_mfma_f32_16x16x32_bf16 v[92:95], v[146:149], v[204:207], v[92:95]
	v_mfma_f32_16x16x32_bf16 v[88:91], v[164:167], v[204:207], v[88:91]
	v_mfma_f32_16x16x32_bf16 v[76:79], v[146:149], v[212:215], v[76:79]
	v_mfma_f32_16x16x32_bf16 v[72:75], v[164:167], v[212:215], v[72:75]
	v_mfma_f32_16x16x32_bf16 v[124:127], v[160:163], v[192:195], v[124:127]
	v_mfma_f32_16x16x32_bf16 v[120:123], v[168:171], v[192:195], v[120:123]
	v_mfma_f32_16x16x32_bf16 v[108:111], v[160:163], v[200:203], v[108:111]
	v_mfma_f32_16x16x32_bf16 v[104:107], v[168:171], v[200:203], v[104:107]
	v_mfma_f32_16x16x32_bf16 v[92:95], v[160:163], v[208:211], v[92:95]
	v_mfma_f32_16x16x32_bf16 v[88:91], v[168:171], v[208:211], v[88:91]
	v_mfma_f32_16x16x32_bf16 v[76:79], v[160:163], v[216:219], v[76:79]
	v_mfma_f32_16x16x32_bf16 v[72:75], v[168:171], v[216:219], v[72:75]
	s_setprio 0
	s_setprio 1
	v_mfma_f32_16x16x32_bf16 v[116:119], v[172:175], v[188:191], v[116:119]
	v_mfma_f32_16x16x32_bf16 v[112:115], v[180:183], v[188:191], v[112:115]
	v_mfma_f32_16x16x32_bf16 v[100:103], v[172:175], v[196:199], v[100:103]
	v_mfma_f32_16x16x32_bf16 v[96:99], v[180:183], v[196:199], v[96:99]
	v_mfma_f32_16x16x32_bf16 v[84:87], v[172:175], v[204:207], v[84:87]
	v_mfma_f32_16x16x32_bf16 v[80:83], v[180:183], v[204:207], v[80:83]
	v_mfma_f32_16x16x32_bf16 v[68:71], v[172:175], v[212:215], v[68:71]
	v_mfma_f32_16x16x32_bf16 v[64:67], v[180:183], v[212:215], v[64:67]
	v_mfma_f32_16x16x32_bf16 v[116:119], v[176:179], v[192:195], v[116:119]
	v_mfma_f32_16x16x32_bf16 v[112:115], v[184:187], v[192:195], v[112:115]
	v_mfma_f32_16x16x32_bf16 v[100:103], v[176:179], v[200:203], v[100:103]
	v_mfma_f32_16x16x32_bf16 v[96:99], v[184:187], v[200:203], v[96:99]
	v_mfma_f32_16x16x32_bf16 v[84:87], v[176:179], v[208:211], v[84:87]
	v_mfma_f32_16x16x32_bf16 v[80:83], v[184:187], v[208:211], v[80:83]
	v_mfma_f32_16x16x32_bf16 v[68:71], v[176:179], v[216:219], v[68:71]
	v_mfma_f32_16x16x32_bf16 v[64:67], v[184:187], v[216:219], v[64:67]
	s_setprio 0
	s_barrier
; #define PG8_STAGE(bufoff, gbase, voff) do { _Pragma("unroll") for (int _i = 0; _i < 2; ++_i) \
;         __builtin_amdgcn_global_load_lds((const unsigned*)((const char*)(gbase) + (voff)[_i]), (PG8_LAS unsigned*)(lds + (bufoff) + ldsw + _i * 8192), 16, 0, PG8_LOAD_AUX); } while (0)
; #define PG8_LDA(dst, b, h) do { _Pragma("unroll") for (int m = 0; m < 4; ++m) _Pragma("unroll") for (int k = 0; k < 2; ++k) dst[m][k] = *(const PG8_LAS bf16x8*)(lds + PG8_SA(b, h) + aoff + m * 2048 + k * 1024); } while (0)
; #define PG8_MMA(ai, bj, At, Bt) do { __builtin_amdgcn_s_setprio(1); _Pragma("unroll") for (int m = 0; m < 4; ++m) _Pragma("unroll") for (int n = 0; n < 2; ++n) _Pragma("unroll") for (int k = 0; k < 2; ++k) \
;         acc[ai][bj][m][n] = __builtin_amdgcn_mfma_f32_16x16x32_bf16(Bt[n][k], At[m][k], acc[ai][bj][m][n], 0, 0, 0); __builtin_amdgcn_s_setprio(0); } while (0)
; #define PG8_WAIT_V(n) asm volatile("s_waitcnt vmcnt(" #n ")" ::: "memory")
; #define PG8_WAIT_L(n) asm volatile("s_waitcnt lgkmcnt(" #n ")" ::: "memory")
; #define PG8_BAR __builtin_amdgcn_s_barrier()
; #define PG8_SCHED __builtin_amdgcn_sched_barrier(0)
; template <class Epi, class Sched, bool ALIGN_EPI = false, bool SP2 = false>
; __device__ __forceinline__ void gemm_phase(PG8_LAS unsigned char* lds, const Gemm g, const Sched& S, const Epi& E) {
;     ...
;             PG8_LDA(At, 1, 1); PG8_STAGE(PG8_SB(1, 0), b3, voffB); PG8_STAGE(PG8_SB(1, 1), b3 + hstepB, voffB); PG8_STAGE(PG8_SA(1, 0), a3, voffA);
;             PG8_WAIT_V(8); PG8_WAIT_L(0); PG8_BAR; PG8_MMA(1, 0, At, B0); PG8_MMA(1, 1, At, B1); PG8_BAR; PG8_SCHED;
;     ...
;         if constexpr (ALIGN_EPI) { if (wr == 0) PG8_BAR; }
	s_add_i32 s22, s28, s42
	v_lshl_add_u64 v[220:221], v[220:221], 0, s[18:19]
	s_mov_b32 m0, s22
	ds_read_b128 v[188:191], v157 offset:49152
	ds_read_b128 v[192:195], v157 offset:50176
	ds_read_b128 v[196:199], v157 offset:51200
	ds_read_b128 v[200:203], v157 offset:52224
	ds_read_b128 v[204:207], v157 offset:53248
	ds_read_b128 v[208:211], v157 offset:54272
	ds_read_b128 v[212:215], v157 offset:55296
	ds_read_b128 v[216:219], v157 offset:56320
	global_load_lds_dwordx4 v[220:221], off
	s_add_i32 m0, s22, 0x2000
	s_add_u32 s20, s20, 0x2c080
	v_lshl_add_u64 v[220:221], v[222:223], 0, s[18:19]
	s_addc_u32 s21, s21, 0
	s_add_i32 s22, s29, s42
	global_load_lds_dwordx4 v[220:221], off
	v_lshl_add_u64 v[220:221], s[20:21], 0, v[130:131]
	s_mov_b32 m0, s22
	s_nop 0
	global_load_lds_dwordx4 v[220:221], off
	v_lshl_add_u64 v[220:221], s[20:21], 0, v[134:135]
	s_add_i32 m0, s22, 0x2000
	s_nop 0
	global_load_lds_dwordx4 v[220:221], off
	v_lshl_add_u64 v[220:221], v[224:225], 0, s[18:19]
	s_mov_b32 m0, s50
	s_nop 0
	global_load_lds_dwordx4 v[220:221], off
	v_lshl_add_u64 v[220:221], v[226:227], 0, s[18:19]
	s_mov_b32 m0, s51
	s_nop 0
	global_load_lds_dwordx4 v[220:221], off
	s_waitcnt vmcnt(8)
	s_waitcnt lgkmcnt(0)
	s_barrier
	s_setprio 1
	s_waitcnt lgkmcnt(0)
	v_mfma_f32_16x16x32_bf16 v[60:63], v[146:149], v[188:191], v[60:63]
	v_mfma_f32_16x16x32_bf16 v[56:59], v[164:167], v[188:191], v[56:59]
	v_mfma_f32_16x16x32_bf16 v[44:47], v[146:149], v[196:199], v[44:47]
	v_mfma_f32_16x16x32_bf16 v[40:43], v[164:167], v[196:199], v[40:43]
	v_mfma_f32_16x16x32_bf16 v[28:31], v[146:149], v[204:207], v[28:31]
	v_mfma_f32_16x16x32_bf16 v[24:27], v[164:167], v[204:207], v[24:27]
	v_mfma_f32_16x16x32_bf16 v[12:15], v[146:149], v[212:215], v[12:15]
	v_mfma_f32_16x16x32_bf16 v[8:11], v[164:167], v[212:215], v[8:11]
	v_mfma_f32_16x16x32_bf16 v[60:63], v[160:163], v[192:195], v[60:63]
	v_mfma_f32_16x16x32_bf16 v[56:59], v[168:171], v[192:195], v[56:59]
	v_mfma_f32_16x16x32_bf16 v[44:47], v[160:163], v[200:203], v[44:47]
	v_mfma_f32_16x16x32_bf16 v[40:43], v[168:171], v[200:203], v[40:43]
	v_mfma_f32_16x16x32_bf16 v[28:31], v[160:163], v[208:211], v[28:31]
	v_mfma_f32_16x16x32_bf16 v[24:27], v[168:171], v[208:211], v[24:27]
	v_mfma_f32_16x16x32_bf16 v[12:15], v[160:163], v[216:219], v[12:15]
	v_mfma_f32_16x16x32_bf16 v[8:11], v[168:171], v[216:219], v[8:11]
	s_setprio 0
	s_setprio 1
	v_mfma_f32_16x16x32_bf16 v[52:55], v[172:175], v[188:191], v[52:55]
	v_mfma_f32_16x16x32_bf16 v[48:51], v[180:183], v[188:191], v[48:51]
	v_mfma_f32_16x16x32_bf16 v[36:39], v[172:175], v[196:199], v[36:39]
	v_mfma_f32_16x16x32_bf16 v[32:35], v[180:183], v[196:199], v[32:35]
	v_mfma_f32_16x16x32_bf16 v[20:23], v[172:175], v[204:207], v[20:23]
	v_mfma_f32_16x16x32_bf16 v[16:19], v[180:183], v[204:207], v[16:19]
	v_mfma_f32_16x16x32_bf16 v[4:7], v[172:175], v[212:215], v[4:7]
	v_mfma_f32_16x16x32_bf16 v[0:3], v[180:183], v[212:215], v[0:3]
	v_mfma_f32_16x16x32_bf16 v[52:55], v[176:179], v[192:195], v[52:55]
	v_mfma_f32_16x16x32_bf16 v[48:51], v[184:187], v[192:195], v[48:51]
	v_mfma_f32_16x16x32_bf16 v[36:39], v[176:179], v[200:203], v[36:39]
	v_mfma_f32_16x16x32_bf16 v[32:35], v[184:187], v[200:203], v[32:35]
	v_mfma_f32_16x16x32_bf16 v[20:23], v[176:179], v[208:211], v[20:23]
	v_mfma_f32_16x16x32_bf16 v[16:19], v[184:187], v[208:211], v[16:19]
	v_mfma_f32_16x16x32_bf16 v[4:7], v[176:179], v[216:219], v[4:7]
	v_mfma_f32_16x16x32_bf16 v[0:3], v[184:187], v[216:219], v[0:3]
	s_setprio 0
	s_barrier
	s_add_i32 s27, s27, 2
	s_add_u32 s0, s0, 0x100
	s_addc_u32 s1, s1, 0
	s_add_u32 s25, s25, 0x100
	s_addc_u32 s26, s26, 0
	s_cmp_gt_u32 s27, 41
	s_cbranch_scc0 .LBB0_1196
	s_and_b64 vcc, exec, s[36:37]
	s_cbranch_vccz .LBB0_1199
	s_barrier
